# hand-written LayerNorm phases with last-level-cache-aware row order (rows the next FFN-out reads first are normalized last); plus v31 changes
# speedup vs baseline: 1.0113x; 1.0007x over previous
.LBB0_359:
	s_or_b64 exec, exec, s[38:39]
	v_readlane_b32 s2, v250, 53
	s_cmp_lg_u32 s2, 3
	s_cselect_b64 s[44:45], -1, 0
	s_cmp_eq_u32 s2, 3
	s_mov_b64 s[38:39], -1
	s_waitcnt lgkmcnt(0)
	s_barrier
	s_cbranch_scc1 .LBB0_383
	v_and_b32_e32 v0, 63, v222
	v_readfirstlane_b32 s46, v222
	v_lshlrev_b32_e32 v1, 5, v0
	v_lshlrev_b32_e32 v2, 4, v0
	s_lshl_b32 s2, s42, 2
	v_readlane_b32 s48, v252, 22
	v_readlane_b32 s49, v252, 23
	v_readlane_b32 s50, v252, 24
	v_readlane_b32 s51, v252, 25
	s_nop 3
	s_lshr_b32 s46, s46, 6
	s_add_u32 s46, s46, s95
	s_add_u32 s48, s48, s2
	s_addc_u32 s49, s49, 0
	s_add_u32 s50, s50, s2
	s_addc_u32 s51, s51, 0
	global_load_dwordx4 v[4:7], v1, s[48:49]
	global_load_dwordx4 v[20:23], v1, s[50:51]
	global_load_dwordx4 v[8:11], v1, s[48:49] offset:16
	global_load_dwordx4 v[24:27], v1, s[50:51] offset:16
	global_load_dwordx4 v[12:15], v1, s[48:49] offset:2048
	global_load_dwordx4 v[28:31], v1, s[50:51] offset:2048
	global_load_dwordx4 v[16:19], v1, s[48:49] offset:2064
	global_load_dwordx4 v[32:35], v1, s[50:51] offset:2064
	s_add_u32 s36, s46, 0x0
	v_lshl_add_u32 v128, s36, 12, v1
	s_add_u32 s37, s46, 0x1000
	v_lshl_add_u32 v129, s37, 12, v1
	s_add_u32 s38, s46, 0x2000
	v_lshl_add_u32 v130, s38, 12, v1
	s_add_u32 s39, s46, 0x3000
	v_lshl_add_u32 v131, s39, 12, v1
	global_load_dwordx4 v[36:39], v128, s[64:65]
	global_load_dwordx4 v[40:43], v128, s[64:65] offset:16
	global_load_dwordx4 v[44:47], v128, s[64:65] offset:2048
	global_load_dwordx4 v[48:51], v128, s[64:65] offset:2064
	global_load_dwordx4 v[52:55], v129, s[64:65]
	global_load_dwordx4 v[56:59], v129, s[64:65] offset:16
	global_load_dwordx4 v[60:63], v129, s[64:65] offset:2048
	global_load_dwordx4 v[64:67], v129, s[64:65] offset:2064
	global_load_dwordx4 v[68:71], v130, s[64:65]
	global_load_dwordx4 v[72:75], v130, s[64:65] offset:16
	global_load_dwordx4 v[76:79], v130, s[64:65] offset:2048
	global_load_dwordx4 v[80:83], v130, s[64:65] offset:2064
	global_load_dwordx4 v[84:87], v131, s[64:65]
	global_load_dwordx4 v[88:91], v131, s[64:65] offset:16
	global_load_dwordx4 v[92:95], v131, s[64:65] offset:2048
	global_load_dwordx4 v[96:99], v131, s[64:65] offset:2064
	s_add_u32 s40, s46, 0x4000
	v_lshl_add_u32 v132, s40, 12, v1
	s_add_u32 s41, s46, 0x5000
	v_lshl_add_u32 v133, s41, 12, v1
	s_add_u32 s42, s46, 0x6000
	v_lshl_add_u32 v134, s42, 12, v1
	s_add_u32 s43, s46, 0x7000
	v_lshl_add_u32 v135, s43, 12, v1
	global_load_dwordx4 v[156:159], v132, s[64:65]
	global_load_dwordx4 v[160:163], v132, s[64:65] offset:16
	global_load_dwordx4 v[164:167], v132, s[64:65] offset:2048
	global_load_dwordx4 v[168:171], v132, s[64:65] offset:2064
	global_load_dwordx4 v[172:175], v133, s[64:65]
	global_load_dwordx4 v[176:179], v133, s[64:65] offset:16
	global_load_dwordx4 v[180:183], v133, s[64:65] offset:2048
	global_load_dwordx4 v[184:187], v133, s[64:65] offset:2064
	global_load_dwordx4 v[188:191], v134, s[64:65]
	global_load_dwordx4 v[192:195], v134, s[64:65] offset:16
	global_load_dwordx4 v[196:199], v134, s[64:65] offset:2048
	global_load_dwordx4 v[200:203], v134, s[64:65] offset:2064
	global_load_dwordx4 v[204:207], v135, s[64:65]
	global_load_dwordx4 v[208:211], v135, s[64:65] offset:16
	global_load_dwordx4 v[212:215], v135, s[64:65] offset:2048
	global_load_dwordx4 v[216:219], v135, s[64:65] offset:2064
	s_waitcnt vmcnt(16)
	v_pk_add_f32 v[108:109], v[36:37], v[38:39]
	v_pk_add_f32 v[110:111], v[40:41], v[42:43]
	v_pk_add_f32 v[112:113], v[44:45], v[46:47]
	v_pk_add_f32 v[114:115], v[48:49], v[50:51]
	v_pk_mul_f32 v[116:117], v[36:37], v[36:37]
	v_pk_fma_f32 v[116:117], v[38:39], v[38:39], v[116:117]
	v_pk_fma_f32 v[116:117], v[40:41], v[40:41], v[116:117]
	v_pk_fma_f32 v[116:117], v[42:43], v[42:43], v[116:117]
	v_pk_fma_f32 v[116:117], v[44:45], v[44:45], v[116:117]
	v_pk_fma_f32 v[116:117], v[46:47], v[46:47], v[116:117]
	v_pk_fma_f32 v[116:117], v[48:49], v[48:49], v[116:117]
	v_pk_fma_f32 v[116:117], v[50:51], v[50:51], v[116:117]
	v_pk_add_f32 v[108:109], v[108:109], v[110:111]
	v_pk_add_f32 v[112:113], v[112:113], v[114:115]
	v_pk_add_f32 v[108:109], v[108:109], v[112:113]
	v_add_f32_e32 v100, v108, v109
	v_add_f32_e32 v101, v116, v117
	v_pk_add_f32 v[108:109], v[52:53], v[54:55]
	v_pk_add_f32 v[110:111], v[56:57], v[58:59]
	v_pk_add_f32 v[112:113], v[60:61], v[62:63]
	v_pk_add_f32 v[114:115], v[64:65], v[66:67]
	v_pk_mul_f32 v[116:117], v[52:53], v[52:53]
	v_pk_fma_f32 v[116:117], v[54:55], v[54:55], v[116:117]
	v_pk_fma_f32 v[116:117], v[56:57], v[56:57], v[116:117]
	v_pk_fma_f32 v[116:117], v[58:59], v[58:59], v[116:117]
	v_pk_fma_f32 v[116:117], v[60:61], v[60:61], v[116:117]
	v_pk_fma_f32 v[116:117], v[62:63], v[62:63], v[116:117]
	v_pk_fma_f32 v[116:117], v[64:65], v[64:65], v[116:117]
	v_pk_fma_f32 v[116:117], v[66:67], v[66:67], v[116:117]
	v_pk_add_f32 v[108:109], v[108:109], v[110:111]
	v_pk_add_f32 v[112:113], v[112:113], v[114:115]
	v_pk_add_f32 v[108:109], v[108:109], v[112:113]
	v_add_f32_e32 v102, v108, v109
	v_add_f32_e32 v103, v116, v117
	v_pk_add_f32 v[108:109], v[68:69], v[70:71]
	v_pk_add_f32 v[110:111], v[72:73], v[74:75]
	v_pk_add_f32 v[112:113], v[76:77], v[78:79]
	v_pk_add_f32 v[114:115], v[80:81], v[82:83]
	v_pk_mul_f32 v[116:117], v[68:69], v[68:69]
	v_pk_fma_f32 v[116:117], v[70:71], v[70:71], v[116:117]
	v_pk_fma_f32 v[116:117], v[72:73], v[72:73], v[116:117]
	v_pk_fma_f32 v[116:117], v[74:75], v[74:75], v[116:117]
	v_pk_fma_f32 v[116:117], v[76:77], v[76:77], v[116:117]
	v_pk_fma_f32 v[116:117], v[78:79], v[78:79], v[116:117]
	v_pk_fma_f32 v[116:117], v[80:81], v[80:81], v[116:117]
	v_pk_fma_f32 v[116:117], v[82:83], v[82:83], v[116:117]
	v_pk_add_f32 v[108:109], v[108:109], v[110:111]
	v_pk_add_f32 v[112:113], v[112:113], v[114:115]
	v_pk_add_f32 v[108:109], v[108:109], v[112:113]
	v_add_f32_e32 v104, v108, v109
	v_add_f32_e32 v105, v116, v117
	v_pk_add_f32 v[108:109], v[84:85], v[86:87]
	v_pk_add_f32 v[110:111], v[88:89], v[90:91]
	v_pk_add_f32 v[112:113], v[92:93], v[94:95]
	v_pk_add_f32 v[114:115], v[96:97], v[98:99]
	v_pk_mul_f32 v[116:117], v[84:85], v[84:85]
	v_pk_fma_f32 v[116:117], v[86:87], v[86:87], v[116:117]
	v_pk_fma_f32 v[116:117], v[88:89], v[88:89], v[116:117]
	v_pk_fma_f32 v[116:117], v[90:91], v[90:91], v[116:117]
	v_pk_fma_f32 v[116:117], v[92:93], v[92:93], v[116:117]
	v_pk_fma_f32 v[116:117], v[94:95], v[94:95], v[116:117]
	v_pk_fma_f32 v[116:117], v[96:97], v[96:97], v[116:117]
	v_pk_fma_f32 v[116:117], v[98:99], v[98:99], v[116:117]
	v_pk_add_f32 v[108:109], v[108:109], v[110:111]
	v_pk_add_f32 v[112:113], v[112:113], v[114:115]
	v_pk_add_f32 v[108:109], v[108:109], v[112:113]
	v_add_f32_e32 v106, v108, v109
	v_add_f32_e32 v107, v116, v117
	v_add_f32_dpp v100, v100, v100 quad_perm:[1,0,3,2] row_mask:0xf bank_mask:0xf
	v_add_f32_dpp v101, v101, v101 quad_perm:[1,0,3,2] row_mask:0xf bank_mask:0xf
	v_add_f32_dpp v102, v102, v102 quad_perm:[1,0,3,2] row_mask:0xf bank_mask:0xf
	v_add_f32_dpp v103, v103, v103 quad_perm:[1,0,3,2] row_mask:0xf bank_mask:0xf
	v_add_f32_dpp v104, v104, v104 quad_perm:[1,0,3,2] row_mask:0xf bank_mask:0xf
	v_add_f32_dpp v105, v105, v105 quad_perm:[1,0,3,2] row_mask:0xf bank_mask:0xf
	v_add_f32_dpp v106, v106, v106 quad_perm:[1,0,3,2] row_mask:0xf bank_mask:0xf
	v_add_f32_dpp v107, v107, v107 quad_perm:[1,0,3,2] row_mask:0xf bank_mask:0xf
	v_add_f32_dpp v100, v100, v100 quad_perm:[2,3,0,1] row_mask:0xf bank_mask:0xf
	v_add_f32_dpp v101, v101, v101 quad_perm:[2,3,0,1] row_mask:0xf bank_mask:0xf
	v_add_f32_dpp v102, v102, v102 quad_perm:[2,3,0,1] row_mask:0xf bank_mask:0xf
	v_add_f32_dpp v103, v103, v103 quad_perm:[2,3,0,1] row_mask:0xf bank_mask:0xf
	v_add_f32_dpp v104, v104, v104 quad_perm:[2,3,0,1] row_mask:0xf bank_mask:0xf
	v_add_f32_dpp v105, v105, v105 quad_perm:[2,3,0,1] row_mask:0xf bank_mask:0xf
	v_add_f32_dpp v106, v106, v106 quad_perm:[2,3,0,1] row_mask:0xf bank_mask:0xf
	v_add_f32_dpp v107, v107, v107 quad_perm:[2,3,0,1] row_mask:0xf bank_mask:0xf
	v_add_f32_dpp v100, v100, v100 row_half_mirror row_mask:0xf bank_mask:0xf
	v_add_f32_dpp v101, v101, v101 row_half_mirror row_mask:0xf bank_mask:0xf
	v_add_f32_dpp v102, v102, v102 row_half_mirror row_mask:0xf bank_mask:0xf
	v_add_f32_dpp v103, v103, v103 row_half_mirror row_mask:0xf bank_mask:0xf
	v_add_f32_dpp v104, v104, v104 row_half_mirror row_mask:0xf bank_mask:0xf
	v_add_f32_dpp v105, v105, v105 row_half_mirror row_mask:0xf bank_mask:0xf
	v_add_f32_dpp v106, v106, v106 row_half_mirror row_mask:0xf bank_mask:0xf
	v_add_f32_dpp v107, v107, v107 row_half_mirror row_mask:0xf bank_mask:0xf
	v_add_f32_dpp v100, v100, v100 row_mirror row_mask:0xf bank_mask:0xf
	v_add_f32_dpp v101, v101, v101 row_mirror row_mask:0xf bank_mask:0xf
	v_add_f32_dpp v102, v102, v102 row_mirror row_mask:0xf bank_mask:0xf
	v_add_f32_dpp v103, v103, v103 row_mirror row_mask:0xf bank_mask:0xf
	v_add_f32_dpp v104, v104, v104 row_mirror row_mask:0xf bank_mask:0xf
	v_add_f32_dpp v105, v105, v105 row_mirror row_mask:0xf bank_mask:0xf
	v_add_f32_dpp v106, v106, v106 row_mirror row_mask:0xf bank_mask:0xf
	v_add_f32_dpp v107, v107, v107 row_mirror row_mask:0xf bank_mask:0xf
	v_mov_b32_e32 v108, v100
	v_mov_b32_e32 v109, v101
	v_mov_b32_e32 v110, v102
	v_mov_b32_e32 v111, v103
	v_mov_b32_e32 v112, v104
	v_mov_b32_e32 v113, v105
	v_mov_b32_e32 v114, v106
	v_mov_b32_e32 v115, v107
	s_nop 1
	v_permlane16_swap_b32_e32 v108, v100
	v_permlane16_swap_b32_e32 v109, v101
	v_permlane16_swap_b32_e32 v110, v102
	v_permlane16_swap_b32_e32 v111, v103
	v_permlane16_swap_b32_e32 v112, v104
	v_permlane16_swap_b32_e32 v113, v105
	v_permlane16_swap_b32_e32 v114, v106
	v_permlane16_swap_b32_e32 v115, v107
	v_add_f32_e32 v100, v100, v108
	v_add_f32_e32 v101, v101, v109
	v_add_f32_e32 v102, v102, v110
	v_add_f32_e32 v103, v103, v111
	v_add_f32_e32 v104, v104, v112
	v_add_f32_e32 v105, v105, v113
	v_add_f32_e32 v106, v106, v114
	v_add_f32_e32 v107, v107, v115
	v_mov_b32_e32 v108, v100
	v_mov_b32_e32 v109, v101
	v_mov_b32_e32 v110, v102
	v_mov_b32_e32 v111, v103
	v_mov_b32_e32 v112, v104
	v_mov_b32_e32 v113, v105
	v_mov_b32_e32 v114, v106
	v_mov_b32_e32 v115, v107
	s_nop 1
	v_permlane32_swap_b32_e32 v108, v100
	v_permlane32_swap_b32_e32 v109, v101
	v_permlane32_swap_b32_e32 v110, v102
	v_permlane32_swap_b32_e32 v111, v103
	v_permlane32_swap_b32_e32 v112, v104
	v_permlane32_swap_b32_e32 v113, v105
	v_permlane32_swap_b32_e32 v114, v106
	v_permlane32_swap_b32_e32 v115, v107
	v_add_f32_e32 v100, v100, v108
	v_add_f32_e32 v101, v101, v109
	v_add_f32_e32 v102, v102, v110
	v_add_f32_e32 v103, v103, v111
	v_add_f32_e32 v104, v104, v112
	v_add_f32_e32 v105, v105, v113
	v_add_f32_e32 v106, v106, v114
	v_add_f32_e32 v107, v107, v115
	v_mul_f32_e32 v230, 0x3a800000, v100
	v_mul_f32_e32 v116, 0x3a800000, v101
	v_fma_f32 v116, -v230, v230, v116
	v_max_f32_e32 v116, 0, v116
	v_add_f32_e32 v116, 0x3727c5ac, v116
	v_mul_f32_e32 v232, 0x3a800000, v102
	v_mul_f32_e32 v118, 0x3a800000, v103
	v_fma_f32 v118, -v232, v232, v118
	v_max_f32_e32 v118, 0, v118
	v_add_f32_e32 v118, 0x3727c5ac, v118
	v_mul_f32_e32 v234, 0x3a800000, v104
	v_mul_f32_e32 v120, 0x3a800000, v105
	v_fma_f32 v120, -v234, v234, v120
	v_max_f32_e32 v120, 0, v120
	v_add_f32_e32 v120, 0x3727c5ac, v120
	v_mul_f32_e32 v236, 0x3a800000, v106
	v_mul_f32_e32 v122, 0x3a800000, v107
	v_fma_f32 v122, -v236, v236, v122
	v_max_f32_e32 v122, 0, v122
	v_add_f32_e32 v122, 0x3727c5ac, v122
	v_rsq_f32_e32 v117, v116
	v_rsq_f32_e32 v119, v118
	v_rsq_f32_e32 v121, v120
	v_rsq_f32_e32 v123, v122
	s_nop 0
	v_mul_f32_e32 v124, v116, v117
	v_mul_f32_e32 v124, v124, v117
	v_fmaak_f32 v124, -0.5, v124, 0x3fc00000
	v_mul_f32_e32 v231, v117, v124
	v_mul_f32_e32 v125, v118, v119
	v_mul_f32_e32 v125, v125, v119
	v_fmaak_f32 v125, -0.5, v125, 0x3fc00000
	v_mul_f32_e32 v233, v119, v125
	v_mul_f32_e32 v126, v120, v121
	v_mul_f32_e32 v126, v126, v121
	v_fmaak_f32 v126, -0.5, v126, 0x3fc00000
	v_mul_f32_e32 v235, v121, v126
	v_mul_f32_e32 v127, v122, v123
	v_mul_f32_e32 v127, v127, v123
	v_fmaak_f32 v127, -0.5, v127, 0x3fc00000
	v_mul_f32_e32 v237, v123, v127
	v_pk_add_f32 v[36:37], v[36:37], v[230:231] op_sel_hi:[1,0] neg_lo:[0,1] neg_hi:[0,1]
	v_pk_add_f32 v[38:39], v[38:39], v[230:231] op_sel_hi:[1,0] neg_lo:[0,1] neg_hi:[0,1]
	v_pk_add_f32 v[40:41], v[40:41], v[230:231] op_sel_hi:[1,0] neg_lo:[0,1] neg_hi:[0,1]
	v_pk_add_f32 v[42:43], v[42:43], v[230:231] op_sel_hi:[1,0] neg_lo:[0,1] neg_hi:[0,1]
	v_pk_add_f32 v[44:45], v[44:45], v[230:231] op_sel_hi:[1,0] neg_lo:[0,1] neg_hi:[0,1]
	v_pk_add_f32 v[46:47], v[46:47], v[230:231] op_sel_hi:[1,0] neg_lo:[0,1] neg_hi:[0,1]
	v_pk_add_f32 v[48:49], v[48:49], v[230:231] op_sel_hi:[1,0] neg_lo:[0,1] neg_hi:[0,1]
	v_pk_add_f32 v[50:51], v[50:51], v[230:231] op_sel_hi:[1,0] neg_lo:[0,1] neg_hi:[0,1]
	v_pk_mul_f32 v[36:37], v[36:37], v[230:231] op_sel:[0,1] op_sel_hi:[1,1]
	v_pk_mul_f32 v[38:39], v[38:39], v[230:231] op_sel:[0,1] op_sel_hi:[1,1]
	v_pk_mul_f32 v[40:41], v[40:41], v[230:231] op_sel:[0,1] op_sel_hi:[1,1]
	v_pk_mul_f32 v[42:43], v[42:43], v[230:231] op_sel:[0,1] op_sel_hi:[1,1]
	v_pk_mul_f32 v[44:45], v[44:45], v[230:231] op_sel:[0,1] op_sel_hi:[1,1]
	v_pk_mul_f32 v[46:47], v[46:47], v[230:231] op_sel:[0,1] op_sel_hi:[1,1]
	v_pk_mul_f32 v[48:49], v[48:49], v[230:231] op_sel:[0,1] op_sel_hi:[1,1]
	v_pk_mul_f32 v[50:51], v[50:51], v[230:231] op_sel:[0,1] op_sel_hi:[1,1]
	v_pk_fma_f32 v[36:37], v[4:5], v[36:37], v[20:21]
	v_pk_fma_f32 v[38:39], v[6:7], v[38:39], v[22:23]
	v_pk_fma_f32 v[40:41], v[8:9], v[40:41], v[24:25]
	v_pk_fma_f32 v[42:43], v[10:11], v[42:43], v[26:27]
	v_pk_fma_f32 v[44:45], v[12:13], v[44:45], v[28:29]
	v_pk_fma_f32 v[46:47], v[14:15], v[46:47], v[30:31]
	v_pk_fma_f32 v[48:49], v[16:17], v[48:49], v[32:33]
	v_pk_fma_f32 v[50:51], v[18:19], v[50:51], v[34:35]
	v_cvt_pk_bf16_f32 v36, v36, v37
	v_cvt_pk_bf16_f32 v37, v38, v39
	v_cvt_pk_bf16_f32 v38, v40, v41
	v_cvt_pk_bf16_f32 v39, v42, v43
	v_cvt_pk_bf16_f32 v44, v44, v45
	v_cvt_pk_bf16_f32 v45, v46, v47
	v_cvt_pk_bf16_f32 v46, v48, v49
	v_cvt_pk_bf16_f32 v47, v50, v51
	v_lshl_add_u32 v3, s36, 11, v2
	global_store_dwordx4 v3, v[36:39], s[96:97] sc1
	global_store_dwordx4 v3, v[44:47], s[96:97] offset:1024 sc1
	v_pk_add_f32 v[52:53], v[52:53], v[232:233] op_sel_hi:[1,0] neg_lo:[0,1] neg_hi:[0,1]
	v_pk_add_f32 v[54:55], v[54:55], v[232:233] op_sel_hi:[1,0] neg_lo:[0,1] neg_hi:[0,1]
	v_pk_add_f32 v[56:57], v[56:57], v[232:233] op_sel_hi:[1,0] neg_lo:[0,1] neg_hi:[0,1]
	v_pk_add_f32 v[58:59], v[58:59], v[232:233] op_sel_hi:[1,0] neg_lo:[0,1] neg_hi:[0,1]
	v_pk_add_f32 v[60:61], v[60:61], v[232:233] op_sel_hi:[1,0] neg_lo:[0,1] neg_hi:[0,1]
	v_pk_add_f32 v[62:63], v[62:63], v[232:233] op_sel_hi:[1,0] neg_lo:[0,1] neg_hi:[0,1]
	v_pk_add_f32 v[64:65], v[64:65], v[232:233] op_sel_hi:[1,0] neg_lo:[0,1] neg_hi:[0,1]
	v_pk_add_f32 v[66:67], v[66:67], v[232:233] op_sel_hi:[1,0] neg_lo:[0,1] neg_hi:[0,1]
	v_pk_mul_f32 v[52:53], v[52:53], v[232:233] op_sel:[0,1] op_sel_hi:[1,1]
	v_pk_mul_f32 v[54:55], v[54:55], v[232:233] op_sel:[0,1] op_sel_hi:[1,1]
	v_pk_mul_f32 v[56:57], v[56:57], v[232:233] op_sel:[0,1] op_sel_hi:[1,1]
	v_pk_mul_f32 v[58:59], v[58:59], v[232:233] op_sel:[0,1] op_sel_hi:[1,1]
	v_pk_mul_f32 v[60:61], v[60:61], v[232:233] op_sel:[0,1] op_sel_hi:[1,1]
	v_pk_mul_f32 v[62:63], v[62:63], v[232:233] op_sel:[0,1] op_sel_hi:[1,1]
	v_pk_mul_f32 v[64:65], v[64:65], v[232:233] op_sel:[0,1] op_sel_hi:[1,1]
	v_pk_mul_f32 v[66:67], v[66:67], v[232:233] op_sel:[0,1] op_sel_hi:[1,1]
	v_pk_fma_f32 v[52:53], v[4:5], v[52:53], v[20:21]
	v_pk_fma_f32 v[54:55], v[6:7], v[54:55], v[22:23]
	v_pk_fma_f32 v[56:57], v[8:9], v[56:57], v[24:25]
	v_pk_fma_f32 v[58:59], v[10:11], v[58:59], v[26:27]
	v_pk_fma_f32 v[60:61], v[12:13], v[60:61], v[28:29]
	v_pk_fma_f32 v[62:63], v[14:15], v[62:63], v[30:31]
	v_pk_fma_f32 v[64:65], v[16:17], v[64:65], v[32:33]
	v_pk_fma_f32 v[66:67], v[18:19], v[66:67], v[34:35]
	v_cvt_pk_bf16_f32 v52, v52, v53
	v_cvt_pk_bf16_f32 v53, v54, v55
	v_cvt_pk_bf16_f32 v54, v56, v57
	v_cvt_pk_bf16_f32 v55, v58, v59
	v_cvt_pk_bf16_f32 v60, v60, v61
	v_cvt_pk_bf16_f32 v61, v62, v63
	v_cvt_pk_bf16_f32 v62, v64, v65
	v_cvt_pk_bf16_f32 v63, v66, v67
	v_lshl_add_u32 v3, s37, 11, v2
	global_store_dwordx4 v3, v[52:55], s[96:97] sc1
	global_store_dwordx4 v3, v[60:63], s[96:97] offset:1024 sc1
	v_pk_add_f32 v[68:69], v[68:69], v[234:235] op_sel_hi:[1,0] neg_lo:[0,1] neg_hi:[0,1]
	v_pk_add_f32 v[70:71], v[70:71], v[234:235] op_sel_hi:[1,0] neg_lo:[0,1] neg_hi:[0,1]
	v_pk_add_f32 v[72:73], v[72:73], v[234:235] op_sel_hi:[1,0] neg_lo:[0,1] neg_hi:[0,1]
	v_pk_add_f32 v[74:75], v[74:75], v[234:235] op_sel_hi:[1,0] neg_lo:[0,1] neg_hi:[0,1]
	v_pk_add_f32 v[76:77], v[76:77], v[234:235] op_sel_hi:[1,0] neg_lo:[0,1] neg_hi:[0,1]
	v_pk_add_f32 v[78:79], v[78:79], v[234:235] op_sel_hi:[1,0] neg_lo:[0,1] neg_hi:[0,1]
	v_pk_add_f32 v[80:81], v[80:81], v[234:235] op_sel_hi:[1,0] neg_lo:[0,1] neg_hi:[0,1]
	v_pk_add_f32 v[82:83], v[82:83], v[234:235] op_sel_hi:[1,0] neg_lo:[0,1] neg_hi:[0,1]
	v_pk_mul_f32 v[68:69], v[68:69], v[234:235] op_sel:[0,1] op_sel_hi:[1,1]
	v_pk_mul_f32 v[70:71], v[70:71], v[234:235] op_sel:[0,1] op_sel_hi:[1,1]
	v_pk_mul_f32 v[72:73], v[72:73], v[234:235] op_sel:[0,1] op_sel_hi:[1,1]
	v_pk_mul_f32 v[74:75], v[74:75], v[234:235] op_sel:[0,1] op_sel_hi:[1,1]
	v_pk_mul_f32 v[76:77], v[76:77], v[234:235] op_sel:[0,1] op_sel_hi:[1,1]
	v_pk_mul_f32 v[78:79], v[78:79], v[234:235] op_sel:[0,1] op_sel_hi:[1,1]
	v_pk_mul_f32 v[80:81], v[80:81], v[234:235] op_sel:[0,1] op_sel_hi:[1,1]
	v_pk_mul_f32 v[82:83], v[82:83], v[234:235] op_sel:[0,1] op_sel_hi:[1,1]
	v_pk_fma_f32 v[68:69], v[4:5], v[68:69], v[20:21]
	v_pk_fma_f32 v[70:71], v[6:7], v[70:71], v[22:23]
	v_pk_fma_f32 v[72:73], v[8:9], v[72:73], v[24:25]
	v_pk_fma_f32 v[74:75], v[10:11], v[74:75], v[26:27]
	v_pk_fma_f32 v[76:77], v[12:13], v[76:77], v[28:29]
	v_pk_fma_f32 v[78:79], v[14:15], v[78:79], v[30:31]
	v_pk_fma_f32 v[80:81], v[16:17], v[80:81], v[32:33]
	v_pk_fma_f32 v[82:83], v[18:19], v[82:83], v[34:35]
	v_cvt_pk_bf16_f32 v68, v68, v69
	v_cvt_pk_bf16_f32 v69, v70, v71
	v_cvt_pk_bf16_f32 v70, v72, v73
	v_cvt_pk_bf16_f32 v71, v74, v75
	v_cvt_pk_bf16_f32 v76, v76, v77
	v_cvt_pk_bf16_f32 v77, v78, v79
	v_cvt_pk_bf16_f32 v78, v80, v81
	v_cvt_pk_bf16_f32 v79, v82, v83
	v_lshl_add_u32 v3, s38, 11, v2
	global_store_dwordx4 v3, v[68:71], s[96:97] sc1
	global_store_dwordx4 v3, v[76:79], s[96:97] offset:1024 sc1
	v_pk_add_f32 v[84:85], v[84:85], v[236:237] op_sel_hi:[1,0] neg_lo:[0,1] neg_hi:[0,1]
	v_pk_add_f32 v[86:87], v[86:87], v[236:237] op_sel_hi:[1,0] neg_lo:[0,1] neg_hi:[0,1]
	v_pk_add_f32 v[88:89], v[88:89], v[236:237] op_sel_hi:[1,0] neg_lo:[0,1] neg_hi:[0,1]
	v_pk_add_f32 v[90:91], v[90:91], v[236:237] op_sel_hi:[1,0] neg_lo:[0,1] neg_hi:[0,1]
	v_pk_add_f32 v[92:93], v[92:93], v[236:237] op_sel_hi:[1,0] neg_lo:[0,1] neg_hi:[0,1]
	v_pk_add_f32 v[94:95], v[94:95], v[236:237] op_sel_hi:[1,0] neg_lo:[0,1] neg_hi:[0,1]
	v_pk_add_f32 v[96:97], v[96:97], v[236:237] op_sel_hi:[1,0] neg_lo:[0,1] neg_hi:[0,1]
	v_pk_add_f32 v[98:99], v[98:99], v[236:237] op_sel_hi:[1,0] neg_lo:[0,1] neg_hi:[0,1]
	v_pk_mul_f32 v[84:85], v[84:85], v[236:237] op_sel:[0,1] op_sel_hi:[1,1]
	v_pk_mul_f32 v[86:87], v[86:87], v[236:237] op_sel:[0,1] op_sel_hi:[1,1]
	v_pk_mul_f32 v[88:89], v[88:89], v[236:237] op_sel:[0,1] op_sel_hi:[1,1]
	v_pk_mul_f32 v[90:91], v[90:91], v[236:237] op_sel:[0,1] op_sel_hi:[1,1]
	v_pk_mul_f32 v[92:93], v[92:93], v[236:237] op_sel:[0,1] op_sel_hi:[1,1]
	v_pk_mul_f32 v[94:95], v[94:95], v[236:237] op_sel:[0,1] op_sel_hi:[1,1]
	v_pk_mul_f32 v[96:97], v[96:97], v[236:237] op_sel:[0,1] op_sel_hi:[1,1]
	v_pk_mul_f32 v[98:99], v[98:99], v[236:237] op_sel:[0,1] op_sel_hi:[1,1]
	v_pk_fma_f32 v[84:85], v[4:5], v[84:85], v[20:21]
	v_pk_fma_f32 v[86:87], v[6:7], v[86:87], v[22:23]
	v_pk_fma_f32 v[88:89], v[8:9], v[88:89], v[24:25]
	v_pk_fma_f32 v[90:91], v[10:11], v[90:91], v[26:27]
	v_pk_fma_f32 v[92:93], v[12:13], v[92:93], v[28:29]
	v_pk_fma_f32 v[94:95], v[14:15], v[94:95], v[30:31]
	v_pk_fma_f32 v[96:97], v[16:17], v[96:97], v[32:33]
	v_pk_fma_f32 v[98:99], v[18:19], v[98:99], v[34:35]
	v_cvt_pk_bf16_f32 v84, v84, v85
	v_cvt_pk_bf16_f32 v85, v86, v87
	v_cvt_pk_bf16_f32 v86, v88, v89
	v_cvt_pk_bf16_f32 v87, v90, v91
	v_cvt_pk_bf16_f32 v92, v92, v93
	v_cvt_pk_bf16_f32 v93, v94, v95
	v_cvt_pk_bf16_f32 v94, v96, v97
	v_cvt_pk_bf16_f32 v95, v98, v99
	v_lshl_add_u32 v3, s39, 11, v2
	global_store_dwordx4 v3, v[84:87], s[96:97] sc1
	global_store_dwordx4 v3, v[92:95], s[96:97] offset:1024 sc1
	s_mov_b64 s[52:53], exec
	s_mov_b64 exec, 1
	v_mov_b32_e32 v3, s36
	v_lshlrev_b32_e32 v3, 3, v3
	global_store_dwordx2 v3, v[230:231], s[92:93] sc1
	v_mov_b32_e32 v3, s37
	v_lshlrev_b32_e32 v3, 3, v3
	global_store_dwordx2 v3, v[232:233], s[92:93] sc1
	v_mov_b32_e32 v3, s38
	v_lshlrev_b32_e32 v3, 3, v3
	global_store_dwordx2 v3, v[234:235], s[92:93] sc1
	v_mov_b32_e32 v3, s39
	v_lshlrev_b32_e32 v3, 3, v3
	global_store_dwordx2 v3, v[236:237], s[92:93] sc1
	s_mov_b64 exec, s[52:53]
	s_add_u32 s36, s46, 0x800
	v_lshl_add_u32 v128, s36, 12, v1
	s_add_u32 s37, s46, 0x1800
	v_lshl_add_u32 v129, s37, 12, v1
	s_add_u32 s38, s46, 0x2800
	v_lshl_add_u32 v130, s38, 12, v1
	s_add_u32 s39, s46, 0x3800
	v_lshl_add_u32 v131, s39, 12, v1
	global_load_dwordx4 v[36:39], v128, s[64:65]
	global_load_dwordx4 v[40:43], v128, s[64:65] offset:16
	global_load_dwordx4 v[44:47], v128, s[64:65] offset:2048
	global_load_dwordx4 v[48:51], v128, s[64:65] offset:2064
	global_load_dwordx4 v[52:55], v129, s[64:65]
	global_load_dwordx4 v[56:59], v129, s[64:65] offset:16
	global_load_dwordx4 v[60:63], v129, s[64:65] offset:2048
	global_load_dwordx4 v[64:67], v129, s[64:65] offset:2064
	global_load_dwordx4 v[68:71], v130, s[64:65]
	global_load_dwordx4 v[72:75], v130, s[64:65] offset:16
	global_load_dwordx4 v[76:79], v130, s[64:65] offset:2048
	global_load_dwordx4 v[80:83], v130, s[64:65] offset:2064
	global_load_dwordx4 v[84:87], v131, s[64:65]
	global_load_dwordx4 v[88:91], v131, s[64:65] offset:16
	global_load_dwordx4 v[92:95], v131, s[64:65] offset:2048
	global_load_dwordx4 v[96:99], v131, s[64:65] offset:2064
	s_waitcnt vmcnt(28)
	v_pk_add_f32 v[108:109], v[156:157], v[158:159]
	v_pk_add_f32 v[110:111], v[160:161], v[162:163]
	v_pk_add_f32 v[112:113], v[164:165], v[166:167]
	v_pk_add_f32 v[114:115], v[168:169], v[170:171]
	v_pk_mul_f32 v[116:117], v[156:157], v[156:157]
	v_pk_fma_f32 v[116:117], v[158:159], v[158:159], v[116:117]
	v_pk_fma_f32 v[116:117], v[160:161], v[160:161], v[116:117]
	v_pk_fma_f32 v[116:117], v[162:163], v[162:163], v[116:117]
	v_pk_fma_f32 v[116:117], v[164:165], v[164:165], v[116:117]
	v_pk_fma_f32 v[116:117], v[166:167], v[166:167], v[116:117]
	v_pk_fma_f32 v[116:117], v[168:169], v[168:169], v[116:117]
	v_pk_fma_f32 v[116:117], v[170:171], v[170:171], v[116:117]
	v_pk_add_f32 v[108:109], v[108:109], v[110:111]
	v_pk_add_f32 v[112:113], v[112:113], v[114:115]
	v_pk_add_f32 v[108:109], v[108:109], v[112:113]
	v_add_f32_e32 v100, v108, v109
	v_add_f32_e32 v101, v116, v117
	v_pk_add_f32 v[108:109], v[172:173], v[174:175]
	v_pk_add_f32 v[110:111], v[176:177], v[178:179]
	v_pk_add_f32 v[112:113], v[180:181], v[182:183]
	v_pk_add_f32 v[114:115], v[184:185], v[186:187]
	v_pk_mul_f32 v[116:117], v[172:173], v[172:173]
	v_pk_fma_f32 v[116:117], v[174:175], v[174:175], v[116:117]
	v_pk_fma_f32 v[116:117], v[176:177], v[176:177], v[116:117]
	v_pk_fma_f32 v[116:117], v[178:179], v[178:179], v[116:117]
	v_pk_fma_f32 v[116:117], v[180:181], v[180:181], v[116:117]
	v_pk_fma_f32 v[116:117], v[182:183], v[182:183], v[116:117]
	v_pk_fma_f32 v[116:117], v[184:185], v[184:185], v[116:117]
	v_pk_fma_f32 v[116:117], v[186:187], v[186:187], v[116:117]
	v_pk_add_f32 v[108:109], v[108:109], v[110:111]
	v_pk_add_f32 v[112:113], v[112:113], v[114:115]
	v_pk_add_f32 v[108:109], v[108:109], v[112:113]
	v_add_f32_e32 v102, v108, v109
	v_add_f32_e32 v103, v116, v117
	v_pk_add_f32 v[108:109], v[188:189], v[190:191]
	v_pk_add_f32 v[110:111], v[192:193], v[194:195]
	v_pk_add_f32 v[112:113], v[196:197], v[198:199]
	v_pk_add_f32 v[114:115], v[200:201], v[202:203]
	v_pk_mul_f32 v[116:117], v[188:189], v[188:189]
	v_pk_fma_f32 v[116:117], v[190:191], v[190:191], v[116:117]
	v_pk_fma_f32 v[116:117], v[192:193], v[192:193], v[116:117]
	v_pk_fma_f32 v[116:117], v[194:195], v[194:195], v[116:117]
	v_pk_fma_f32 v[116:117], v[196:197], v[196:197], v[116:117]
	v_pk_fma_f32 v[116:117], v[198:199], v[198:199], v[116:117]
	v_pk_fma_f32 v[116:117], v[200:201], v[200:201], v[116:117]
	v_pk_fma_f32 v[116:117], v[202:203], v[202:203], v[116:117]
	v_pk_add_f32 v[108:109], v[108:109], v[110:111]
	v_pk_add_f32 v[112:113], v[112:113], v[114:115]
	v_pk_add_f32 v[108:109], v[108:109], v[112:113]
	v_add_f32_e32 v104, v108, v109
	v_add_f32_e32 v105, v116, v117
	v_pk_add_f32 v[108:109], v[204:205], v[206:207]
	v_pk_add_f32 v[110:111], v[208:209], v[210:211]
	v_pk_add_f32 v[112:113], v[212:213], v[214:215]
	v_pk_add_f32 v[114:115], v[216:217], v[218:219]
	v_pk_mul_f32 v[116:117], v[204:205], v[204:205]
	v_pk_fma_f32 v[116:117], v[206:207], v[206:207], v[116:117]
	v_pk_fma_f32 v[116:117], v[208:209], v[208:209], v[116:117]
	v_pk_fma_f32 v[116:117], v[210:211], v[210:211], v[116:117]
	v_pk_fma_f32 v[116:117], v[212:213], v[212:213], v[116:117]
	v_pk_fma_f32 v[116:117], v[214:215], v[214:215], v[116:117]
	v_pk_fma_f32 v[116:117], v[216:217], v[216:217], v[116:117]
	v_pk_fma_f32 v[116:117], v[218:219], v[218:219], v[116:117]
	v_pk_add_f32 v[108:109], v[108:109], v[110:111]
	v_pk_add_f32 v[112:113], v[112:113], v[114:115]
	v_pk_add_f32 v[108:109], v[108:109], v[112:113]
	v_add_f32_e32 v106, v108, v109
	v_add_f32_e32 v107, v116, v117
	v_add_f32_dpp v100, v100, v100 quad_perm:[1,0,3,2] row_mask:0xf bank_mask:0xf
	v_add_f32_dpp v101, v101, v101 quad_perm:[1,0,3,2] row_mask:0xf bank_mask:0xf
	v_add_f32_dpp v102, v102, v102 quad_perm:[1,0,3,2] row_mask:0xf bank_mask:0xf
	v_add_f32_dpp v103, v103, v103 quad_perm:[1,0,3,2] row_mask:0xf bank_mask:0xf
	v_add_f32_dpp v104, v104, v104 quad_perm:[1,0,3,2] row_mask:0xf bank_mask:0xf
	v_add_f32_dpp v105, v105, v105 quad_perm:[1,0,3,2] row_mask:0xf bank_mask:0xf
	v_add_f32_dpp v106, v106, v106 quad_perm:[1,0,3,2] row_mask:0xf bank_mask:0xf
	v_add_f32_dpp v107, v107, v107 quad_perm:[1,0,3,2] row_mask:0xf bank_mask:0xf
	v_add_f32_dpp v100, v100, v100 quad_perm:[2,3,0,1] row_mask:0xf bank_mask:0xf
	v_add_f32_dpp v101, v101, v101 quad_perm:[2,3,0,1] row_mask:0xf bank_mask:0xf
	v_add_f32_dpp v102, v102, v102 quad_perm:[2,3,0,1] row_mask:0xf bank_mask:0xf
	v_add_f32_dpp v103, v103, v103 quad_perm:[2,3,0,1] row_mask:0xf bank_mask:0xf
	v_add_f32_dpp v104, v104, v104 quad_perm:[2,3,0,1] row_mask:0xf bank_mask:0xf
	v_add_f32_dpp v105, v105, v105 quad_perm:[2,3,0,1] row_mask:0xf bank_mask:0xf
	v_add_f32_dpp v106, v106, v106 quad_perm:[2,3,0,1] row_mask:0xf bank_mask:0xf
	v_add_f32_dpp v107, v107, v107 quad_perm:[2,3,0,1] row_mask:0xf bank_mask:0xf
	v_add_f32_dpp v100, v100, v100 row_half_mirror row_mask:0xf bank_mask:0xf
	v_add_f32_dpp v101, v101, v101 row_half_mirror row_mask:0xf bank_mask:0xf
	v_add_f32_dpp v102, v102, v102 row_half_mirror row_mask:0xf bank_mask:0xf
	v_add_f32_dpp v103, v103, v103 row_half_mirror row_mask:0xf bank_mask:0xf
	v_add_f32_dpp v104, v104, v104 row_half_mirror row_mask:0xf bank_mask:0xf
	v_add_f32_dpp v105, v105, v105 row_half_mirror row_mask:0xf bank_mask:0xf
	v_add_f32_dpp v106, v106, v106 row_half_mirror row_mask:0xf bank_mask:0xf
	v_add_f32_dpp v107, v107, v107 row_half_mirror row_mask:0xf bank_mask:0xf
	v_add_f32_dpp v100, v100, v100 row_mirror row_mask:0xf bank_mask:0xf
	v_add_f32_dpp v101, v101, v101 row_mirror row_mask:0xf bank_mask:0xf
	v_add_f32_dpp v102, v102, v102 row_mirror row_mask:0xf bank_mask:0xf
	v_add_f32_dpp v103, v103, v103 row_mirror row_mask:0xf bank_mask:0xf
	v_add_f32_dpp v104, v104, v104 row_mirror row_mask:0xf bank_mask:0xf
	v_add_f32_dpp v105, v105, v105 row_mirror row_mask:0xf bank_mask:0xf
	v_add_f32_dpp v106, v106, v106 row_mirror row_mask:0xf bank_mask:0xf
	v_add_f32_dpp v107, v107, v107 row_mirror row_mask:0xf bank_mask:0xf
	v_mov_b32_e32 v108, v100
	v_mov_b32_e32 v109, v101
	v_mov_b32_e32 v110, v102
	v_mov_b32_e32 v111, v103
	v_mov_b32_e32 v112, v104
	v_mov_b32_e32 v113, v105
	v_mov_b32_e32 v114, v106
	v_mov_b32_e32 v115, v107
	s_nop 1
	v_permlane16_swap_b32_e32 v108, v100
	v_permlane16_swap_b32_e32 v109, v101
	v_permlane16_swap_b32_e32 v110, v102
	v_permlane16_swap_b32_e32 v111, v103
	v_permlane16_swap_b32_e32 v112, v104
	v_permlane16_swap_b32_e32 v113, v105
	v_permlane16_swap_b32_e32 v114, v106
	v_permlane16_swap_b32_e32 v115, v107
	v_add_f32_e32 v100, v100, v108
	v_add_f32_e32 v101, v101, v109
	v_add_f32_e32 v102, v102, v110
	v_add_f32_e32 v103, v103, v111
	v_add_f32_e32 v104, v104, v112
	v_add_f32_e32 v105, v105, v113
	v_add_f32_e32 v106, v106, v114
	v_add_f32_e32 v107, v107, v115
	v_mov_b32_e32 v108, v100
	v_mov_b32_e32 v109, v101
	v_mov_b32_e32 v110, v102
	v_mov_b32_e32 v111, v103
	v_mov_b32_e32 v112, v104
	v_mov_b32_e32 v113, v105
	v_mov_b32_e32 v114, v106
	v_mov_b32_e32 v115, v107
	s_nop 1
	v_permlane32_swap_b32_e32 v108, v100
	v_permlane32_swap_b32_e32 v109, v101
	v_permlane32_swap_b32_e32 v110, v102
	v_permlane32_swap_b32_e32 v111, v103
	v_permlane32_swap_b32_e32 v112, v104
	v_permlane32_swap_b32_e32 v113, v105
	v_permlane32_swap_b32_e32 v114, v106
	v_permlane32_swap_b32_e32 v115, v107
	v_add_f32_e32 v100, v100, v108
	v_add_f32_e32 v101, v101, v109
	v_add_f32_e32 v102, v102, v110
	v_add_f32_e32 v103, v103, v111
	v_add_f32_e32 v104, v104, v112
	v_add_f32_e32 v105, v105, v113
	v_add_f32_e32 v106, v106, v114
	v_add_f32_e32 v107, v107, v115
	v_mul_f32_e32 v238, 0x3a800000, v100
	v_mul_f32_e32 v116, 0x3a800000, v101
	v_fma_f32 v116, -v238, v238, v116
	v_max_f32_e32 v116, 0, v116
	v_add_f32_e32 v116, 0x3727c5ac, v116
	v_mul_f32_e32 v240, 0x3a800000, v102
	v_mul_f32_e32 v118, 0x3a800000, v103
	v_fma_f32 v118, -v240, v240, v118
	v_max_f32_e32 v118, 0, v118
	v_add_f32_e32 v118, 0x3727c5ac, v118
	v_mul_f32_e32 v242, 0x3a800000, v104
	v_mul_f32_e32 v120, 0x3a800000, v105
	v_fma_f32 v120, -v242, v242, v120
	v_max_f32_e32 v120, 0, v120
	v_add_f32_e32 v120, 0x3727c5ac, v120
	v_mul_f32_e32 v244, 0x3a800000, v106
	v_mul_f32_e32 v122, 0x3a800000, v107
	v_fma_f32 v122, -v244, v244, v122
	v_max_f32_e32 v122, 0, v122
	v_add_f32_e32 v122, 0x3727c5ac, v122
	v_rsq_f32_e32 v117, v116
	v_rsq_f32_e32 v119, v118
	v_rsq_f32_e32 v121, v120
	v_rsq_f32_e32 v123, v122
	s_nop 0
	v_mul_f32_e32 v124, v116, v117
	v_mul_f32_e32 v124, v124, v117
	v_fmaak_f32 v124, -0.5, v124, 0x3fc00000
	v_mul_f32_e32 v239, v117, v124
	v_mul_f32_e32 v125, v118, v119
	v_mul_f32_e32 v125, v125, v119
	v_fmaak_f32 v125, -0.5, v125, 0x3fc00000
	v_mul_f32_e32 v241, v119, v125
	v_mul_f32_e32 v126, v120, v121
	v_mul_f32_e32 v126, v126, v121
	v_fmaak_f32 v126, -0.5, v126, 0x3fc00000
	v_mul_f32_e32 v243, v121, v126
	v_mul_f32_e32 v127, v122, v123
	v_mul_f32_e32 v127, v127, v123
	v_fmaak_f32 v127, -0.5, v127, 0x3fc00000
	v_mul_f32_e32 v245, v123, v127
	v_pk_add_f32 v[156:157], v[156:157], v[238:239] op_sel_hi:[1,0] neg_lo:[0,1] neg_hi:[0,1]
	v_pk_add_f32 v[158:159], v[158:159], v[238:239] op_sel_hi:[1,0] neg_lo:[0,1] neg_hi:[0,1]
	v_pk_add_f32 v[160:161], v[160:161], v[238:239] op_sel_hi:[1,0] neg_lo:[0,1] neg_hi:[0,1]
	v_pk_add_f32 v[162:163], v[162:163], v[238:239] op_sel_hi:[1,0] neg_lo:[0,1] neg_hi:[0,1]
	v_pk_add_f32 v[164:165], v[164:165], v[238:239] op_sel_hi:[1,0] neg_lo:[0,1] neg_hi:[0,1]
	v_pk_add_f32 v[166:167], v[166:167], v[238:239] op_sel_hi:[1,0] neg_lo:[0,1] neg_hi:[0,1]
	v_pk_add_f32 v[168:169], v[168:169], v[238:239] op_sel_hi:[1,0] neg_lo:[0,1] neg_hi:[0,1]
	v_pk_add_f32 v[170:171], v[170:171], v[238:239] op_sel_hi:[1,0] neg_lo:[0,1] neg_hi:[0,1]
	v_pk_mul_f32 v[156:157], v[156:157], v[238:239] op_sel:[0,1] op_sel_hi:[1,1]
	v_pk_mul_f32 v[158:159], v[158:159], v[238:239] op_sel:[0,1] op_sel_hi:[1,1]
	v_pk_mul_f32 v[160:161], v[160:161], v[238:239] op_sel:[0,1] op_sel_hi:[1,1]
	v_pk_mul_f32 v[162:163], v[162:163], v[238:239] op_sel:[0,1] op_sel_hi:[1,1]
	v_pk_mul_f32 v[164:165], v[164:165], v[238:239] op_sel:[0,1] op_sel_hi:[1,1]
	v_pk_mul_f32 v[166:167], v[166:167], v[238:239] op_sel:[0,1] op_sel_hi:[1,1]
	v_pk_mul_f32 v[168:169], v[168:169], v[238:239] op_sel:[0,1] op_sel_hi:[1,1]
	v_pk_mul_f32 v[170:171], v[170:171], v[238:239] op_sel:[0,1] op_sel_hi:[1,1]
	v_pk_fma_f32 v[156:157], v[4:5], v[156:157], v[20:21]
	v_pk_fma_f32 v[158:159], v[6:7], v[158:159], v[22:23]
	v_pk_fma_f32 v[160:161], v[8:9], v[160:161], v[24:25]
	v_pk_fma_f32 v[162:163], v[10:11], v[162:163], v[26:27]
	v_pk_fma_f32 v[164:165], v[12:13], v[164:165], v[28:29]
	v_pk_fma_f32 v[166:167], v[14:15], v[166:167], v[30:31]
	v_pk_fma_f32 v[168:169], v[16:17], v[168:169], v[32:33]
	v_pk_fma_f32 v[170:171], v[18:19], v[170:171], v[34:35]
	v_cvt_pk_bf16_f32 v156, v156, v157
	v_cvt_pk_bf16_f32 v157, v158, v159
	v_cvt_pk_bf16_f32 v158, v160, v161
	v_cvt_pk_bf16_f32 v159, v162, v163
	v_cvt_pk_bf16_f32 v164, v164, v165
	v_cvt_pk_bf16_f32 v165, v166, v167
	v_cvt_pk_bf16_f32 v166, v168, v169
	v_cvt_pk_bf16_f32 v167, v170, v171
	v_lshl_add_u32 v3, s40, 11, v2
	global_store_dwordx4 v3, v[156:159], s[96:97] sc1
	global_store_dwordx4 v3, v[164:167], s[96:97] offset:1024 sc1
	v_pk_add_f32 v[172:173], v[172:173], v[240:241] op_sel_hi:[1,0] neg_lo:[0,1] neg_hi:[0,1]
	v_pk_add_f32 v[174:175], v[174:175], v[240:241] op_sel_hi:[1,0] neg_lo:[0,1] neg_hi:[0,1]
	v_pk_add_f32 v[176:177], v[176:177], v[240:241] op_sel_hi:[1,0] neg_lo:[0,1] neg_hi:[0,1]
	v_pk_add_f32 v[178:179], v[178:179], v[240:241] op_sel_hi:[1,0] neg_lo:[0,1] neg_hi:[0,1]
	v_pk_add_f32 v[180:181], v[180:181], v[240:241] op_sel_hi:[1,0] neg_lo:[0,1] neg_hi:[0,1]
	v_pk_add_f32 v[182:183], v[182:183], v[240:241] op_sel_hi:[1,0] neg_lo:[0,1] neg_hi:[0,1]
	v_pk_add_f32 v[184:185], v[184:185], v[240:241] op_sel_hi:[1,0] neg_lo:[0,1] neg_hi:[0,1]
	v_pk_add_f32 v[186:187], v[186:187], v[240:241] op_sel_hi:[1,0] neg_lo:[0,1] neg_hi:[0,1]
	v_pk_mul_f32 v[172:173], v[172:173], v[240:241] op_sel:[0,1] op_sel_hi:[1,1]
	v_pk_mul_f32 v[174:175], v[174:175], v[240:241] op_sel:[0,1] op_sel_hi:[1,1]
	v_pk_mul_f32 v[176:177], v[176:177], v[240:241] op_sel:[0,1] op_sel_hi:[1,1]
	v_pk_mul_f32 v[178:179], v[178:179], v[240:241] op_sel:[0,1] op_sel_hi:[1,1]
	v_pk_mul_f32 v[180:181], v[180:181], v[240:241] op_sel:[0,1] op_sel_hi:[1,1]
	v_pk_mul_f32 v[182:183], v[182:183], v[240:241] op_sel:[0,1] op_sel_hi:[1,1]
	v_pk_mul_f32 v[184:185], v[184:185], v[240:241] op_sel:[0,1] op_sel_hi:[1,1]
	v_pk_mul_f32 v[186:187], v[186:187], v[240:241] op_sel:[0,1] op_sel_hi:[1,1]
	v_pk_fma_f32 v[172:173], v[4:5], v[172:173], v[20:21]
	v_pk_fma_f32 v[174:175], v[6:7], v[174:175], v[22:23]
	v_pk_fma_f32 v[176:177], v[8:9], v[176:177], v[24:25]
	v_pk_fma_f32 v[178:179], v[10:11], v[178:179], v[26:27]
	v_pk_fma_f32 v[180:181], v[12:13], v[180:181], v[28:29]
	v_pk_fma_f32 v[182:183], v[14:15], v[182:183], v[30:31]
	v_pk_fma_f32 v[184:185], v[16:17], v[184:185], v[32:33]
	v_pk_fma_f32 v[186:187], v[18:19], v[186:187], v[34:35]
	v_cvt_pk_bf16_f32 v172, v172, v173
	v_cvt_pk_bf16_f32 v173, v174, v175
	v_cvt_pk_bf16_f32 v174, v176, v177
	v_cvt_pk_bf16_f32 v175, v178, v179
	v_cvt_pk_bf16_f32 v180, v180, v181
	v_cvt_pk_bf16_f32 v181, v182, v183
	v_cvt_pk_bf16_f32 v182, v184, v185
	v_cvt_pk_bf16_f32 v183, v186, v187
	v_lshl_add_u32 v3, s41, 11, v2
	global_store_dwordx4 v3, v[172:175], s[96:97] sc1
	global_store_dwordx4 v3, v[180:183], s[96:97] offset:1024 sc1
	v_pk_add_f32 v[188:189], v[188:189], v[242:243] op_sel_hi:[1,0] neg_lo:[0,1] neg_hi:[0,1]
	v_pk_add_f32 v[190:191], v[190:191], v[242:243] op_sel_hi:[1,0] neg_lo:[0,1] neg_hi:[0,1]
	v_pk_add_f32 v[192:193], v[192:193], v[242:243] op_sel_hi:[1,0] neg_lo:[0,1] neg_hi:[0,1]
	v_pk_add_f32 v[194:195], v[194:195], v[242:243] op_sel_hi:[1,0] neg_lo:[0,1] neg_hi:[0,1]
	v_pk_add_f32 v[196:197], v[196:197], v[242:243] op_sel_hi:[1,0] neg_lo:[0,1] neg_hi:[0,1]
	v_pk_add_f32 v[198:199], v[198:199], v[242:243] op_sel_hi:[1,0] neg_lo:[0,1] neg_hi:[0,1]
	v_pk_add_f32 v[200:201], v[200:201], v[242:243] op_sel_hi:[1,0] neg_lo:[0,1] neg_hi:[0,1]
	v_pk_add_f32 v[202:203], v[202:203], v[242:243] op_sel_hi:[1,0] neg_lo:[0,1] neg_hi:[0,1]
	v_pk_mul_f32 v[188:189], v[188:189], v[242:243] op_sel:[0,1] op_sel_hi:[1,1]
	v_pk_mul_f32 v[190:191], v[190:191], v[242:243] op_sel:[0,1] op_sel_hi:[1,1]
	v_pk_mul_f32 v[192:193], v[192:193], v[242:243] op_sel:[0,1] op_sel_hi:[1,1]
	v_pk_mul_f32 v[194:195], v[194:195], v[242:243] op_sel:[0,1] op_sel_hi:[1,1]
	v_pk_mul_f32 v[196:197], v[196:197], v[242:243] op_sel:[0,1] op_sel_hi:[1,1]
	v_pk_mul_f32 v[198:199], v[198:199], v[242:243] op_sel:[0,1] op_sel_hi:[1,1]
	v_pk_mul_f32 v[200:201], v[200:201], v[242:243] op_sel:[0,1] op_sel_hi:[1,1]
	v_pk_mul_f32 v[202:203], v[202:203], v[242:243] op_sel:[0,1] op_sel_hi:[1,1]
	v_pk_fma_f32 v[188:189], v[4:5], v[188:189], v[20:21]
	v_pk_fma_f32 v[190:191], v[6:7], v[190:191], v[22:23]
	v_pk_fma_f32 v[192:193], v[8:9], v[192:193], v[24:25]
	v_pk_fma_f32 v[194:195], v[10:11], v[194:195], v[26:27]
	v_pk_fma_f32 v[196:197], v[12:13], v[196:197], v[28:29]
	v_pk_fma_f32 v[198:199], v[14:15], v[198:199], v[30:31]
	v_pk_fma_f32 v[200:201], v[16:17], v[200:201], v[32:33]
	v_pk_fma_f32 v[202:203], v[18:19], v[202:203], v[34:35]
	v_cvt_pk_bf16_f32 v188, v188, v189
	v_cvt_pk_bf16_f32 v189, v190, v191
	v_cvt_pk_bf16_f32 v190, v192, v193
	v_cvt_pk_bf16_f32 v191, v194, v195
	v_cvt_pk_bf16_f32 v196, v196, v197
	v_cvt_pk_bf16_f32 v197, v198, v199
	v_cvt_pk_bf16_f32 v198, v200, v201
	v_cvt_pk_bf16_f32 v199, v202, v203
	v_lshl_add_u32 v3, s42, 11, v2
	global_store_dwordx4 v3, v[188:191], s[96:97] sc1
	global_store_dwordx4 v3, v[196:199], s[96:97] offset:1024 sc1
	v_pk_add_f32 v[204:205], v[204:205], v[244:245] op_sel_hi:[1,0] neg_lo:[0,1] neg_hi:[0,1]
	v_pk_add_f32 v[206:207], v[206:207], v[244:245] op_sel_hi:[1,0] neg_lo:[0,1] neg_hi:[0,1]
	v_pk_add_f32 v[208:209], v[208:209], v[244:245] op_sel_hi:[1,0] neg_lo:[0,1] neg_hi:[0,1]
	v_pk_add_f32 v[210:211], v[210:211], v[244:245] op_sel_hi:[1,0] neg_lo:[0,1] neg_hi:[0,1]
	v_pk_add_f32 v[212:213], v[212:213], v[244:245] op_sel_hi:[1,0] neg_lo:[0,1] neg_hi:[0,1]
	v_pk_add_f32 v[214:215], v[214:215], v[244:245] op_sel_hi:[1,0] neg_lo:[0,1] neg_hi:[0,1]
	v_pk_add_f32 v[216:217], v[216:217], v[244:245] op_sel_hi:[1,0] neg_lo:[0,1] neg_hi:[0,1]
	v_pk_add_f32 v[218:219], v[218:219], v[244:245] op_sel_hi:[1,0] neg_lo:[0,1] neg_hi:[0,1]
	v_pk_mul_f32 v[204:205], v[204:205], v[244:245] op_sel:[0,1] op_sel_hi:[1,1]
	v_pk_mul_f32 v[206:207], v[206:207], v[244:245] op_sel:[0,1] op_sel_hi:[1,1]
	v_pk_mul_f32 v[208:209], v[208:209], v[244:245] op_sel:[0,1] op_sel_hi:[1,1]
	v_pk_mul_f32 v[210:211], v[210:211], v[244:245] op_sel:[0,1] op_sel_hi:[1,1]
	v_pk_mul_f32 v[212:213], v[212:213], v[244:245] op_sel:[0,1] op_sel_hi:[1,1]
	v_pk_mul_f32 v[214:215], v[214:215], v[244:245] op_sel:[0,1] op_sel_hi:[1,1]
	v_pk_mul_f32 v[216:217], v[216:217], v[244:245] op_sel:[0,1] op_sel_hi:[1,1]
	v_pk_mul_f32 v[218:219], v[218:219], v[244:245] op_sel:[0,1] op_sel_hi:[1,1]
	v_pk_fma_f32 v[204:205], v[4:5], v[204:205], v[20:21]
	v_pk_fma_f32 v[206:207], v[6:7], v[206:207], v[22:23]
	v_pk_fma_f32 v[208:209], v[8:9], v[208:209], v[24:25]
	v_pk_fma_f32 v[210:211], v[10:11], v[210:211], v[26:27]
	v_pk_fma_f32 v[212:213], v[12:13], v[212:213], v[28:29]
	v_pk_fma_f32 v[214:215], v[14:15], v[214:215], v[30:31]
	v_pk_fma_f32 v[216:217], v[16:17], v[216:217], v[32:33]
	v_pk_fma_f32 v[218:219], v[18:19], v[218:219], v[34:35]
	v_cvt_pk_bf16_f32 v204, v204, v205
	v_cvt_pk_bf16_f32 v205, v206, v207
	v_cvt_pk_bf16_f32 v206, v208, v209
	v_cvt_pk_bf16_f32 v207, v210, v211
	v_cvt_pk_bf16_f32 v212, v212, v213
	v_cvt_pk_bf16_f32 v213, v214, v215
	v_cvt_pk_bf16_f32 v214, v216, v217
	v_cvt_pk_bf16_f32 v215, v218, v219
	v_lshl_add_u32 v3, s43, 11, v2
	global_store_dwordx4 v3, v[204:207], s[96:97] sc1
	global_store_dwordx4 v3, v[212:215], s[96:97] offset:1024 sc1
	s_mov_b64 s[52:53], exec
	s_mov_b64 exec, 1
	v_mov_b32_e32 v3, s40
	v_lshlrev_b32_e32 v3, 3, v3
	global_store_dwordx2 v3, v[238:239], s[92:93] sc1
	v_mov_b32_e32 v3, s41
	v_lshlrev_b32_e32 v3, 3, v3
	global_store_dwordx2 v3, v[240:241], s[92:93] sc1
	v_mov_b32_e32 v3, s42
	v_lshlrev_b32_e32 v3, 3, v3
	global_store_dwordx2 v3, v[242:243], s[92:93] sc1
	v_mov_b32_e32 v3, s43
	v_lshlrev_b32_e32 v3, 3, v3
	global_store_dwordx2 v3, v[244:245], s[92:93] sc1
	s_mov_b64 exec, s[52:53]
	s_add_u32 s40, s46, 0x4800
	v_lshl_add_u32 v132, s40, 12, v1
	s_add_u32 s41, s46, 0x5800
	v_lshl_add_u32 v133, s41, 12, v1
	s_add_u32 s42, s46, 0x6800
	v_lshl_add_u32 v134, s42, 12, v1
	s_add_u32 s43, s46, 0x7800
	v_lshl_add_u32 v135, s43, 12, v1
	global_load_dwordx4 v[156:159], v132, s[64:65]
	global_load_dwordx4 v[160:163], v132, s[64:65] offset:16
	global_load_dwordx4 v[164:167], v132, s[64:65] offset:2048
	global_load_dwordx4 v[168:171], v132, s[64:65] offset:2064
	global_load_dwordx4 v[172:175], v133, s[64:65]
	global_load_dwordx4 v[176:179], v133, s[64:65] offset:16
	global_load_dwordx4 v[180:183], v133, s[64:65] offset:2048
	global_load_dwordx4 v[184:187], v133, s[64:65] offset:2064
	global_load_dwordx4 v[188:191], v134, s[64:65]
	global_load_dwordx4 v[192:195], v134, s[64:65] offset:16
	global_load_dwordx4 v[196:199], v134, s[64:65] offset:2048
	global_load_dwordx4 v[200:203], v134, s[64:65] offset:2064
	global_load_dwordx4 v[204:207], v135, s[64:65]
	global_load_dwordx4 v[208:211], v135, s[64:65] offset:16
	global_load_dwordx4 v[212:215], v135, s[64:65] offset:2048
	global_load_dwordx4 v[216:219], v135, s[64:65] offset:2064
	s_waitcnt vmcnt(28)
	v_pk_add_f32 v[108:109], v[36:37], v[38:39]
	v_pk_add_f32 v[110:111], v[40:41], v[42:43]
	v_pk_add_f32 v[112:113], v[44:45], v[46:47]
	v_pk_add_f32 v[114:115], v[48:49], v[50:51]
	v_pk_mul_f32 v[116:117], v[36:37], v[36:37]
	v_pk_fma_f32 v[116:117], v[38:39], v[38:39], v[116:117]
	v_pk_fma_f32 v[116:117], v[40:41], v[40:41], v[116:117]
	v_pk_fma_f32 v[116:117], v[42:43], v[42:43], v[116:117]
	v_pk_fma_f32 v[116:117], v[44:45], v[44:45], v[116:117]
	v_pk_fma_f32 v[116:117], v[46:47], v[46:47], v[116:117]
	v_pk_fma_f32 v[116:117], v[48:49], v[48:49], v[116:117]
	v_pk_fma_f32 v[116:117], v[50:51], v[50:51], v[116:117]
	v_pk_add_f32 v[108:109], v[108:109], v[110:111]
	v_pk_add_f32 v[112:113], v[112:113], v[114:115]
	v_pk_add_f32 v[108:109], v[108:109], v[112:113]
	v_add_f32_e32 v100, v108, v109
	v_add_f32_e32 v101, v116, v117
	v_pk_add_f32 v[108:109], v[52:53], v[54:55]
	v_pk_add_f32 v[110:111], v[56:57], v[58:59]
	v_pk_add_f32 v[112:113], v[60:61], v[62:63]
	v_pk_add_f32 v[114:115], v[64:65], v[66:67]
	v_pk_mul_f32 v[116:117], v[52:53], v[52:53]
	v_pk_fma_f32 v[116:117], v[54:55], v[54:55], v[116:117]
	v_pk_fma_f32 v[116:117], v[56:57], v[56:57], v[116:117]
	v_pk_fma_f32 v[116:117], v[58:59], v[58:59], v[116:117]
	v_pk_fma_f32 v[116:117], v[60:61], v[60:61], v[116:117]
	v_pk_fma_f32 v[116:117], v[62:63], v[62:63], v[116:117]
	v_pk_fma_f32 v[116:117], v[64:65], v[64:65], v[116:117]
	v_pk_fma_f32 v[116:117], v[66:67], v[66:67], v[116:117]
	v_pk_add_f32 v[108:109], v[108:109], v[110:111]
	v_pk_add_f32 v[112:113], v[112:113], v[114:115]
	v_pk_add_f32 v[108:109], v[108:109], v[112:113]
	v_add_f32_e32 v102, v108, v109
	v_add_f32_e32 v103, v116, v117
	v_pk_add_f32 v[108:109], v[68:69], v[70:71]
	v_pk_add_f32 v[110:111], v[72:73], v[74:75]
	v_pk_add_f32 v[112:113], v[76:77], v[78:79]
	v_pk_add_f32 v[114:115], v[80:81], v[82:83]
	v_pk_mul_f32 v[116:117], v[68:69], v[68:69]
	v_pk_fma_f32 v[116:117], v[70:71], v[70:71], v[116:117]
	v_pk_fma_f32 v[116:117], v[72:73], v[72:73], v[116:117]
	v_pk_fma_f32 v[116:117], v[74:75], v[74:75], v[116:117]
	v_pk_fma_f32 v[116:117], v[76:77], v[76:77], v[116:117]
	v_pk_fma_f32 v[116:117], v[78:79], v[78:79], v[116:117]
	v_pk_fma_f32 v[116:117], v[80:81], v[80:81], v[116:117]
	v_pk_fma_f32 v[116:117], v[82:83], v[82:83], v[116:117]
	v_pk_add_f32 v[108:109], v[108:109], v[110:111]
	v_pk_add_f32 v[112:113], v[112:113], v[114:115]
	v_pk_add_f32 v[108:109], v[108:109], v[112:113]
	v_add_f32_e32 v104, v108, v109
	v_add_f32_e32 v105, v116, v117
	v_pk_add_f32 v[108:109], v[84:85], v[86:87]
	v_pk_add_f32 v[110:111], v[88:89], v[90:91]
	v_pk_add_f32 v[112:113], v[92:93], v[94:95]
	v_pk_add_f32 v[114:115], v[96:97], v[98:99]
	v_pk_mul_f32 v[116:117], v[84:85], v[84:85]
	v_pk_fma_f32 v[116:117], v[86:87], v[86:87], v[116:117]
	v_pk_fma_f32 v[116:117], v[88:89], v[88:89], v[116:117]
	v_pk_fma_f32 v[116:117], v[90:91], v[90:91], v[116:117]
	v_pk_fma_f32 v[116:117], v[92:93], v[92:93], v[116:117]
	v_pk_fma_f32 v[116:117], v[94:95], v[94:95], v[116:117]
	v_pk_fma_f32 v[116:117], v[96:97], v[96:97], v[116:117]
	v_pk_fma_f32 v[116:117], v[98:99], v[98:99], v[116:117]
	v_pk_add_f32 v[108:109], v[108:109], v[110:111]
	v_pk_add_f32 v[112:113], v[112:113], v[114:115]
	v_pk_add_f32 v[108:109], v[108:109], v[112:113]
	v_add_f32_e32 v106, v108, v109
	v_add_f32_e32 v107, v116, v117
	v_add_f32_dpp v100, v100, v100 quad_perm:[1,0,3,2] row_mask:0xf bank_mask:0xf
	v_add_f32_dpp v101, v101, v101 quad_perm:[1,0,3,2] row_mask:0xf bank_mask:0xf
	v_add_f32_dpp v102, v102, v102 quad_perm:[1,0,3,2] row_mask:0xf bank_mask:0xf
	v_add_f32_dpp v103, v103, v103 quad_perm:[1,0,3,2] row_mask:0xf bank_mask:0xf
	v_add_f32_dpp v104, v104, v104 quad_perm:[1,0,3,2] row_mask:0xf bank_mask:0xf
	v_add_f32_dpp v105, v105, v105 quad_perm:[1,0,3,2] row_mask:0xf bank_mask:0xf
	v_add_f32_dpp v106, v106, v106 quad_perm:[1,0,3,2] row_mask:0xf bank_mask:0xf
	v_add_f32_dpp v107, v107, v107 quad_perm:[1,0,3,2] row_mask:0xf bank_mask:0xf
	v_add_f32_dpp v100, v100, v100 quad_perm:[2,3,0,1] row_mask:0xf bank_mask:0xf
	v_add_f32_dpp v101, v101, v101 quad_perm:[2,3,0,1] row_mask:0xf bank_mask:0xf
	v_add_f32_dpp v102, v102, v102 quad_perm:[2,3,0,1] row_mask:0xf bank_mask:0xf
	v_add_f32_dpp v103, v103, v103 quad_perm:[2,3,0,1] row_mask:0xf bank_mask:0xf
	v_add_f32_dpp v104, v104, v104 quad_perm:[2,3,0,1] row_mask:0xf bank_mask:0xf
	v_add_f32_dpp v105, v105, v105 quad_perm:[2,3,0,1] row_mask:0xf bank_mask:0xf
	v_add_f32_dpp v106, v106, v106 quad_perm:[2,3,0,1] row_mask:0xf bank_mask:0xf
	v_add_f32_dpp v107, v107, v107 quad_perm:[2,3,0,1] row_mask:0xf bank_mask:0xf
	v_add_f32_dpp v100, v100, v100 row_half_mirror row_mask:0xf bank_mask:0xf
	v_add_f32_dpp v101, v101, v101 row_half_mirror row_mask:0xf bank_mask:0xf
	v_add_f32_dpp v102, v102, v102 row_half_mirror row_mask:0xf bank_mask:0xf
	v_add_f32_dpp v103, v103, v103 row_half_mirror row_mask:0xf bank_mask:0xf
	v_add_f32_dpp v104, v104, v104 row_half_mirror row_mask:0xf bank_mask:0xf
	v_add_f32_dpp v105, v105, v105 row_half_mirror row_mask:0xf bank_mask:0xf
	v_add_f32_dpp v106, v106, v106 row_half_mirror row_mask:0xf bank_mask:0xf
	v_add_f32_dpp v107, v107, v107 row_half_mirror row_mask:0xf bank_mask:0xf
	v_add_f32_dpp v100, v100, v100 row_mirror row_mask:0xf bank_mask:0xf
	v_add_f32_dpp v101, v101, v101 row_mirror row_mask:0xf bank_mask:0xf
	v_add_f32_dpp v102, v102, v102 row_mirror row_mask:0xf bank_mask:0xf
	v_add_f32_dpp v103, v103, v103 row_mirror row_mask:0xf bank_mask:0xf
	v_add_f32_dpp v104, v104, v104 row_mirror row_mask:0xf bank_mask:0xf
	v_add_f32_dpp v105, v105, v105 row_mirror row_mask:0xf bank_mask:0xf
	v_add_f32_dpp v106, v106, v106 row_mirror row_mask:0xf bank_mask:0xf
	v_add_f32_dpp v107, v107, v107 row_mirror row_mask:0xf bank_mask:0xf
	v_mov_b32_e32 v108, v100
	v_mov_b32_e32 v109, v101
	v_mov_b32_e32 v110, v102
	v_mov_b32_e32 v111, v103
	v_mov_b32_e32 v112, v104
	v_mov_b32_e32 v113, v105
	v_mov_b32_e32 v114, v106
	v_mov_b32_e32 v115, v107
	s_nop 1
	v_permlane16_swap_b32_e32 v108, v100
	v_permlane16_swap_b32_e32 v109, v101
	v_permlane16_swap_b32_e32 v110, v102
	v_permlane16_swap_b32_e32 v111, v103
	v_permlane16_swap_b32_e32 v112, v104
	v_permlane16_swap_b32_e32 v113, v105
	v_permlane16_swap_b32_e32 v114, v106
	v_permlane16_swap_b32_e32 v115, v107
	v_add_f32_e32 v100, v100, v108
	v_add_f32_e32 v101, v101, v109
	v_add_f32_e32 v102, v102, v110
	v_add_f32_e32 v103, v103, v111
	v_add_f32_e32 v104, v104, v112
	v_add_f32_e32 v105, v105, v113
	v_add_f32_e32 v106, v106, v114
	v_add_f32_e32 v107, v107, v115
	v_mov_b32_e32 v108, v100
	v_mov_b32_e32 v109, v101
	v_mov_b32_e32 v110, v102
	v_mov_b32_e32 v111, v103
	v_mov_b32_e32 v112, v104
	v_mov_b32_e32 v113, v105
	v_mov_b32_e32 v114, v106
	v_mov_b32_e32 v115, v107
	s_nop 1
	v_permlane32_swap_b32_e32 v108, v100
	v_permlane32_swap_b32_e32 v109, v101
	v_permlane32_swap_b32_e32 v110, v102
	v_permlane32_swap_b32_e32 v111, v103
	v_permlane32_swap_b32_e32 v112, v104
	v_permlane32_swap_b32_e32 v113, v105
	v_permlane32_swap_b32_e32 v114, v106
	v_permlane32_swap_b32_e32 v115, v107
	v_add_f32_e32 v100, v100, v108
	v_add_f32_e32 v101, v101, v109
	v_add_f32_e32 v102, v102, v110
	v_add_f32_e32 v103, v103, v111
	v_add_f32_e32 v104, v104, v112
	v_add_f32_e32 v105, v105, v113
	v_add_f32_e32 v106, v106, v114
	v_add_f32_e32 v107, v107, v115
	v_mul_f32_e32 v230, 0x3a800000, v100
	v_mul_f32_e32 v116, 0x3a800000, v101
	v_fma_f32 v116, -v230, v230, v116
	v_max_f32_e32 v116, 0, v116
	v_add_f32_e32 v116, 0x3727c5ac, v116
	v_mul_f32_e32 v232, 0x3a800000, v102
	v_mul_f32_e32 v118, 0x3a800000, v103
	v_fma_f32 v118, -v232, v232, v118
	v_max_f32_e32 v118, 0, v118
	v_add_f32_e32 v118, 0x3727c5ac, v118
	v_mul_f32_e32 v234, 0x3a800000, v104
	v_mul_f32_e32 v120, 0x3a800000, v105
	v_fma_f32 v120, -v234, v234, v120
	v_max_f32_e32 v120, 0, v120
	v_add_f32_e32 v120, 0x3727c5ac, v120
	v_mul_f32_e32 v236, 0x3a800000, v106
	v_mul_f32_e32 v122, 0x3a800000, v107
	v_fma_f32 v122, -v236, v236, v122
	v_max_f32_e32 v122, 0, v122
	v_add_f32_e32 v122, 0x3727c5ac, v122
	v_rsq_f32_e32 v117, v116
	v_rsq_f32_e32 v119, v118
	v_rsq_f32_e32 v121, v120
	v_rsq_f32_e32 v123, v122
	s_nop 0
	v_mul_f32_e32 v124, v116, v117
	v_mul_f32_e32 v124, v124, v117
	v_fmaak_f32 v124, -0.5, v124, 0x3fc00000
	v_mul_f32_e32 v231, v117, v124
	v_mul_f32_e32 v125, v118, v119
	v_mul_f32_e32 v125, v125, v119
	v_fmaak_f32 v125, -0.5, v125, 0x3fc00000
	v_mul_f32_e32 v233, v119, v125
	v_mul_f32_e32 v126, v120, v121
	v_mul_f32_e32 v126, v126, v121
	v_fmaak_f32 v126, -0.5, v126, 0x3fc00000
	v_mul_f32_e32 v235, v121, v126
	v_mul_f32_e32 v127, v122, v123
	v_mul_f32_e32 v127, v127, v123
	v_fmaak_f32 v127, -0.5, v127, 0x3fc00000
	v_mul_f32_e32 v237, v123, v127
	v_pk_add_f32 v[36:37], v[36:37], v[230:231] op_sel_hi:[1,0] neg_lo:[0,1] neg_hi:[0,1]
	v_pk_add_f32 v[38:39], v[38:39], v[230:231] op_sel_hi:[1,0] neg_lo:[0,1] neg_hi:[0,1]
	v_pk_add_f32 v[40:41], v[40:41], v[230:231] op_sel_hi:[1,0] neg_lo:[0,1] neg_hi:[0,1]
	v_pk_add_f32 v[42:43], v[42:43], v[230:231] op_sel_hi:[1,0] neg_lo:[0,1] neg_hi:[0,1]
	v_pk_add_f32 v[44:45], v[44:45], v[230:231] op_sel_hi:[1,0] neg_lo:[0,1] neg_hi:[0,1]
	v_pk_add_f32 v[46:47], v[46:47], v[230:231] op_sel_hi:[1,0] neg_lo:[0,1] neg_hi:[0,1]
	v_pk_add_f32 v[48:49], v[48:49], v[230:231] op_sel_hi:[1,0] neg_lo:[0,1] neg_hi:[0,1]
	v_pk_add_f32 v[50:51], v[50:51], v[230:231] op_sel_hi:[1,0] neg_lo:[0,1] neg_hi:[0,1]
	v_pk_mul_f32 v[36:37], v[36:37], v[230:231] op_sel:[0,1] op_sel_hi:[1,1]
	v_pk_mul_f32 v[38:39], v[38:39], v[230:231] op_sel:[0,1] op_sel_hi:[1,1]
	v_pk_mul_f32 v[40:41], v[40:41], v[230:231] op_sel:[0,1] op_sel_hi:[1,1]
	v_pk_mul_f32 v[42:43], v[42:43], v[230:231] op_sel:[0,1] op_sel_hi:[1,1]
	v_pk_mul_f32 v[44:45], v[44:45], v[230:231] op_sel:[0,1] op_sel_hi:[1,1]
	v_pk_mul_f32 v[46:47], v[46:47], v[230:231] op_sel:[0,1] op_sel_hi:[1,1]
	v_pk_mul_f32 v[48:49], v[48:49], v[230:231] op_sel:[0,1] op_sel_hi:[1,1]
	v_pk_mul_f32 v[50:51], v[50:51], v[230:231] op_sel:[0,1] op_sel_hi:[1,1]
	v_pk_fma_f32 v[36:37], v[4:5], v[36:37], v[20:21]
	v_pk_fma_f32 v[38:39], v[6:7], v[38:39], v[22:23]
	v_pk_fma_f32 v[40:41], v[8:9], v[40:41], v[24:25]
	v_pk_fma_f32 v[42:43], v[10:11], v[42:43], v[26:27]
	v_pk_fma_f32 v[44:45], v[12:13], v[44:45], v[28:29]
	v_pk_fma_f32 v[46:47], v[14:15], v[46:47], v[30:31]
	v_pk_fma_f32 v[48:49], v[16:17], v[48:49], v[32:33]
	v_pk_fma_f32 v[50:51], v[18:19], v[50:51], v[34:35]
	v_cvt_pk_bf16_f32 v36, v36, v37
	v_cvt_pk_bf16_f32 v37, v38, v39
	v_cvt_pk_bf16_f32 v38, v40, v41
	v_cvt_pk_bf16_f32 v39, v42, v43
	v_cvt_pk_bf16_f32 v44, v44, v45
	v_cvt_pk_bf16_f32 v45, v46, v47
	v_cvt_pk_bf16_f32 v46, v48, v49
	v_cvt_pk_bf16_f32 v47, v50, v51
	v_lshl_add_u32 v3, s36, 11, v2
	global_store_dwordx4 v3, v[36:39], s[96:97] sc1
	global_store_dwordx4 v3, v[44:47], s[96:97] offset:1024 sc1
	v_pk_add_f32 v[52:53], v[52:53], v[232:233] op_sel_hi:[1,0] neg_lo:[0,1] neg_hi:[0,1]
	v_pk_add_f32 v[54:55], v[54:55], v[232:233] op_sel_hi:[1,0] neg_lo:[0,1] neg_hi:[0,1]
	v_pk_add_f32 v[56:57], v[56:57], v[232:233] op_sel_hi:[1,0] neg_lo:[0,1] neg_hi:[0,1]
	v_pk_add_f32 v[58:59], v[58:59], v[232:233] op_sel_hi:[1,0] neg_lo:[0,1] neg_hi:[0,1]
	v_pk_add_f32 v[60:61], v[60:61], v[232:233] op_sel_hi:[1,0] neg_lo:[0,1] neg_hi:[0,1]
	v_pk_add_f32 v[62:63], v[62:63], v[232:233] op_sel_hi:[1,0] neg_lo:[0,1] neg_hi:[0,1]
	v_pk_add_f32 v[64:65], v[64:65], v[232:233] op_sel_hi:[1,0] neg_lo:[0,1] neg_hi:[0,1]
	v_pk_add_f32 v[66:67], v[66:67], v[232:233] op_sel_hi:[1,0] neg_lo:[0,1] neg_hi:[0,1]
	v_pk_mul_f32 v[52:53], v[52:53], v[232:233] op_sel:[0,1] op_sel_hi:[1,1]
	v_pk_mul_f32 v[54:55], v[54:55], v[232:233] op_sel:[0,1] op_sel_hi:[1,1]
	v_pk_mul_f32 v[56:57], v[56:57], v[232:233] op_sel:[0,1] op_sel_hi:[1,1]
	v_pk_mul_f32 v[58:59], v[58:59], v[232:233] op_sel:[0,1] op_sel_hi:[1,1]
	v_pk_mul_f32 v[60:61], v[60:61], v[232:233] op_sel:[0,1] op_sel_hi:[1,1]
	v_pk_mul_f32 v[62:63], v[62:63], v[232:233] op_sel:[0,1] op_sel_hi:[1,1]
	v_pk_mul_f32 v[64:65], v[64:65], v[232:233] op_sel:[0,1] op_sel_hi:[1,1]
	v_pk_mul_f32 v[66:67], v[66:67], v[232:233] op_sel:[0,1] op_sel_hi:[1,1]
	v_pk_fma_f32 v[52:53], v[4:5], v[52:53], v[20:21]
	v_pk_fma_f32 v[54:55], v[6:7], v[54:55], v[22:23]
	v_pk_fma_f32 v[56:57], v[8:9], v[56:57], v[24:25]
	v_pk_fma_f32 v[58:59], v[10:11], v[58:59], v[26:27]
	v_pk_fma_f32 v[60:61], v[12:13], v[60:61], v[28:29]
	v_pk_fma_f32 v[62:63], v[14:15], v[62:63], v[30:31]
	v_pk_fma_f32 v[64:65], v[16:17], v[64:65], v[32:33]
	v_pk_fma_f32 v[66:67], v[18:19], v[66:67], v[34:35]
	v_cvt_pk_bf16_f32 v52, v52, v53
	v_cvt_pk_bf16_f32 v53, v54, v55
	v_cvt_pk_bf16_f32 v54, v56, v57
	v_cvt_pk_bf16_f32 v55, v58, v59
	v_cvt_pk_bf16_f32 v60, v60, v61
	v_cvt_pk_bf16_f32 v61, v62, v63
	v_cvt_pk_bf16_f32 v62, v64, v65
	v_cvt_pk_bf16_f32 v63, v66, v67
	v_lshl_add_u32 v3, s37, 11, v2
	global_store_dwordx4 v3, v[52:55], s[96:97] sc1
	global_store_dwordx4 v3, v[60:63], s[96:97] offset:1024 sc1
	v_pk_add_f32 v[68:69], v[68:69], v[234:235] op_sel_hi:[1,0] neg_lo:[0,1] neg_hi:[0,1]
	v_pk_add_f32 v[70:71], v[70:71], v[234:235] op_sel_hi:[1,0] neg_lo:[0,1] neg_hi:[0,1]
	v_pk_add_f32 v[72:73], v[72:73], v[234:235] op_sel_hi:[1,0] neg_lo:[0,1] neg_hi:[0,1]
	v_pk_add_f32 v[74:75], v[74:75], v[234:235] op_sel_hi:[1,0] neg_lo:[0,1] neg_hi:[0,1]
	v_pk_add_f32 v[76:77], v[76:77], v[234:235] op_sel_hi:[1,0] neg_lo:[0,1] neg_hi:[0,1]
	v_pk_add_f32 v[78:79], v[78:79], v[234:235] op_sel_hi:[1,0] neg_lo:[0,1] neg_hi:[0,1]
	v_pk_add_f32 v[80:81], v[80:81], v[234:235] op_sel_hi:[1,0] neg_lo:[0,1] neg_hi:[0,1]
	v_pk_add_f32 v[82:83], v[82:83], v[234:235] op_sel_hi:[1,0] neg_lo:[0,1] neg_hi:[0,1]
	v_pk_mul_f32 v[68:69], v[68:69], v[234:235] op_sel:[0,1] op_sel_hi:[1,1]
	v_pk_mul_f32 v[70:71], v[70:71], v[234:235] op_sel:[0,1] op_sel_hi:[1,1]
	v_pk_mul_f32 v[72:73], v[72:73], v[234:235] op_sel:[0,1] op_sel_hi:[1,1]
	v_pk_mul_f32 v[74:75], v[74:75], v[234:235] op_sel:[0,1] op_sel_hi:[1,1]
	v_pk_mul_f32 v[76:77], v[76:77], v[234:235] op_sel:[0,1] op_sel_hi:[1,1]
	v_pk_mul_f32 v[78:79], v[78:79], v[234:235] op_sel:[0,1] op_sel_hi:[1,1]
	v_pk_mul_f32 v[80:81], v[80:81], v[234:235] op_sel:[0,1] op_sel_hi:[1,1]
	v_pk_mul_f32 v[82:83], v[82:83], v[234:235] op_sel:[0,1] op_sel_hi:[1,1]
	v_pk_fma_f32 v[68:69], v[4:5], v[68:69], v[20:21]
	v_pk_fma_f32 v[70:71], v[6:7], v[70:71], v[22:23]
	v_pk_fma_f32 v[72:73], v[8:9], v[72:73], v[24:25]
	v_pk_fma_f32 v[74:75], v[10:11], v[74:75], v[26:27]
	v_pk_fma_f32 v[76:77], v[12:13], v[76:77], v[28:29]
	v_pk_fma_f32 v[78:79], v[14:15], v[78:79], v[30:31]
	v_pk_fma_f32 v[80:81], v[16:17], v[80:81], v[32:33]
	v_pk_fma_f32 v[82:83], v[18:19], v[82:83], v[34:35]
	v_cvt_pk_bf16_f32 v68, v68, v69
	v_cvt_pk_bf16_f32 v69, v70, v71
	v_cvt_pk_bf16_f32 v70, v72, v73
	v_cvt_pk_bf16_f32 v71, v74, v75
	v_cvt_pk_bf16_f32 v76, v76, v77
	v_cvt_pk_bf16_f32 v77, v78, v79
	v_cvt_pk_bf16_f32 v78, v80, v81
	v_cvt_pk_bf16_f32 v79, v82, v83
	v_lshl_add_u32 v3, s38, 11, v2
	global_store_dwordx4 v3, v[68:71], s[96:97] sc1
	global_store_dwordx4 v3, v[76:79], s[96:97] offset:1024 sc1
	v_pk_add_f32 v[84:85], v[84:85], v[236:237] op_sel_hi:[1,0] neg_lo:[0,1] neg_hi:[0,1]
	v_pk_add_f32 v[86:87], v[86:87], v[236:237] op_sel_hi:[1,0] neg_lo:[0,1] neg_hi:[0,1]
	v_pk_add_f32 v[88:89], v[88:89], v[236:237] op_sel_hi:[1,0] neg_lo:[0,1] neg_hi:[0,1]
	v_pk_add_f32 v[90:91], v[90:91], v[236:237] op_sel_hi:[1,0] neg_lo:[0,1] neg_hi:[0,1]
	v_pk_add_f32 v[92:93], v[92:93], v[236:237] op_sel_hi:[1,0] neg_lo:[0,1] neg_hi:[0,1]
	v_pk_add_f32 v[94:95], v[94:95], v[236:237] op_sel_hi:[1,0] neg_lo:[0,1] neg_hi:[0,1]
	v_pk_add_f32 v[96:97], v[96:97], v[236:237] op_sel_hi:[1,0] neg_lo:[0,1] neg_hi:[0,1]
	v_pk_add_f32 v[98:99], v[98:99], v[236:237] op_sel_hi:[1,0] neg_lo:[0,1] neg_hi:[0,1]
	v_pk_mul_f32 v[84:85], v[84:85], v[236:237] op_sel:[0,1] op_sel_hi:[1,1]
	v_pk_mul_f32 v[86:87], v[86:87], v[236:237] op_sel:[0,1] op_sel_hi:[1,1]
	v_pk_mul_f32 v[88:89], v[88:89], v[236:237] op_sel:[0,1] op_sel_hi:[1,1]
	v_pk_mul_f32 v[90:91], v[90:91], v[236:237] op_sel:[0,1] op_sel_hi:[1,1]
	v_pk_mul_f32 v[92:93], v[92:93], v[236:237] op_sel:[0,1] op_sel_hi:[1,1]
	v_pk_mul_f32 v[94:95], v[94:95], v[236:237] op_sel:[0,1] op_sel_hi:[1,1]
	v_pk_mul_f32 v[96:97], v[96:97], v[236:237] op_sel:[0,1] op_sel_hi:[1,1]
	v_pk_mul_f32 v[98:99], v[98:99], v[236:237] op_sel:[0,1] op_sel_hi:[1,1]
	v_pk_fma_f32 v[84:85], v[4:5], v[84:85], v[20:21]
	v_pk_fma_f32 v[86:87], v[6:7], v[86:87], v[22:23]
	v_pk_fma_f32 v[88:89], v[8:9], v[88:89], v[24:25]
	v_pk_fma_f32 v[90:91], v[10:11], v[90:91], v[26:27]
	v_pk_fma_f32 v[92:93], v[12:13], v[92:93], v[28:29]
	v_pk_fma_f32 v[94:95], v[14:15], v[94:95], v[30:31]
	v_pk_fma_f32 v[96:97], v[16:17], v[96:97], v[32:33]
	v_pk_fma_f32 v[98:99], v[18:19], v[98:99], v[34:35]
	v_cvt_pk_bf16_f32 v84, v84, v85
	v_cvt_pk_bf16_f32 v85, v86, v87
	v_cvt_pk_bf16_f32 v86, v88, v89
	v_cvt_pk_bf16_f32 v87, v90, v91
	v_cvt_pk_bf16_f32 v92, v92, v93
	v_cvt_pk_bf16_f32 v93, v94, v95
	v_cvt_pk_bf16_f32 v94, v96, v97
	v_cvt_pk_bf16_f32 v95, v98, v99
	v_lshl_add_u32 v3, s39, 11, v2
	global_store_dwordx4 v3, v[84:87], s[96:97] sc1
	global_store_dwordx4 v3, v[92:95], s[96:97] offset:1024 sc1
	s_mov_b64 s[52:53], exec
	s_mov_b64 exec, 1
	v_mov_b32_e32 v3, s36
	v_lshlrev_b32_e32 v3, 3, v3
	global_store_dwordx2 v3, v[230:231], s[92:93] sc1
	v_mov_b32_e32 v3, s37
	v_lshlrev_b32_e32 v3, 3, v3
	global_store_dwordx2 v3, v[232:233], s[92:93] sc1
	v_mov_b32_e32 v3, s38
	v_lshlrev_b32_e32 v3, 3, v3
	global_store_dwordx2 v3, v[234:235], s[92:93] sc1
	v_mov_b32_e32 v3, s39
	v_lshlrev_b32_e32 v3, 3, v3
	global_store_dwordx2 v3, v[236:237], s[92:93] sc1
	s_mov_b64 exec, s[52:53]
	s_waitcnt vmcnt(12)
	v_pk_add_f32 v[108:109], v[156:157], v[158:159]
	v_pk_add_f32 v[110:111], v[160:161], v[162:163]
	v_pk_add_f32 v[112:113], v[164:165], v[166:167]
	v_pk_add_f32 v[114:115], v[168:169], v[170:171]
	v_pk_mul_f32 v[116:117], v[156:157], v[156:157]
	v_pk_fma_f32 v[116:117], v[158:159], v[158:159], v[116:117]
	v_pk_fma_f32 v[116:117], v[160:161], v[160:161], v[116:117]
	v_pk_fma_f32 v[116:117], v[162:163], v[162:163], v[116:117]
	v_pk_fma_f32 v[116:117], v[164:165], v[164:165], v[116:117]
	v_pk_fma_f32 v[116:117], v[166:167], v[166:167], v[116:117]
	v_pk_fma_f32 v[116:117], v[168:169], v[168:169], v[116:117]
	v_pk_fma_f32 v[116:117], v[170:171], v[170:171], v[116:117]
	v_pk_add_f32 v[108:109], v[108:109], v[110:111]
	v_pk_add_f32 v[112:113], v[112:113], v[114:115]
	v_pk_add_f32 v[108:109], v[108:109], v[112:113]
	v_add_f32_e32 v100, v108, v109
	v_add_f32_e32 v101, v116, v117
	v_pk_add_f32 v[108:109], v[172:173], v[174:175]
	v_pk_add_f32 v[110:111], v[176:177], v[178:179]
	v_pk_add_f32 v[112:113], v[180:181], v[182:183]
	v_pk_add_f32 v[114:115], v[184:185], v[186:187]
	v_pk_mul_f32 v[116:117], v[172:173], v[172:173]
	v_pk_fma_f32 v[116:117], v[174:175], v[174:175], v[116:117]
	v_pk_fma_f32 v[116:117], v[176:177], v[176:177], v[116:117]
	v_pk_fma_f32 v[116:117], v[178:179], v[178:179], v[116:117]
	v_pk_fma_f32 v[116:117], v[180:181], v[180:181], v[116:117]
	v_pk_fma_f32 v[116:117], v[182:183], v[182:183], v[116:117]
	v_pk_fma_f32 v[116:117], v[184:185], v[184:185], v[116:117]
	v_pk_fma_f32 v[116:117], v[186:187], v[186:187], v[116:117]
	v_pk_add_f32 v[108:109], v[108:109], v[110:111]
	v_pk_add_f32 v[112:113], v[112:113], v[114:115]
	v_pk_add_f32 v[108:109], v[108:109], v[112:113]
	v_add_f32_e32 v102, v108, v109
	v_add_f32_e32 v103, v116, v117
	v_pk_add_f32 v[108:109], v[188:189], v[190:191]
	v_pk_add_f32 v[110:111], v[192:193], v[194:195]
	v_pk_add_f32 v[112:113], v[196:197], v[198:199]
	v_pk_add_f32 v[114:115], v[200:201], v[202:203]
	v_pk_mul_f32 v[116:117], v[188:189], v[188:189]
	v_pk_fma_f32 v[116:117], v[190:191], v[190:191], v[116:117]
	v_pk_fma_f32 v[116:117], v[192:193], v[192:193], v[116:117]
	v_pk_fma_f32 v[116:117], v[194:195], v[194:195], v[116:117]
	v_pk_fma_f32 v[116:117], v[196:197], v[196:197], v[116:117]
	v_pk_fma_f32 v[116:117], v[198:199], v[198:199], v[116:117]
	v_pk_fma_f32 v[116:117], v[200:201], v[200:201], v[116:117]
	v_pk_fma_f32 v[116:117], v[202:203], v[202:203], v[116:117]
	v_pk_add_f32 v[108:109], v[108:109], v[110:111]
	v_pk_add_f32 v[112:113], v[112:113], v[114:115]
	v_pk_add_f32 v[108:109], v[108:109], v[112:113]
	v_add_f32_e32 v104, v108, v109
	v_add_f32_e32 v105, v116, v117
	v_pk_add_f32 v[108:109], v[204:205], v[206:207]
	v_pk_add_f32 v[110:111], v[208:209], v[210:211]
	v_pk_add_f32 v[112:113], v[212:213], v[214:215]
	v_pk_add_f32 v[114:115], v[216:217], v[218:219]
	v_pk_mul_f32 v[116:117], v[204:205], v[204:205]
	v_pk_fma_f32 v[116:117], v[206:207], v[206:207], v[116:117]
	v_pk_fma_f32 v[116:117], v[208:209], v[208:209], v[116:117]
	v_pk_fma_f32 v[116:117], v[210:211], v[210:211], v[116:117]
	v_pk_fma_f32 v[116:117], v[212:213], v[212:213], v[116:117]
	v_pk_fma_f32 v[116:117], v[214:215], v[214:215], v[116:117]
	v_pk_fma_f32 v[116:117], v[216:217], v[216:217], v[116:117]
	v_pk_fma_f32 v[116:117], v[218:219], v[218:219], v[116:117]
	v_pk_add_f32 v[108:109], v[108:109], v[110:111]
	v_pk_add_f32 v[112:113], v[112:113], v[114:115]
	v_pk_add_f32 v[108:109], v[108:109], v[112:113]
	v_add_f32_e32 v106, v108, v109
	v_add_f32_e32 v107, v116, v117
	v_add_f32_dpp v100, v100, v100 quad_perm:[1,0,3,2] row_mask:0xf bank_mask:0xf
	v_add_f32_dpp v101, v101, v101 quad_perm:[1,0,3,2] row_mask:0xf bank_mask:0xf
	v_add_f32_dpp v102, v102, v102 quad_perm:[1,0,3,2] row_mask:0xf bank_mask:0xf
	v_add_f32_dpp v103, v103, v103 quad_perm:[1,0,3,2] row_mask:0xf bank_mask:0xf
	v_add_f32_dpp v104, v104, v104 quad_perm:[1,0,3,2] row_mask:0xf bank_mask:0xf
	v_add_f32_dpp v105, v105, v105 quad_perm:[1,0,3,2] row_mask:0xf bank_mask:0xf
	v_add_f32_dpp v106, v106, v106 quad_perm:[1,0,3,2] row_mask:0xf bank_mask:0xf
	v_add_f32_dpp v107, v107, v107 quad_perm:[1,0,3,2] row_mask:0xf bank_mask:0xf
	v_add_f32_dpp v100, v100, v100 quad_perm:[2,3,0,1] row_mask:0xf bank_mask:0xf
	v_add_f32_dpp v101, v101, v101 quad_perm:[2,3,0,1] row_mask:0xf bank_mask:0xf
	v_add_f32_dpp v102, v102, v102 quad_perm:[2,3,0,1] row_mask:0xf bank_mask:0xf
	v_add_f32_dpp v103, v103, v103 quad_perm:[2,3,0,1] row_mask:0xf bank_mask:0xf
	v_add_f32_dpp v104, v104, v104 quad_perm:[2,3,0,1] row_mask:0xf bank_mask:0xf
	v_add_f32_dpp v105, v105, v105 quad_perm:[2,3,0,1] row_mask:0xf bank_mask:0xf
	v_add_f32_dpp v106, v106, v106 quad_perm:[2,3,0,1] row_mask:0xf bank_mask:0xf
	v_add_f32_dpp v107, v107, v107 quad_perm:[2,3,0,1] row_mask:0xf bank_mask:0xf
	v_add_f32_dpp v100, v100, v100 row_half_mirror row_mask:0xf bank_mask:0xf
	v_add_f32_dpp v101, v101, v101 row_half_mirror row_mask:0xf bank_mask:0xf
	v_add_f32_dpp v102, v102, v102 row_half_mirror row_mask:0xf bank_mask:0xf
	v_add_f32_dpp v103, v103, v103 row_half_mirror row_mask:0xf bank_mask:0xf
	v_add_f32_dpp v104, v104, v104 row_half_mirror row_mask:0xf bank_mask:0xf
	v_add_f32_dpp v105, v105, v105 row_half_mirror row_mask:0xf bank_mask:0xf
	v_add_f32_dpp v106, v106, v106 row_half_mirror row_mask:0xf bank_mask:0xf
	v_add_f32_dpp v107, v107, v107 row_half_mirror row_mask:0xf bank_mask:0xf
	v_add_f32_dpp v100, v100, v100 row_mirror row_mask:0xf bank_mask:0xf
	v_add_f32_dpp v101, v101, v101 row_mirror row_mask:0xf bank_mask:0xf
	v_add_f32_dpp v102, v102, v102 row_mirror row_mask:0xf bank_mask:0xf
	v_add_f32_dpp v103, v103, v103 row_mirror row_mask:0xf bank_mask:0xf
	v_add_f32_dpp v104, v104, v104 row_mirror row_mask:0xf bank_mask:0xf
	v_add_f32_dpp v105, v105, v105 row_mirror row_mask:0xf bank_mask:0xf
	v_add_f32_dpp v106, v106, v106 row_mirror row_mask:0xf bank_mask:0xf
	v_add_f32_dpp v107, v107, v107 row_mirror row_mask:0xf bank_mask:0xf
	v_mov_b32_e32 v108, v100
	v_mov_b32_e32 v109, v101
	v_mov_b32_e32 v110, v102
	v_mov_b32_e32 v111, v103
	v_mov_b32_e32 v112, v104
	v_mov_b32_e32 v113, v105
	v_mov_b32_e32 v114, v106
	v_mov_b32_e32 v115, v107
	s_nop 1
	v_permlane16_swap_b32_e32 v108, v100
	v_permlane16_swap_b32_e32 v109, v101
	v_permlane16_swap_b32_e32 v110, v102
	v_permlane16_swap_b32_e32 v111, v103
	v_permlane16_swap_b32_e32 v112, v104
	v_permlane16_swap_b32_e32 v113, v105
	v_permlane16_swap_b32_e32 v114, v106
	v_permlane16_swap_b32_e32 v115, v107
	v_add_f32_e32 v100, v100, v108
	v_add_f32_e32 v101, v101, v109
	v_add_f32_e32 v102, v102, v110
	v_add_f32_e32 v103, v103, v111
	v_add_f32_e32 v104, v104, v112
	v_add_f32_e32 v105, v105, v113
	v_add_f32_e32 v106, v106, v114
	v_add_f32_e32 v107, v107, v115
	v_mov_b32_e32 v108, v100
	v_mov_b32_e32 v109, v101
	v_mov_b32_e32 v110, v102
	v_mov_b32_e32 v111, v103
	v_mov_b32_e32 v112, v104
	v_mov_b32_e32 v113, v105
	v_mov_b32_e32 v114, v106
	v_mov_b32_e32 v115, v107
	s_nop 1
	v_permlane32_swap_b32_e32 v108, v100
	v_permlane32_swap_b32_e32 v109, v101
	v_permlane32_swap_b32_e32 v110, v102
	v_permlane32_swap_b32_e32 v111, v103
	v_permlane32_swap_b32_e32 v112, v104
	v_permlane32_swap_b32_e32 v113, v105
	v_permlane32_swap_b32_e32 v114, v106
	v_permlane32_swap_b32_e32 v115, v107
	v_add_f32_e32 v100, v100, v108
	v_add_f32_e32 v101, v101, v109
	v_add_f32_e32 v102, v102, v110
	v_add_f32_e32 v103, v103, v111
	v_add_f32_e32 v104, v104, v112
	v_add_f32_e32 v105, v105, v113
	v_add_f32_e32 v106, v106, v114
	v_add_f32_e32 v107, v107, v115
	v_mul_f32_e32 v238, 0x3a800000, v100
	v_mul_f32_e32 v116, 0x3a800000, v101
	v_fma_f32 v116, -v238, v238, v116
	v_max_f32_e32 v116, 0, v116
	v_add_f32_e32 v116, 0x3727c5ac, v116
	v_mul_f32_e32 v240, 0x3a800000, v102
	v_mul_f32_e32 v118, 0x3a800000, v103
	v_fma_f32 v118, -v240, v240, v118
	v_max_f32_e32 v118, 0, v118
	v_add_f32_e32 v118, 0x3727c5ac, v118
	v_mul_f32_e32 v242, 0x3a800000, v104
	v_mul_f32_e32 v120, 0x3a800000, v105
	v_fma_f32 v120, -v242, v242, v120
	v_max_f32_e32 v120, 0, v120
	v_add_f32_e32 v120, 0x3727c5ac, v120
	v_mul_f32_e32 v244, 0x3a800000, v106
	v_mul_f32_e32 v122, 0x3a800000, v107
	v_fma_f32 v122, -v244, v244, v122
	v_max_f32_e32 v122, 0, v122
	v_add_f32_e32 v122, 0x3727c5ac, v122
	v_rsq_f32_e32 v117, v116
	v_rsq_f32_e32 v119, v118
	v_rsq_f32_e32 v121, v120
	v_rsq_f32_e32 v123, v122
	s_nop 0
	v_mul_f32_e32 v124, v116, v117
	v_mul_f32_e32 v124, v124, v117
	v_fmaak_f32 v124, -0.5, v124, 0x3fc00000
	v_mul_f32_e32 v239, v117, v124
	v_mul_f32_e32 v125, v118, v119
	v_mul_f32_e32 v125, v125, v119
	v_fmaak_f32 v125, -0.5, v125, 0x3fc00000
	v_mul_f32_e32 v241, v119, v125
	v_mul_f32_e32 v126, v120, v121
	v_mul_f32_e32 v126, v126, v121
	v_fmaak_f32 v126, -0.5, v126, 0x3fc00000
	v_mul_f32_e32 v243, v121, v126
	v_mul_f32_e32 v127, v122, v123
	v_mul_f32_e32 v127, v127, v123
	v_fmaak_f32 v127, -0.5, v127, 0x3fc00000
	v_mul_f32_e32 v245, v123, v127
	v_pk_add_f32 v[156:157], v[156:157], v[238:239] op_sel_hi:[1,0] neg_lo:[0,1] neg_hi:[0,1]
	v_pk_add_f32 v[158:159], v[158:159], v[238:239] op_sel_hi:[1,0] neg_lo:[0,1] neg_hi:[0,1]
	v_pk_add_f32 v[160:161], v[160:161], v[238:239] op_sel_hi:[1,0] neg_lo:[0,1] neg_hi:[0,1]
	v_pk_add_f32 v[162:163], v[162:163], v[238:239] op_sel_hi:[1,0] neg_lo:[0,1] neg_hi:[0,1]
	v_pk_add_f32 v[164:165], v[164:165], v[238:239] op_sel_hi:[1,0] neg_lo:[0,1] neg_hi:[0,1]
	v_pk_add_f32 v[166:167], v[166:167], v[238:239] op_sel_hi:[1,0] neg_lo:[0,1] neg_hi:[0,1]
	v_pk_add_f32 v[168:169], v[168:169], v[238:239] op_sel_hi:[1,0] neg_lo:[0,1] neg_hi:[0,1]
	v_pk_add_f32 v[170:171], v[170:171], v[238:239] op_sel_hi:[1,0] neg_lo:[0,1] neg_hi:[0,1]
	v_pk_mul_f32 v[156:157], v[156:157], v[238:239] op_sel:[0,1] op_sel_hi:[1,1]
	v_pk_mul_f32 v[158:159], v[158:159], v[238:239] op_sel:[0,1] op_sel_hi:[1,1]
	v_pk_mul_f32 v[160:161], v[160:161], v[238:239] op_sel:[0,1] op_sel_hi:[1,1]
	v_pk_mul_f32 v[162:163], v[162:163], v[238:239] op_sel:[0,1] op_sel_hi:[1,1]
	v_pk_mul_f32 v[164:165], v[164:165], v[238:239] op_sel:[0,1] op_sel_hi:[1,1]
	v_pk_mul_f32 v[166:167], v[166:167], v[238:239] op_sel:[0,1] op_sel_hi:[1,1]
	v_pk_mul_f32 v[168:169], v[168:169], v[238:239] op_sel:[0,1] op_sel_hi:[1,1]
	v_pk_mul_f32 v[170:171], v[170:171], v[238:239] op_sel:[0,1] op_sel_hi:[1,1]
	v_pk_fma_f32 v[156:157], v[4:5], v[156:157], v[20:21]
	v_pk_fma_f32 v[158:159], v[6:7], v[158:159], v[22:23]
	v_pk_fma_f32 v[160:161], v[8:9], v[160:161], v[24:25]
	v_pk_fma_f32 v[162:163], v[10:11], v[162:163], v[26:27]
	v_pk_fma_f32 v[164:165], v[12:13], v[164:165], v[28:29]
	v_pk_fma_f32 v[166:167], v[14:15], v[166:167], v[30:31]
	v_pk_fma_f32 v[168:169], v[16:17], v[168:169], v[32:33]
	v_pk_fma_f32 v[170:171], v[18:19], v[170:171], v[34:35]
	v_cvt_pk_bf16_f32 v156, v156, v157
	v_cvt_pk_bf16_f32 v157, v158, v159
	v_cvt_pk_bf16_f32 v158, v160, v161
	v_cvt_pk_bf16_f32 v159, v162, v163
	v_cvt_pk_bf16_f32 v164, v164, v165
	v_cvt_pk_bf16_f32 v165, v166, v167
	v_cvt_pk_bf16_f32 v166, v168, v169
	v_cvt_pk_bf16_f32 v167, v170, v171
	v_lshl_add_u32 v3, s40, 11, v2
	global_store_dwordx4 v3, v[156:159], s[96:97] sc1
	global_store_dwordx4 v3, v[164:167], s[96:97] offset:1024 sc1
	v_pk_add_f32 v[172:173], v[172:173], v[240:241] op_sel_hi:[1,0] neg_lo:[0,1] neg_hi:[0,1]
	v_pk_add_f32 v[174:175], v[174:175], v[240:241] op_sel_hi:[1,0] neg_lo:[0,1] neg_hi:[0,1]
	v_pk_add_f32 v[176:177], v[176:177], v[240:241] op_sel_hi:[1,0] neg_lo:[0,1] neg_hi:[0,1]
	v_pk_add_f32 v[178:179], v[178:179], v[240:241] op_sel_hi:[1,0] neg_lo:[0,1] neg_hi:[0,1]
	v_pk_add_f32 v[180:181], v[180:181], v[240:241] op_sel_hi:[1,0] neg_lo:[0,1] neg_hi:[0,1]
	v_pk_add_f32 v[182:183], v[182:183], v[240:241] op_sel_hi:[1,0] neg_lo:[0,1] neg_hi:[0,1]
	v_pk_add_f32 v[184:185], v[184:185], v[240:241] op_sel_hi:[1,0] neg_lo:[0,1] neg_hi:[0,1]
	v_pk_add_f32 v[186:187], v[186:187], v[240:241] op_sel_hi:[1,0] neg_lo:[0,1] neg_hi:[0,1]
	v_pk_mul_f32 v[172:173], v[172:173], v[240:241] op_sel:[0,1] op_sel_hi:[1,1]
	v_pk_mul_f32 v[174:175], v[174:175], v[240:241] op_sel:[0,1] op_sel_hi:[1,1]
	v_pk_mul_f32 v[176:177], v[176:177], v[240:241] op_sel:[0,1] op_sel_hi:[1,1]
	v_pk_mul_f32 v[178:179], v[178:179], v[240:241] op_sel:[0,1] op_sel_hi:[1,1]
	v_pk_mul_f32 v[180:181], v[180:181], v[240:241] op_sel:[0,1] op_sel_hi:[1,1]
	v_pk_mul_f32 v[182:183], v[182:183], v[240:241] op_sel:[0,1] op_sel_hi:[1,1]
	v_pk_mul_f32 v[184:185], v[184:185], v[240:241] op_sel:[0,1] op_sel_hi:[1,1]
	v_pk_mul_f32 v[186:187], v[186:187], v[240:241] op_sel:[0,1] op_sel_hi:[1,1]
	v_pk_fma_f32 v[172:173], v[4:5], v[172:173], v[20:21]
	v_pk_fma_f32 v[174:175], v[6:7], v[174:175], v[22:23]
	v_pk_fma_f32 v[176:177], v[8:9], v[176:177], v[24:25]
	v_pk_fma_f32 v[178:179], v[10:11], v[178:179], v[26:27]
	v_pk_fma_f32 v[180:181], v[12:13], v[180:181], v[28:29]
	v_pk_fma_f32 v[182:183], v[14:15], v[182:183], v[30:31]
	v_pk_fma_f32 v[184:185], v[16:17], v[184:185], v[32:33]
	v_pk_fma_f32 v[186:187], v[18:19], v[186:187], v[34:35]
	v_cvt_pk_bf16_f32 v172, v172, v173
	v_cvt_pk_bf16_f32 v173, v174, v175
	v_cvt_pk_bf16_f32 v174, v176, v177
	v_cvt_pk_bf16_f32 v175, v178, v179
	v_cvt_pk_bf16_f32 v180, v180, v181
	v_cvt_pk_bf16_f32 v181, v182, v183
	v_cvt_pk_bf16_f32 v182, v184, v185
	v_cvt_pk_bf16_f32 v183, v186, v187
	v_lshl_add_u32 v3, s41, 11, v2
	global_store_dwordx4 v3, v[172:175], s[96:97] sc1
	global_store_dwordx4 v3, v[180:183], s[96:97] offset:1024 sc1
	v_pk_add_f32 v[188:189], v[188:189], v[242:243] op_sel_hi:[1,0] neg_lo:[0,1] neg_hi:[0,1]
	v_pk_add_f32 v[190:191], v[190:191], v[242:243] op_sel_hi:[1,0] neg_lo:[0,1] neg_hi:[0,1]
	v_pk_add_f32 v[192:193], v[192:193], v[242:243] op_sel_hi:[1,0] neg_lo:[0,1] neg_hi:[0,1]
	v_pk_add_f32 v[194:195], v[194:195], v[242:243] op_sel_hi:[1,0] neg_lo:[0,1] neg_hi:[0,1]
	v_pk_add_f32 v[196:197], v[196:197], v[242:243] op_sel_hi:[1,0] neg_lo:[0,1] neg_hi:[0,1]
	v_pk_add_f32 v[198:199], v[198:199], v[242:243] op_sel_hi:[1,0] neg_lo:[0,1] neg_hi:[0,1]
	v_pk_add_f32 v[200:201], v[200:201], v[242:243] op_sel_hi:[1,0] neg_lo:[0,1] neg_hi:[0,1]
	v_pk_add_f32 v[202:203], v[202:203], v[242:243] op_sel_hi:[1,0] neg_lo:[0,1] neg_hi:[0,1]
	v_pk_mul_f32 v[188:189], v[188:189], v[242:243] op_sel:[0,1] op_sel_hi:[1,1]
	v_pk_mul_f32 v[190:191], v[190:191], v[242:243] op_sel:[0,1] op_sel_hi:[1,1]
	v_pk_mul_f32 v[192:193], v[192:193], v[242:243] op_sel:[0,1] op_sel_hi:[1,1]
	v_pk_mul_f32 v[194:195], v[194:195], v[242:243] op_sel:[0,1] op_sel_hi:[1,1]
	v_pk_mul_f32 v[196:197], v[196:197], v[242:243] op_sel:[0,1] op_sel_hi:[1,1]
	v_pk_mul_f32 v[198:199], v[198:199], v[242:243] op_sel:[0,1] op_sel_hi:[1,1]
	v_pk_mul_f32 v[200:201], v[200:201], v[242:243] op_sel:[0,1] op_sel_hi:[1,1]
	v_pk_mul_f32 v[202:203], v[202:203], v[242:243] op_sel:[0,1] op_sel_hi:[1,1]
	v_pk_fma_f32 v[188:189], v[4:5], v[188:189], v[20:21]
	v_pk_fma_f32 v[190:191], v[6:7], v[190:191], v[22:23]
	v_pk_fma_f32 v[192:193], v[8:9], v[192:193], v[24:25]
	v_pk_fma_f32 v[194:195], v[10:11], v[194:195], v[26:27]
	v_pk_fma_f32 v[196:197], v[12:13], v[196:197], v[28:29]
	v_pk_fma_f32 v[198:199], v[14:15], v[198:199], v[30:31]
	v_pk_fma_f32 v[200:201], v[16:17], v[200:201], v[32:33]
	v_pk_fma_f32 v[202:203], v[18:19], v[202:203], v[34:35]
	v_cvt_pk_bf16_f32 v188, v188, v189
	v_cvt_pk_bf16_f32 v189, v190, v191
	v_cvt_pk_bf16_f32 v190, v192, v193
	v_cvt_pk_bf16_f32 v191, v194, v195
	v_cvt_pk_bf16_f32 v196, v196, v197
	v_cvt_pk_bf16_f32 v197, v198, v199
	v_cvt_pk_bf16_f32 v198, v200, v201
	v_cvt_pk_bf16_f32 v199, v202, v203
	v_lshl_add_u32 v3, s42, 11, v2
	global_store_dwordx4 v3, v[188:191], s[96:97] sc1
	global_store_dwordx4 v3, v[196:199], s[96:97] offset:1024 sc1
	v_pk_add_f32 v[204:205], v[204:205], v[244:245] op_sel_hi:[1,0] neg_lo:[0,1] neg_hi:[0,1]
	v_pk_add_f32 v[206:207], v[206:207], v[244:245] op_sel_hi:[1,0] neg_lo:[0,1] neg_hi:[0,1]
	v_pk_add_f32 v[208:209], v[208:209], v[244:245] op_sel_hi:[1,0] neg_lo:[0,1] neg_hi:[0,1]
	v_pk_add_f32 v[210:211], v[210:211], v[244:245] op_sel_hi:[1,0] neg_lo:[0,1] neg_hi:[0,1]
	v_pk_add_f32 v[212:213], v[212:213], v[244:245] op_sel_hi:[1,0] neg_lo:[0,1] neg_hi:[0,1]
	v_pk_add_f32 v[214:215], v[214:215], v[244:245] op_sel_hi:[1,0] neg_lo:[0,1] neg_hi:[0,1]
	v_pk_add_f32 v[216:217], v[216:217], v[244:245] op_sel_hi:[1,0] neg_lo:[0,1] neg_hi:[0,1]
	v_pk_add_f32 v[218:219], v[218:219], v[244:245] op_sel_hi:[1,0] neg_lo:[0,1] neg_hi:[0,1]
	v_pk_mul_f32 v[204:205], v[204:205], v[244:245] op_sel:[0,1] op_sel_hi:[1,1]
	v_pk_mul_f32 v[206:207], v[206:207], v[244:245] op_sel:[0,1] op_sel_hi:[1,1]
	v_pk_mul_f32 v[208:209], v[208:209], v[244:245] op_sel:[0,1] op_sel_hi:[1,1]
	v_pk_mul_f32 v[210:211], v[210:211], v[244:245] op_sel:[0,1] op_sel_hi:[1,1]
	v_pk_mul_f32 v[212:213], v[212:213], v[244:245] op_sel:[0,1] op_sel_hi:[1,1]
	v_pk_mul_f32 v[214:215], v[214:215], v[244:245] op_sel:[0,1] op_sel_hi:[1,1]
	v_pk_mul_f32 v[216:217], v[216:217], v[244:245] op_sel:[0,1] op_sel_hi:[1,1]
	v_pk_mul_f32 v[218:219], v[218:219], v[244:245] op_sel:[0,1] op_sel_hi:[1,1]
	v_pk_fma_f32 v[204:205], v[4:5], v[204:205], v[20:21]
	v_pk_fma_f32 v[206:207], v[6:7], v[206:207], v[22:23]
	v_pk_fma_f32 v[208:209], v[8:9], v[208:209], v[24:25]
	v_pk_fma_f32 v[210:211], v[10:11], v[210:211], v[26:27]
	v_pk_fma_f32 v[212:213], v[12:13], v[212:213], v[28:29]
	v_pk_fma_f32 v[214:215], v[14:15], v[214:215], v[30:31]
	v_pk_fma_f32 v[216:217], v[16:17], v[216:217], v[32:33]
	v_pk_fma_f32 v[218:219], v[18:19], v[218:219], v[34:35]
	v_cvt_pk_bf16_f32 v204, v204, v205
	v_cvt_pk_bf16_f32 v205, v206, v207
	v_cvt_pk_bf16_f32 v206, v208, v209
	v_cvt_pk_bf16_f32 v207, v210, v211
	v_cvt_pk_bf16_f32 v212, v212, v213
	v_cvt_pk_bf16_f32 v213, v214, v215
	v_cvt_pk_bf16_f32 v214, v216, v217
	v_cvt_pk_bf16_f32 v215, v218, v219
	v_lshl_add_u32 v3, s43, 11, v2
	global_store_dwordx4 v3, v[204:207], s[96:97] sc1
	global_store_dwordx4 v3, v[212:215], s[96:97] offset:1024 sc1
	s_mov_b64 s[52:53], exec
	s_mov_b64 exec, 1
	v_mov_b32_e32 v3, s40
	v_lshlrev_b32_e32 v3, 3, v3
	global_store_dwordx2 v3, v[238:239], s[92:93] sc1
	v_mov_b32_e32 v3, s41
	v_lshlrev_b32_e32 v3, 3, v3
	global_store_dwordx2 v3, v[240:241], s[92:93] sc1
	v_mov_b32_e32 v3, s42
	v_lshlrev_b32_e32 v3, 3, v3
	global_store_dwordx2 v3, v[242:243], s[92:93] sc1
	v_mov_b32_e32 v3, s43
	v_lshlrev_b32_e32 v3, 3, v3
	global_store_dwordx2 v3, v[244:245], s[92:93] sc1
	s_mov_b64 exec, s[52:53]
	s_cmp_gt_u32 s46, 15
	s_cbranch_scc1 .Lln1_done
	v_lshl_add_u32 v128, s46, 12, v1
	global_load_dwordx4 v[36:39], v128, s[30:31]
	global_load_dwordx4 v[40:43], v128, s[30:31] offset:16
	global_load_dwordx4 v[44:47], v128, s[30:31] offset:2048
	global_load_dwordx4 v[48:51], v128, s[30:31] offset:2064
	s_add_u32 s36, s46, 0x8000
	s_waitcnt vmcnt(0)
	v_pk_add_f32 v[108:109], v[36:37], v[38:39]
	v_pk_add_f32 v[110:111], v[40:41], v[42:43]
	v_pk_add_f32 v[112:113], v[44:45], v[46:47]
	v_pk_add_f32 v[114:115], v[48:49], v[50:51]
	v_pk_mul_f32 v[116:117], v[36:37], v[36:37]
	v_pk_fma_f32 v[116:117], v[38:39], v[38:39], v[116:117]
	v_pk_fma_f32 v[116:117], v[40:41], v[40:41], v[116:117]
	v_pk_fma_f32 v[116:117], v[42:43], v[42:43], v[116:117]
	v_pk_fma_f32 v[116:117], v[44:45], v[44:45], v[116:117]
	v_pk_fma_f32 v[116:117], v[46:47], v[46:47], v[116:117]
	v_pk_fma_f32 v[116:117], v[48:49], v[48:49], v[116:117]
	v_pk_fma_f32 v[116:117], v[50:51], v[50:51], v[116:117]
	v_pk_add_f32 v[108:109], v[108:109], v[110:111]
	v_pk_add_f32 v[112:113], v[112:113], v[114:115]
	v_pk_add_f32 v[108:109], v[108:109], v[112:113]
	v_add_f32_e32 v100, v108, v109
	v_add_f32_e32 v101, v116, v117
	s_nop 1
	v_add_f32_dpp v100, v100, v100 quad_perm:[1,0,3,2] row_mask:0xf bank_mask:0xf
	v_add_f32_dpp v101, v101, v101 quad_perm:[1,0,3,2] row_mask:0xf bank_mask:0xf
	s_nop 1
	v_add_f32_dpp v100, v100, v100 quad_perm:[2,3,0,1] row_mask:0xf bank_mask:0xf
	v_add_f32_dpp v101, v101, v101 quad_perm:[2,3,0,1] row_mask:0xf bank_mask:0xf
	s_nop 1
	v_add_f32_dpp v100, v100, v100 row_half_mirror row_mask:0xf bank_mask:0xf
	v_add_f32_dpp v101, v101, v101 row_half_mirror row_mask:0xf bank_mask:0xf
	s_nop 1
	v_add_f32_dpp v100, v100, v100 row_mirror row_mask:0xf bank_mask:0xf
	v_add_f32_dpp v101, v101, v101 row_mirror row_mask:0xf bank_mask:0xf
	s_nop 1
	v_mov_b32_e32 v108, v100
	v_mov_b32_e32 v109, v101
	s_nop 1
	v_permlane16_swap_b32_e32 v108, v100
	v_permlane16_swap_b32_e32 v109, v101
	v_add_f32_e32 v100, v100, v108
	v_add_f32_e32 v101, v101, v109
	v_mov_b32_e32 v108, v100
	v_mov_b32_e32 v109, v101
	s_nop 1
	v_permlane32_swap_b32_e32 v108, v100
	v_permlane32_swap_b32_e32 v109, v101
	v_add_f32_e32 v100, v100, v108
	v_add_f32_e32 v101, v101, v109
	v_mul_f32_e32 v230, 0x3a800000, v100
	v_mul_f32_e32 v116, 0x3a800000, v101
	v_fma_f32 v116, -v230, v230, v116
	v_max_f32_e32 v116, 0, v116
	v_add_f32_e32 v116, 0x3727c5ac, v116
	v_rsq_f32_e32 v117, v116
	s_nop 0
	v_mul_f32_e32 v124, v116, v117
	v_mul_f32_e32 v124, v124, v117
	v_fmaak_f32 v124, -0.5, v124, 0x3fc00000
	v_mul_f32_e32 v231, v117, v124
	v_pk_add_f32 v[36:37], v[36:37], v[230:231] op_sel_hi:[1,0] neg_lo:[0,1] neg_hi:[0,1]
	v_pk_add_f32 v[38:39], v[38:39], v[230:231] op_sel_hi:[1,0] neg_lo:[0,1] neg_hi:[0,1]
	v_pk_add_f32 v[40:41], v[40:41], v[230:231] op_sel_hi:[1,0] neg_lo:[0,1] neg_hi:[0,1]
	v_pk_add_f32 v[42:43], v[42:43], v[230:231] op_sel_hi:[1,0] neg_lo:[0,1] neg_hi:[0,1]
	v_pk_add_f32 v[44:45], v[44:45], v[230:231] op_sel_hi:[1,0] neg_lo:[0,1] neg_hi:[0,1]
	v_pk_add_f32 v[46:47], v[46:47], v[230:231] op_sel_hi:[1,0] neg_lo:[0,1] neg_hi:[0,1]
	v_pk_add_f32 v[48:49], v[48:49], v[230:231] op_sel_hi:[1,0] neg_lo:[0,1] neg_hi:[0,1]
	v_pk_add_f32 v[50:51], v[50:51], v[230:231] op_sel_hi:[1,0] neg_lo:[0,1] neg_hi:[0,1]
	v_pk_mul_f32 v[36:37], v[36:37], v[230:231] op_sel:[0,1] op_sel_hi:[1,1]
	v_pk_mul_f32 v[38:39], v[38:39], v[230:231] op_sel:[0,1] op_sel_hi:[1,1]
	v_pk_mul_f32 v[40:41], v[40:41], v[230:231] op_sel:[0,1] op_sel_hi:[1,1]
	v_pk_mul_f32 v[42:43], v[42:43], v[230:231] op_sel:[0,1] op_sel_hi:[1,1]
	v_pk_mul_f32 v[44:45], v[44:45], v[230:231] op_sel:[0,1] op_sel_hi:[1,1]
	v_pk_mul_f32 v[46:47], v[46:47], v[230:231] op_sel:[0,1] op_sel_hi:[1,1]
	v_pk_mul_f32 v[48:49], v[48:49], v[230:231] op_sel:[0,1] op_sel_hi:[1,1]
	v_pk_mul_f32 v[50:51], v[50:51], v[230:231] op_sel:[0,1] op_sel_hi:[1,1]
	v_pk_fma_f32 v[36:37], v[4:5], v[36:37], v[20:21]
	v_pk_fma_f32 v[38:39], v[6:7], v[38:39], v[22:23]
	v_pk_fma_f32 v[40:41], v[8:9], v[40:41], v[24:25]
	v_pk_fma_f32 v[42:43], v[10:11], v[42:43], v[26:27]
	v_pk_fma_f32 v[44:45], v[12:13], v[44:45], v[28:29]
	v_pk_fma_f32 v[46:47], v[14:15], v[46:47], v[30:31]
	v_pk_fma_f32 v[48:49], v[16:17], v[48:49], v[32:33]
	v_pk_fma_f32 v[50:51], v[18:19], v[50:51], v[34:35]
	v_cvt_pk_bf16_f32 v36, v36, v37
	v_cvt_pk_bf16_f32 v37, v38, v39
	v_cvt_pk_bf16_f32 v38, v40, v41
	v_cvt_pk_bf16_f32 v39, v42, v43
	v_cvt_pk_bf16_f32 v44, v44, v45
	v_cvt_pk_bf16_f32 v45, v46, v47
	v_cvt_pk_bf16_f32 v46, v48, v49
	v_cvt_pk_bf16_f32 v47, v50, v51
	v_lshl_add_u32 v3, s36, 11, v2
	global_store_dwordx4 v3, v[36:39], s[96:97] sc1
	global_store_dwordx4 v3, v[44:47], s[96:97] offset:1024 sc1
	s_mov_b64 s[52:53], exec
	s_mov_b64 exec, 1
	v_mov_b32_e32 v3, s36
	v_lshlrev_b32_e32 v3, 3, v3
	global_store_dwordx2 v3, v[230:231], s[92:93] sc1
	s_mov_b64 exec, s[52:53]
.Lln1_done:
	s_branch .LBB0_399
	v_mov_b32_e32 v0, v222
	s_nop 0
	v_readfirstlane_b32 s2, v0
	s_ashr_i32 s2, s2, 6
	s_add_i32 s56, s2, s95
	s_cmp_lt_i32 s56, 0x8010
	s_cbranch_scc0 .LBB0_399
	v_readlane_b32 s4, v252, 18
	s_ashr_i32 s43, s42, 31
	v_readlane_b32 s10, v252, 24
	v_readlane_b32 s11, v252, 25
	s_lshl_b64 s[28:29], s[42:43], 2
	v_readlane_b32 s8, v252, 22
	v_readlane_b32 s9, v252, 23
	s_mov_b64 s[42:43], s[10:11]
	s_mov_b64 s[40:41], s[8:9]
	s_add_u32 s36, s40, s28
	s_addc_u32 s37, s41, s29
	v_and_b32_e32 v96, 63, v0
	s_add_u32 s28, s42, s28
	v_lshlrev_b32_e32 v28, 4, v96
	s_addc_u32 s29, s43, s29
	global_load_dwordx4 v[0:3], v28, s[36:37]
	global_load_dwordx4 v[4:7], v28, s[36:37] offset:1024
	global_load_dwordx4 v[8:11], v28, s[28:29]
	global_load_dwordx4 v[12:15], v28, s[28:29] offset:1024
	global_load_dwordx4 v[16:19], v28, s[36:37] offset:2048
	global_load_dwordx4 v[20:23], v28, s[36:37] offset:3072
	global_load_dwordx4 v[24:27], v28, s[28:29] offset:2048
	s_nop 0
	global_load_dwordx4 v[28:31], v28, s[28:29] offset:3072
	v_and_b32_e32 v32, 64, v227
	v_add_u32_e32 v32, 64, v32
	v_xor_b32_e32 v33, 1, v227
	v_cmp_lt_i32_e32 vcc, v33, v32
	v_lshlrev_b32_e32 v142, 3, v96
	v_cmp_eq_u32_e64 s[38:39], 0, v96
	v_cndmask_b32_e32 v33, v227, v33, vcc
	v_lshlrev_b32_e32 v97, 2, v33
	v_xor_b32_e32 v33, 2, v227
	v_cmp_lt_i32_e32 vcc, v33, v32
	v_lshl_add_u64 v[98:99], s[96:97], 0, v[142:143]
	v_readlane_b32 s5, v252, 19
	v_cndmask_b32_e32 v33, v227, v33, vcc
	v_lshlrev_b32_e32 v114, 2, v33
	v_xor_b32_e32 v33, 4, v227
	v_cmp_lt_i32_e32 vcc, v33, v32
	v_readlane_b32 s6, v252, 20
	v_readlane_b32 s7, v252, 21
	v_cndmask_b32_e32 v33, v227, v33, vcc
	v_lshlrev_b32_e32 v115, 2, v33
	v_xor_b32_e32 v33, 8, v227
	v_cmp_lt_i32_e32 vcc, v33, v32
	v_readlane_b32 s12, v252, 26
	v_readlane_b32 s13, v252, 27
	v_cndmask_b32_e32 v33, v227, v33, vcc
	v_lshlrev_b32_e32 v116, 2, v33
	v_xor_b32_e32 v33, 16, v227
	v_cmp_lt_i32_e32 vcc, v33, v32
	v_readlane_b32 s14, v252, 28
	v_readlane_b32 s15, v252, 29
	v_cndmask_b32_e32 v33, v227, v33, vcc
	v_lshlrev_b32_e32 v117, 2, v33
	v_xor_b32_e32 v33, 32, v227
	v_cmp_lt_i32_e32 vcc, v33, v32
	v_readlane_b32 s16, v252, 30
	v_readlane_b32 s17, v252, 31
	v_cndmask_b32_e32 v32, v227, v33, vcc
	v_lshlrev_b32_e32 v118, 2, v32
	v_readlane_b32 s18, v252, 32
	v_readlane_b32 s19, v252, 33
	s_branch .LBB0_364

.LBB0_1142:
	s_or_b64 exec, exec, s[36:37]
	s_waitcnt lgkmcnt(0)
	v_mov_b32_e32 v0, v222
	s_barrier
	v_and_b32_e32 v0, 63, v222
	v_readfirstlane_b32 s46, v222
	v_lshlrev_b32_e32 v1, 5, v0
	v_lshlrev_b32_e32 v2, 4, v0
	s_lshl_b32 s2, s38, 2
	v_readlane_b32 s48, v252, 22
	v_readlane_b32 s49, v252, 23
	v_readlane_b32 s50, v252, 24
	v_readlane_b32 s51, v252, 25
	s_nop 3
	s_lshr_b32 s46, s46, 6
	s_add_u32 s46, s46, s95
	s_add_u32 s48, s48, s2
	s_addc_u32 s49, s49, 0
	s_add_u32 s50, s50, s2
	s_addc_u32 s51, s51, 0
	global_load_dwordx4 v[4:7], v1, s[48:49]
	global_load_dwordx4 v[20:23], v1, s[50:51]
	global_load_dwordx4 v[8:11], v1, s[48:49] offset:16
	global_load_dwordx4 v[24:27], v1, s[50:51] offset:16
	global_load_dwordx4 v[12:15], v1, s[48:49] offset:2048
	global_load_dwordx4 v[28:31], v1, s[50:51] offset:2048
	global_load_dwordx4 v[16:19], v1, s[48:49] offset:2064
	global_load_dwordx4 v[32:35], v1, s[50:51] offset:2064
	s_add_u32 s36, s46, 0x0
	v_lshl_add_u32 v128, s36, 12, v1
	s_add_u32 s37, s46, 0x1000
	v_lshl_add_u32 v129, s37, 12, v1
	s_add_u32 s38, s46, 0x2000
	v_lshl_add_u32 v130, s38, 12, v1
	s_add_u32 s39, s46, 0x3000
	v_lshl_add_u32 v131, s39, 12, v1
	global_load_dwordx4 v[36:39], v128, s[64:65]
	global_load_dwordx4 v[40:43], v128, s[64:65] offset:16
	global_load_dwordx4 v[44:47], v128, s[64:65] offset:2048
	global_load_dwordx4 v[48:51], v128, s[64:65] offset:2064
	global_load_dwordx4 v[52:55], v129, s[64:65]
	global_load_dwordx4 v[56:59], v129, s[64:65] offset:16
	global_load_dwordx4 v[60:63], v129, s[64:65] offset:2048
	global_load_dwordx4 v[64:67], v129, s[64:65] offset:2064
	global_load_dwordx4 v[68:71], v130, s[64:65]
	global_load_dwordx4 v[72:75], v130, s[64:65] offset:16
	global_load_dwordx4 v[76:79], v130, s[64:65] offset:2048
	global_load_dwordx4 v[80:83], v130, s[64:65] offset:2064
	global_load_dwordx4 v[84:87], v131, s[64:65]
	global_load_dwordx4 v[88:91], v131, s[64:65] offset:16
	global_load_dwordx4 v[92:95], v131, s[64:65] offset:2048
	global_load_dwordx4 v[96:99], v131, s[64:65] offset:2064
	s_add_u32 s40, s46, 0x4000
	v_lshl_add_u32 v132, s40, 12, v1
	s_add_u32 s41, s46, 0x5000
	v_lshl_add_u32 v133, s41, 12, v1
	s_add_u32 s42, s46, 0x6000
	v_lshl_add_u32 v134, s42, 12, v1
	s_add_u32 s43, s46, 0x7000
	v_lshl_add_u32 v135, s43, 12, v1
	global_load_dwordx4 v[156:159], v132, s[64:65]
	global_load_dwordx4 v[160:163], v132, s[64:65] offset:16
	global_load_dwordx4 v[164:167], v132, s[64:65] offset:2048
	global_load_dwordx4 v[168:171], v132, s[64:65] offset:2064
	global_load_dwordx4 v[172:175], v133, s[64:65]
	global_load_dwordx4 v[176:179], v133, s[64:65] offset:16
	global_load_dwordx4 v[180:183], v133, s[64:65] offset:2048
	global_load_dwordx4 v[184:187], v133, s[64:65] offset:2064
	global_load_dwordx4 v[188:191], v134, s[64:65]
	global_load_dwordx4 v[192:195], v134, s[64:65] offset:16
	global_load_dwordx4 v[196:199], v134, s[64:65] offset:2048
	global_load_dwordx4 v[200:203], v134, s[64:65] offset:2064
	global_load_dwordx4 v[204:207], v135, s[64:65]
	global_load_dwordx4 v[208:211], v135, s[64:65] offset:16
	global_load_dwordx4 v[212:215], v135, s[64:65] offset:2048
	global_load_dwordx4 v[216:219], v135, s[64:65] offset:2064
	s_waitcnt vmcnt(16)
	v_pk_add_f32 v[108:109], v[36:37], v[38:39]
	v_pk_add_f32 v[110:111], v[40:41], v[42:43]
	v_pk_add_f32 v[112:113], v[44:45], v[46:47]
	v_pk_add_f32 v[114:115], v[48:49], v[50:51]
	v_pk_mul_f32 v[116:117], v[36:37], v[36:37]
	v_pk_fma_f32 v[116:117], v[38:39], v[38:39], v[116:117]
	v_pk_fma_f32 v[116:117], v[40:41], v[40:41], v[116:117]
	v_pk_fma_f32 v[116:117], v[42:43], v[42:43], v[116:117]
	v_pk_fma_f32 v[116:117], v[44:45], v[44:45], v[116:117]
	v_pk_fma_f32 v[116:117], v[46:47], v[46:47], v[116:117]
	v_pk_fma_f32 v[116:117], v[48:49], v[48:49], v[116:117]
	v_pk_fma_f32 v[116:117], v[50:51], v[50:51], v[116:117]
	v_pk_add_f32 v[108:109], v[108:109], v[110:111]
	v_pk_add_f32 v[112:113], v[112:113], v[114:115]
	v_pk_add_f32 v[108:109], v[108:109], v[112:113]
	v_add_f32_e32 v100, v108, v109
	v_add_f32_e32 v101, v116, v117
	v_pk_add_f32 v[108:109], v[52:53], v[54:55]
	v_pk_add_f32 v[110:111], v[56:57], v[58:59]
	v_pk_add_f32 v[112:113], v[60:61], v[62:63]
	v_pk_add_f32 v[114:115], v[64:65], v[66:67]
	v_pk_mul_f32 v[116:117], v[52:53], v[52:53]
	v_pk_fma_f32 v[116:117], v[54:55], v[54:55], v[116:117]
	v_pk_fma_f32 v[116:117], v[56:57], v[56:57], v[116:117]
	v_pk_fma_f32 v[116:117], v[58:59], v[58:59], v[116:117]
	v_pk_fma_f32 v[116:117], v[60:61], v[60:61], v[116:117]
	v_pk_fma_f32 v[116:117], v[62:63], v[62:63], v[116:117]
	v_pk_fma_f32 v[116:117], v[64:65], v[64:65], v[116:117]
	v_pk_fma_f32 v[116:117], v[66:67], v[66:67], v[116:117]
	v_pk_add_f32 v[108:109], v[108:109], v[110:111]
	v_pk_add_f32 v[112:113], v[112:113], v[114:115]
	v_pk_add_f32 v[108:109], v[108:109], v[112:113]
	v_add_f32_e32 v102, v108, v109
	v_add_f32_e32 v103, v116, v117
	v_pk_add_f32 v[108:109], v[68:69], v[70:71]
	v_pk_add_f32 v[110:111], v[72:73], v[74:75]
	v_pk_add_f32 v[112:113], v[76:77], v[78:79]
	v_pk_add_f32 v[114:115], v[80:81], v[82:83]
	v_pk_mul_f32 v[116:117], v[68:69], v[68:69]
	v_pk_fma_f32 v[116:117], v[70:71], v[70:71], v[116:117]
	v_pk_fma_f32 v[116:117], v[72:73], v[72:73], v[116:117]
	v_pk_fma_f32 v[116:117], v[74:75], v[74:75], v[116:117]
	v_pk_fma_f32 v[116:117], v[76:77], v[76:77], v[116:117]
	v_pk_fma_f32 v[116:117], v[78:79], v[78:79], v[116:117]
	v_pk_fma_f32 v[116:117], v[80:81], v[80:81], v[116:117]
	v_pk_fma_f32 v[116:117], v[82:83], v[82:83], v[116:117]
	v_pk_add_f32 v[108:109], v[108:109], v[110:111]
	v_pk_add_f32 v[112:113], v[112:113], v[114:115]
	v_pk_add_f32 v[108:109], v[108:109], v[112:113]
	v_add_f32_e32 v104, v108, v109
	v_add_f32_e32 v105, v116, v117
	v_pk_add_f32 v[108:109], v[84:85], v[86:87]
	v_pk_add_f32 v[110:111], v[88:89], v[90:91]
	v_pk_add_f32 v[112:113], v[92:93], v[94:95]
	v_pk_add_f32 v[114:115], v[96:97], v[98:99]
	v_pk_mul_f32 v[116:117], v[84:85], v[84:85]
	v_pk_fma_f32 v[116:117], v[86:87], v[86:87], v[116:117]
	v_pk_fma_f32 v[116:117], v[88:89], v[88:89], v[116:117]
	v_pk_fma_f32 v[116:117], v[90:91], v[90:91], v[116:117]
	v_pk_fma_f32 v[116:117], v[92:93], v[92:93], v[116:117]
	v_pk_fma_f32 v[116:117], v[94:95], v[94:95], v[116:117]
	v_pk_fma_f32 v[116:117], v[96:97], v[96:97], v[116:117]
	v_pk_fma_f32 v[116:117], v[98:99], v[98:99], v[116:117]
	v_pk_add_f32 v[108:109], v[108:109], v[110:111]
	v_pk_add_f32 v[112:113], v[112:113], v[114:115]
	v_pk_add_f32 v[108:109], v[108:109], v[112:113]
	v_add_f32_e32 v106, v108, v109
	v_add_f32_e32 v107, v116, v117
	v_add_f32_dpp v100, v100, v100 quad_perm:[1,0,3,2] row_mask:0xf bank_mask:0xf
	v_add_f32_dpp v101, v101, v101 quad_perm:[1,0,3,2] row_mask:0xf bank_mask:0xf
	v_add_f32_dpp v102, v102, v102 quad_perm:[1,0,3,2] row_mask:0xf bank_mask:0xf
	v_add_f32_dpp v103, v103, v103 quad_perm:[1,0,3,2] row_mask:0xf bank_mask:0xf
	v_add_f32_dpp v104, v104, v104 quad_perm:[1,0,3,2] row_mask:0xf bank_mask:0xf
	v_add_f32_dpp v105, v105, v105 quad_perm:[1,0,3,2] row_mask:0xf bank_mask:0xf
	v_add_f32_dpp v106, v106, v106 quad_perm:[1,0,3,2] row_mask:0xf bank_mask:0xf
	v_add_f32_dpp v107, v107, v107 quad_perm:[1,0,3,2] row_mask:0xf bank_mask:0xf
	v_add_f32_dpp v100, v100, v100 quad_perm:[2,3,0,1] row_mask:0xf bank_mask:0xf
	v_add_f32_dpp v101, v101, v101 quad_perm:[2,3,0,1] row_mask:0xf bank_mask:0xf
	v_add_f32_dpp v102, v102, v102 quad_perm:[2,3,0,1] row_mask:0xf bank_mask:0xf
	v_add_f32_dpp v103, v103, v103 quad_perm:[2,3,0,1] row_mask:0xf bank_mask:0xf
	v_add_f32_dpp v104, v104, v104 quad_perm:[2,3,0,1] row_mask:0xf bank_mask:0xf
	v_add_f32_dpp v105, v105, v105 quad_perm:[2,3,0,1] row_mask:0xf bank_mask:0xf
	v_add_f32_dpp v106, v106, v106 quad_perm:[2,3,0,1] row_mask:0xf bank_mask:0xf
	v_add_f32_dpp v107, v107, v107 quad_perm:[2,3,0,1] row_mask:0xf bank_mask:0xf
	v_add_f32_dpp v100, v100, v100 row_half_mirror row_mask:0xf bank_mask:0xf
	v_add_f32_dpp v101, v101, v101 row_half_mirror row_mask:0xf bank_mask:0xf
	v_add_f32_dpp v102, v102, v102 row_half_mirror row_mask:0xf bank_mask:0xf
	v_add_f32_dpp v103, v103, v103 row_half_mirror row_mask:0xf bank_mask:0xf
	v_add_f32_dpp v104, v104, v104 row_half_mirror row_mask:0xf bank_mask:0xf
	v_add_f32_dpp v105, v105, v105 row_half_mirror row_mask:0xf bank_mask:0xf
	v_add_f32_dpp v106, v106, v106 row_half_mirror row_mask:0xf bank_mask:0xf
	v_add_f32_dpp v107, v107, v107 row_half_mirror row_mask:0xf bank_mask:0xf
	v_add_f32_dpp v100, v100, v100 row_mirror row_mask:0xf bank_mask:0xf
	v_add_f32_dpp v101, v101, v101 row_mirror row_mask:0xf bank_mask:0xf
	v_add_f32_dpp v102, v102, v102 row_mirror row_mask:0xf bank_mask:0xf
	v_add_f32_dpp v103, v103, v103 row_mirror row_mask:0xf bank_mask:0xf
	v_add_f32_dpp v104, v104, v104 row_mirror row_mask:0xf bank_mask:0xf
	v_add_f32_dpp v105, v105, v105 row_mirror row_mask:0xf bank_mask:0xf
	v_add_f32_dpp v106, v106, v106 row_mirror row_mask:0xf bank_mask:0xf
	v_add_f32_dpp v107, v107, v107 row_mirror row_mask:0xf bank_mask:0xf
	v_mov_b32_e32 v108, v100
	v_mov_b32_e32 v109, v101
	v_mov_b32_e32 v110, v102
	v_mov_b32_e32 v111, v103
	v_mov_b32_e32 v112, v104
	v_mov_b32_e32 v113, v105
	v_mov_b32_e32 v114, v106
	v_mov_b32_e32 v115, v107
	s_nop 1
	v_permlane16_swap_b32_e32 v108, v100
	v_permlane16_swap_b32_e32 v109, v101
	v_permlane16_swap_b32_e32 v110, v102
	v_permlane16_swap_b32_e32 v111, v103
	v_permlane16_swap_b32_e32 v112, v104
	v_permlane16_swap_b32_e32 v113, v105
	v_permlane16_swap_b32_e32 v114, v106
	v_permlane16_swap_b32_e32 v115, v107
	v_add_f32_e32 v100, v100, v108
	v_add_f32_e32 v101, v101, v109
	v_add_f32_e32 v102, v102, v110
	v_add_f32_e32 v103, v103, v111
	v_add_f32_e32 v104, v104, v112
	v_add_f32_e32 v105, v105, v113
	v_add_f32_e32 v106, v106, v114
	v_add_f32_e32 v107, v107, v115
	v_mov_b32_e32 v108, v100
	v_mov_b32_e32 v109, v101
	v_mov_b32_e32 v110, v102
	v_mov_b32_e32 v111, v103
	v_mov_b32_e32 v112, v104
	v_mov_b32_e32 v113, v105
	v_mov_b32_e32 v114, v106
	v_mov_b32_e32 v115, v107
	s_nop 1
	v_permlane32_swap_b32_e32 v108, v100
	v_permlane32_swap_b32_e32 v109, v101
	v_permlane32_swap_b32_e32 v110, v102
	v_permlane32_swap_b32_e32 v111, v103
	v_permlane32_swap_b32_e32 v112, v104
	v_permlane32_swap_b32_e32 v113, v105
	v_permlane32_swap_b32_e32 v114, v106
	v_permlane32_swap_b32_e32 v115, v107
	v_add_f32_e32 v100, v100, v108
	v_add_f32_e32 v101, v101, v109
	v_add_f32_e32 v102, v102, v110
	v_add_f32_e32 v103, v103, v111
	v_add_f32_e32 v104, v104, v112
	v_add_f32_e32 v105, v105, v113
	v_add_f32_e32 v106, v106, v114
	v_add_f32_e32 v107, v107, v115
	v_mul_f32_e32 v230, 0x3a800000, v100
	v_mul_f32_e32 v116, 0x3a800000, v101
	v_fma_f32 v116, -v230, v230, v116
	v_max_f32_e32 v116, 0, v116
	v_add_f32_e32 v116, 0x3727c5ac, v116
	v_mul_f32_e32 v232, 0x3a800000, v102
	v_mul_f32_e32 v118, 0x3a800000, v103
	v_fma_f32 v118, -v232, v232, v118
	v_max_f32_e32 v118, 0, v118
	v_add_f32_e32 v118, 0x3727c5ac, v118
	v_mul_f32_e32 v234, 0x3a800000, v104
	v_mul_f32_e32 v120, 0x3a800000, v105
	v_fma_f32 v120, -v234, v234, v120
	v_max_f32_e32 v120, 0, v120
	v_add_f32_e32 v120, 0x3727c5ac, v120
	v_mul_f32_e32 v236, 0x3a800000, v106
	v_mul_f32_e32 v122, 0x3a800000, v107
	v_fma_f32 v122, -v236, v236, v122
	v_max_f32_e32 v122, 0, v122
	v_add_f32_e32 v122, 0x3727c5ac, v122
	v_rsq_f32_e32 v117, v116
	v_rsq_f32_e32 v119, v118
	v_rsq_f32_e32 v121, v120
	v_rsq_f32_e32 v123, v122
	s_nop 0
	v_mul_f32_e32 v124, v116, v117
	v_mul_f32_e32 v124, v124, v117
	v_fmaak_f32 v124, -0.5, v124, 0x3fc00000
	v_mul_f32_e32 v231, v117, v124
	v_mul_f32_e32 v125, v118, v119
	v_mul_f32_e32 v125, v125, v119
	v_fmaak_f32 v125, -0.5, v125, 0x3fc00000
	v_mul_f32_e32 v233, v119, v125
	v_mul_f32_e32 v126, v120, v121
	v_mul_f32_e32 v126, v126, v121
	v_fmaak_f32 v126, -0.5, v126, 0x3fc00000
	v_mul_f32_e32 v235, v121, v126
	v_mul_f32_e32 v127, v122, v123
	v_mul_f32_e32 v127, v127, v123
	v_fmaak_f32 v127, -0.5, v127, 0x3fc00000
	v_mul_f32_e32 v237, v123, v127
	v_pk_add_f32 v[36:37], v[36:37], v[230:231] op_sel_hi:[1,0] neg_lo:[0,1] neg_hi:[0,1]
	v_pk_add_f32 v[38:39], v[38:39], v[230:231] op_sel_hi:[1,0] neg_lo:[0,1] neg_hi:[0,1]
	v_pk_add_f32 v[40:41], v[40:41], v[230:231] op_sel_hi:[1,0] neg_lo:[0,1] neg_hi:[0,1]
	v_pk_add_f32 v[42:43], v[42:43], v[230:231] op_sel_hi:[1,0] neg_lo:[0,1] neg_hi:[0,1]
	v_pk_add_f32 v[44:45], v[44:45], v[230:231] op_sel_hi:[1,0] neg_lo:[0,1] neg_hi:[0,1]
	v_pk_add_f32 v[46:47], v[46:47], v[230:231] op_sel_hi:[1,0] neg_lo:[0,1] neg_hi:[0,1]
	v_pk_add_f32 v[48:49], v[48:49], v[230:231] op_sel_hi:[1,0] neg_lo:[0,1] neg_hi:[0,1]
	v_pk_add_f32 v[50:51], v[50:51], v[230:231] op_sel_hi:[1,0] neg_lo:[0,1] neg_hi:[0,1]
	v_pk_mul_f32 v[36:37], v[36:37], v[230:231] op_sel:[0,1] op_sel_hi:[1,1]
	v_pk_mul_f32 v[38:39], v[38:39], v[230:231] op_sel:[0,1] op_sel_hi:[1,1]
	v_pk_mul_f32 v[40:41], v[40:41], v[230:231] op_sel:[0,1] op_sel_hi:[1,1]
	v_pk_mul_f32 v[42:43], v[42:43], v[230:231] op_sel:[0,1] op_sel_hi:[1,1]
	v_pk_mul_f32 v[44:45], v[44:45], v[230:231] op_sel:[0,1] op_sel_hi:[1,1]
	v_pk_mul_f32 v[46:47], v[46:47], v[230:231] op_sel:[0,1] op_sel_hi:[1,1]
	v_pk_mul_f32 v[48:49], v[48:49], v[230:231] op_sel:[0,1] op_sel_hi:[1,1]
	v_pk_mul_f32 v[50:51], v[50:51], v[230:231] op_sel:[0,1] op_sel_hi:[1,1]
	v_pk_fma_f32 v[36:37], v[4:5], v[36:37], v[20:21]
	v_pk_fma_f32 v[38:39], v[6:7], v[38:39], v[22:23]
	v_pk_fma_f32 v[40:41], v[8:9], v[40:41], v[24:25]
	v_pk_fma_f32 v[42:43], v[10:11], v[42:43], v[26:27]
	v_pk_fma_f32 v[44:45], v[12:13], v[44:45], v[28:29]
	v_pk_fma_f32 v[46:47], v[14:15], v[46:47], v[30:31]
	v_pk_fma_f32 v[48:49], v[16:17], v[48:49], v[32:33]
	v_pk_fma_f32 v[50:51], v[18:19], v[50:51], v[34:35]
	v_cvt_pk_bf16_f32 v36, v36, v37
	v_cvt_pk_bf16_f32 v37, v38, v39
	v_cvt_pk_bf16_f32 v38, v40, v41
	v_cvt_pk_bf16_f32 v39, v42, v43
	v_cvt_pk_bf16_f32 v44, v44, v45
	v_cvt_pk_bf16_f32 v45, v46, v47
	v_cvt_pk_bf16_f32 v46, v48, v49
	v_cvt_pk_bf16_f32 v47, v50, v51
	v_lshl_add_u32 v3, s36, 11, v2
	global_store_dwordx4 v3, v[36:39], s[96:97] sc1
	global_store_dwordx4 v3, v[44:47], s[96:97] offset:1024 sc1
	v_pk_add_f32 v[52:53], v[52:53], v[232:233] op_sel_hi:[1,0] neg_lo:[0,1] neg_hi:[0,1]
	v_pk_add_f32 v[54:55], v[54:55], v[232:233] op_sel_hi:[1,0] neg_lo:[0,1] neg_hi:[0,1]
	v_pk_add_f32 v[56:57], v[56:57], v[232:233] op_sel_hi:[1,0] neg_lo:[0,1] neg_hi:[0,1]
	v_pk_add_f32 v[58:59], v[58:59], v[232:233] op_sel_hi:[1,0] neg_lo:[0,1] neg_hi:[0,1]
	v_pk_add_f32 v[60:61], v[60:61], v[232:233] op_sel_hi:[1,0] neg_lo:[0,1] neg_hi:[0,1]
	v_pk_add_f32 v[62:63], v[62:63], v[232:233] op_sel_hi:[1,0] neg_lo:[0,1] neg_hi:[0,1]
	v_pk_add_f32 v[64:65], v[64:65], v[232:233] op_sel_hi:[1,0] neg_lo:[0,1] neg_hi:[0,1]
	v_pk_add_f32 v[66:67], v[66:67], v[232:233] op_sel_hi:[1,0] neg_lo:[0,1] neg_hi:[0,1]
	v_pk_mul_f32 v[52:53], v[52:53], v[232:233] op_sel:[0,1] op_sel_hi:[1,1]
	v_pk_mul_f32 v[54:55], v[54:55], v[232:233] op_sel:[0,1] op_sel_hi:[1,1]
	v_pk_mul_f32 v[56:57], v[56:57], v[232:233] op_sel:[0,1] op_sel_hi:[1,1]
	v_pk_mul_f32 v[58:59], v[58:59], v[232:233] op_sel:[0,1] op_sel_hi:[1,1]
	v_pk_mul_f32 v[60:61], v[60:61], v[232:233] op_sel:[0,1] op_sel_hi:[1,1]
	v_pk_mul_f32 v[62:63], v[62:63], v[232:233] op_sel:[0,1] op_sel_hi:[1,1]
	v_pk_mul_f32 v[64:65], v[64:65], v[232:233] op_sel:[0,1] op_sel_hi:[1,1]
	v_pk_mul_f32 v[66:67], v[66:67], v[232:233] op_sel:[0,1] op_sel_hi:[1,1]
	v_pk_fma_f32 v[52:53], v[4:5], v[52:53], v[20:21]
	v_pk_fma_f32 v[54:55], v[6:7], v[54:55], v[22:23]
	v_pk_fma_f32 v[56:57], v[8:9], v[56:57], v[24:25]
	v_pk_fma_f32 v[58:59], v[10:11], v[58:59], v[26:27]
	v_pk_fma_f32 v[60:61], v[12:13], v[60:61], v[28:29]
	v_pk_fma_f32 v[62:63], v[14:15], v[62:63], v[30:31]
	v_pk_fma_f32 v[64:65], v[16:17], v[64:65], v[32:33]
	v_pk_fma_f32 v[66:67], v[18:19], v[66:67], v[34:35]
	v_cvt_pk_bf16_f32 v52, v52, v53
	v_cvt_pk_bf16_f32 v53, v54, v55
	v_cvt_pk_bf16_f32 v54, v56, v57
	v_cvt_pk_bf16_f32 v55, v58, v59
	v_cvt_pk_bf16_f32 v60, v60, v61
	v_cvt_pk_bf16_f32 v61, v62, v63
	v_cvt_pk_bf16_f32 v62, v64, v65
	v_cvt_pk_bf16_f32 v63, v66, v67
	v_lshl_add_u32 v3, s37, 11, v2
	global_store_dwordx4 v3, v[52:55], s[96:97] sc1
	global_store_dwordx4 v3, v[60:63], s[96:97] offset:1024 sc1
	v_pk_add_f32 v[68:69], v[68:69], v[234:235] op_sel_hi:[1,0] neg_lo:[0,1] neg_hi:[0,1]
	v_pk_add_f32 v[70:71], v[70:71], v[234:235] op_sel_hi:[1,0] neg_lo:[0,1] neg_hi:[0,1]
	v_pk_add_f32 v[72:73], v[72:73], v[234:235] op_sel_hi:[1,0] neg_lo:[0,1] neg_hi:[0,1]
	v_pk_add_f32 v[74:75], v[74:75], v[234:235] op_sel_hi:[1,0] neg_lo:[0,1] neg_hi:[0,1]
	v_pk_add_f32 v[76:77], v[76:77], v[234:235] op_sel_hi:[1,0] neg_lo:[0,1] neg_hi:[0,1]
	v_pk_add_f32 v[78:79], v[78:79], v[234:235] op_sel_hi:[1,0] neg_lo:[0,1] neg_hi:[0,1]
	v_pk_add_f32 v[80:81], v[80:81], v[234:235] op_sel_hi:[1,0] neg_lo:[0,1] neg_hi:[0,1]
	v_pk_add_f32 v[82:83], v[82:83], v[234:235] op_sel_hi:[1,0] neg_lo:[0,1] neg_hi:[0,1]
	v_pk_mul_f32 v[68:69], v[68:69], v[234:235] op_sel:[0,1] op_sel_hi:[1,1]
	v_pk_mul_f32 v[70:71], v[70:71], v[234:235] op_sel:[0,1] op_sel_hi:[1,1]
	v_pk_mul_f32 v[72:73], v[72:73], v[234:235] op_sel:[0,1] op_sel_hi:[1,1]
	v_pk_mul_f32 v[74:75], v[74:75], v[234:235] op_sel:[0,1] op_sel_hi:[1,1]
	v_pk_mul_f32 v[76:77], v[76:77], v[234:235] op_sel:[0,1] op_sel_hi:[1,1]
	v_pk_mul_f32 v[78:79], v[78:79], v[234:235] op_sel:[0,1] op_sel_hi:[1,1]
	v_pk_mul_f32 v[80:81], v[80:81], v[234:235] op_sel:[0,1] op_sel_hi:[1,1]
	v_pk_mul_f32 v[82:83], v[82:83], v[234:235] op_sel:[0,1] op_sel_hi:[1,1]
	v_pk_fma_f32 v[68:69], v[4:5], v[68:69], v[20:21]
	v_pk_fma_f32 v[70:71], v[6:7], v[70:71], v[22:23]
	v_pk_fma_f32 v[72:73], v[8:9], v[72:73], v[24:25]
	v_pk_fma_f32 v[74:75], v[10:11], v[74:75], v[26:27]
	v_pk_fma_f32 v[76:77], v[12:13], v[76:77], v[28:29]
	v_pk_fma_f32 v[78:79], v[14:15], v[78:79], v[30:31]
	v_pk_fma_f32 v[80:81], v[16:17], v[80:81], v[32:33]
	v_pk_fma_f32 v[82:83], v[18:19], v[82:83], v[34:35]
	v_cvt_pk_bf16_f32 v68, v68, v69
	v_cvt_pk_bf16_f32 v69, v70, v71
	v_cvt_pk_bf16_f32 v70, v72, v73
	v_cvt_pk_bf16_f32 v71, v74, v75
	v_cvt_pk_bf16_f32 v76, v76, v77
	v_cvt_pk_bf16_f32 v77, v78, v79
	v_cvt_pk_bf16_f32 v78, v80, v81
	v_cvt_pk_bf16_f32 v79, v82, v83
	v_lshl_add_u32 v3, s38, 11, v2
	global_store_dwordx4 v3, v[68:71], s[96:97] sc1
	global_store_dwordx4 v3, v[76:79], s[96:97] offset:1024 sc1
	v_pk_add_f32 v[84:85], v[84:85], v[236:237] op_sel_hi:[1,0] neg_lo:[0,1] neg_hi:[0,1]
	v_pk_add_f32 v[86:87], v[86:87], v[236:237] op_sel_hi:[1,0] neg_lo:[0,1] neg_hi:[0,1]
	v_pk_add_f32 v[88:89], v[88:89], v[236:237] op_sel_hi:[1,0] neg_lo:[0,1] neg_hi:[0,1]
	v_pk_add_f32 v[90:91], v[90:91], v[236:237] op_sel_hi:[1,0] neg_lo:[0,1] neg_hi:[0,1]
	v_pk_add_f32 v[92:93], v[92:93], v[236:237] op_sel_hi:[1,0] neg_lo:[0,1] neg_hi:[0,1]
	v_pk_add_f32 v[94:95], v[94:95], v[236:237] op_sel_hi:[1,0] neg_lo:[0,1] neg_hi:[0,1]
	v_pk_add_f32 v[96:97], v[96:97], v[236:237] op_sel_hi:[1,0] neg_lo:[0,1] neg_hi:[0,1]
	v_pk_add_f32 v[98:99], v[98:99], v[236:237] op_sel_hi:[1,0] neg_lo:[0,1] neg_hi:[0,1]
	v_pk_mul_f32 v[84:85], v[84:85], v[236:237] op_sel:[0,1] op_sel_hi:[1,1]
	v_pk_mul_f32 v[86:87], v[86:87], v[236:237] op_sel:[0,1] op_sel_hi:[1,1]
	v_pk_mul_f32 v[88:89], v[88:89], v[236:237] op_sel:[0,1] op_sel_hi:[1,1]
	v_pk_mul_f32 v[90:91], v[90:91], v[236:237] op_sel:[0,1] op_sel_hi:[1,1]
	v_pk_mul_f32 v[92:93], v[92:93], v[236:237] op_sel:[0,1] op_sel_hi:[1,1]
	v_pk_mul_f32 v[94:95], v[94:95], v[236:237] op_sel:[0,1] op_sel_hi:[1,1]
	v_pk_mul_f32 v[96:97], v[96:97], v[236:237] op_sel:[0,1] op_sel_hi:[1,1]
	v_pk_mul_f32 v[98:99], v[98:99], v[236:237] op_sel:[0,1] op_sel_hi:[1,1]
	v_pk_fma_f32 v[84:85], v[4:5], v[84:85], v[20:21]
	v_pk_fma_f32 v[86:87], v[6:7], v[86:87], v[22:23]
	v_pk_fma_f32 v[88:89], v[8:9], v[88:89], v[24:25]
	v_pk_fma_f32 v[90:91], v[10:11], v[90:91], v[26:27]
	v_pk_fma_f32 v[92:93], v[12:13], v[92:93], v[28:29]
	v_pk_fma_f32 v[94:95], v[14:15], v[94:95], v[30:31]
	v_pk_fma_f32 v[96:97], v[16:17], v[96:97], v[32:33]
	v_pk_fma_f32 v[98:99], v[18:19], v[98:99], v[34:35]
	v_cvt_pk_bf16_f32 v84, v84, v85
	v_cvt_pk_bf16_f32 v85, v86, v87
	v_cvt_pk_bf16_f32 v86, v88, v89
	v_cvt_pk_bf16_f32 v87, v90, v91
	v_cvt_pk_bf16_f32 v92, v92, v93
	v_cvt_pk_bf16_f32 v93, v94, v95
	v_cvt_pk_bf16_f32 v94, v96, v97
	v_cvt_pk_bf16_f32 v95, v98, v99
	v_lshl_add_u32 v3, s39, 11, v2
	global_store_dwordx4 v3, v[84:87], s[96:97] sc1
	global_store_dwordx4 v3, v[92:95], s[96:97] offset:1024 sc1
	s_mov_b64 s[52:53], exec
	s_mov_b64 exec, 1
	v_mov_b32_e32 v3, s36
	v_lshlrev_b32_e32 v3, 3, v3
	global_store_dwordx2 v3, v[230:231], s[92:93] sc1
	v_mov_b32_e32 v3, s37
	v_lshlrev_b32_e32 v3, 3, v3
	global_store_dwordx2 v3, v[232:233], s[92:93] sc1
	v_mov_b32_e32 v3, s38
	v_lshlrev_b32_e32 v3, 3, v3
	global_store_dwordx2 v3, v[234:235], s[92:93] sc1
	v_mov_b32_e32 v3, s39
	v_lshlrev_b32_e32 v3, 3, v3
	global_store_dwordx2 v3, v[236:237], s[92:93] sc1
	s_mov_b64 exec, s[52:53]
	s_add_u32 s36, s46, 0x800
	v_lshl_add_u32 v128, s36, 12, v1
	s_add_u32 s37, s46, 0x1800
	v_lshl_add_u32 v129, s37, 12, v1
	s_add_u32 s38, s46, 0x2800
	v_lshl_add_u32 v130, s38, 12, v1
	s_add_u32 s39, s46, 0x3800
	v_lshl_add_u32 v131, s39, 12, v1
	global_load_dwordx4 v[36:39], v128, s[64:65]
	global_load_dwordx4 v[40:43], v128, s[64:65] offset:16
	global_load_dwordx4 v[44:47], v128, s[64:65] offset:2048
	global_load_dwordx4 v[48:51], v128, s[64:65] offset:2064
	global_load_dwordx4 v[52:55], v129, s[64:65]
	global_load_dwordx4 v[56:59], v129, s[64:65] offset:16
	global_load_dwordx4 v[60:63], v129, s[64:65] offset:2048
	global_load_dwordx4 v[64:67], v129, s[64:65] offset:2064
	global_load_dwordx4 v[68:71], v130, s[64:65]
	global_load_dwordx4 v[72:75], v130, s[64:65] offset:16
	global_load_dwordx4 v[76:79], v130, s[64:65] offset:2048
	global_load_dwordx4 v[80:83], v130, s[64:65] offset:2064
	global_load_dwordx4 v[84:87], v131, s[64:65]
	global_load_dwordx4 v[88:91], v131, s[64:65] offset:16
	global_load_dwordx4 v[92:95], v131, s[64:65] offset:2048
	global_load_dwordx4 v[96:99], v131, s[64:65] offset:2064
	s_waitcnt vmcnt(28)
	v_pk_add_f32 v[108:109], v[156:157], v[158:159]
	v_pk_add_f32 v[110:111], v[160:161], v[162:163]
	v_pk_add_f32 v[112:113], v[164:165], v[166:167]
	v_pk_add_f32 v[114:115], v[168:169], v[170:171]
	v_pk_mul_f32 v[116:117], v[156:157], v[156:157]
	v_pk_fma_f32 v[116:117], v[158:159], v[158:159], v[116:117]
	v_pk_fma_f32 v[116:117], v[160:161], v[160:161], v[116:117]
	v_pk_fma_f32 v[116:117], v[162:163], v[162:163], v[116:117]
	v_pk_fma_f32 v[116:117], v[164:165], v[164:165], v[116:117]
	v_pk_fma_f32 v[116:117], v[166:167], v[166:167], v[116:117]
	v_pk_fma_f32 v[116:117], v[168:169], v[168:169], v[116:117]
	v_pk_fma_f32 v[116:117], v[170:171], v[170:171], v[116:117]
	v_pk_add_f32 v[108:109], v[108:109], v[110:111]
	v_pk_add_f32 v[112:113], v[112:113], v[114:115]
	v_pk_add_f32 v[108:109], v[108:109], v[112:113]
	v_add_f32_e32 v100, v108, v109
	v_add_f32_e32 v101, v116, v117
	v_pk_add_f32 v[108:109], v[172:173], v[174:175]
	v_pk_add_f32 v[110:111], v[176:177], v[178:179]
	v_pk_add_f32 v[112:113], v[180:181], v[182:183]
	v_pk_add_f32 v[114:115], v[184:185], v[186:187]
	v_pk_mul_f32 v[116:117], v[172:173], v[172:173]
	v_pk_fma_f32 v[116:117], v[174:175], v[174:175], v[116:117]
	v_pk_fma_f32 v[116:117], v[176:177], v[176:177], v[116:117]
	v_pk_fma_f32 v[116:117], v[178:179], v[178:179], v[116:117]
	v_pk_fma_f32 v[116:117], v[180:181], v[180:181], v[116:117]
	v_pk_fma_f32 v[116:117], v[182:183], v[182:183], v[116:117]
	v_pk_fma_f32 v[116:117], v[184:185], v[184:185], v[116:117]
	v_pk_fma_f32 v[116:117], v[186:187], v[186:187], v[116:117]
	v_pk_add_f32 v[108:109], v[108:109], v[110:111]
	v_pk_add_f32 v[112:113], v[112:113], v[114:115]
	v_pk_add_f32 v[108:109], v[108:109], v[112:113]
	v_add_f32_e32 v102, v108, v109
	v_add_f32_e32 v103, v116, v117
	v_pk_add_f32 v[108:109], v[188:189], v[190:191]
	v_pk_add_f32 v[110:111], v[192:193], v[194:195]
	v_pk_add_f32 v[112:113], v[196:197], v[198:199]
	v_pk_add_f32 v[114:115], v[200:201], v[202:203]
	v_pk_mul_f32 v[116:117], v[188:189], v[188:189]
	v_pk_fma_f32 v[116:117], v[190:191], v[190:191], v[116:117]
	v_pk_fma_f32 v[116:117], v[192:193], v[192:193], v[116:117]
	v_pk_fma_f32 v[116:117], v[194:195], v[194:195], v[116:117]
	v_pk_fma_f32 v[116:117], v[196:197], v[196:197], v[116:117]
	v_pk_fma_f32 v[116:117], v[198:199], v[198:199], v[116:117]
	v_pk_fma_f32 v[116:117], v[200:201], v[200:201], v[116:117]
	v_pk_fma_f32 v[116:117], v[202:203], v[202:203], v[116:117]
	v_pk_add_f32 v[108:109], v[108:109], v[110:111]
	v_pk_add_f32 v[112:113], v[112:113], v[114:115]
	v_pk_add_f32 v[108:109], v[108:109], v[112:113]
	v_add_f32_e32 v104, v108, v109
	v_add_f32_e32 v105, v116, v117
	v_pk_add_f32 v[108:109], v[204:205], v[206:207]
	v_pk_add_f32 v[110:111], v[208:209], v[210:211]
	v_pk_add_f32 v[112:113], v[212:213], v[214:215]
	v_pk_add_f32 v[114:115], v[216:217], v[218:219]
	v_pk_mul_f32 v[116:117], v[204:205], v[204:205]
	v_pk_fma_f32 v[116:117], v[206:207], v[206:207], v[116:117]
	v_pk_fma_f32 v[116:117], v[208:209], v[208:209], v[116:117]
	v_pk_fma_f32 v[116:117], v[210:211], v[210:211], v[116:117]
	v_pk_fma_f32 v[116:117], v[212:213], v[212:213], v[116:117]
	v_pk_fma_f32 v[116:117], v[214:215], v[214:215], v[116:117]
	v_pk_fma_f32 v[116:117], v[216:217], v[216:217], v[116:117]
	v_pk_fma_f32 v[116:117], v[218:219], v[218:219], v[116:117]
	v_pk_add_f32 v[108:109], v[108:109], v[110:111]
	v_pk_add_f32 v[112:113], v[112:113], v[114:115]
	v_pk_add_f32 v[108:109], v[108:109], v[112:113]
	v_add_f32_e32 v106, v108, v109
	v_add_f32_e32 v107, v116, v117
	v_add_f32_dpp v100, v100, v100 quad_perm:[1,0,3,2] row_mask:0xf bank_mask:0xf
	v_add_f32_dpp v101, v101, v101 quad_perm:[1,0,3,2] row_mask:0xf bank_mask:0xf
	v_add_f32_dpp v102, v102, v102 quad_perm:[1,0,3,2] row_mask:0xf bank_mask:0xf
	v_add_f32_dpp v103, v103, v103 quad_perm:[1,0,3,2] row_mask:0xf bank_mask:0xf
	v_add_f32_dpp v104, v104, v104 quad_perm:[1,0,3,2] row_mask:0xf bank_mask:0xf
	v_add_f32_dpp v105, v105, v105 quad_perm:[1,0,3,2] row_mask:0xf bank_mask:0xf
	v_add_f32_dpp v106, v106, v106 quad_perm:[1,0,3,2] row_mask:0xf bank_mask:0xf
	v_add_f32_dpp v107, v107, v107 quad_perm:[1,0,3,2] row_mask:0xf bank_mask:0xf
	v_add_f32_dpp v100, v100, v100 quad_perm:[2,3,0,1] row_mask:0xf bank_mask:0xf
	v_add_f32_dpp v101, v101, v101 quad_perm:[2,3,0,1] row_mask:0xf bank_mask:0xf
	v_add_f32_dpp v102, v102, v102 quad_perm:[2,3,0,1] row_mask:0xf bank_mask:0xf
	v_add_f32_dpp v103, v103, v103 quad_perm:[2,3,0,1] row_mask:0xf bank_mask:0xf
	v_add_f32_dpp v104, v104, v104 quad_perm:[2,3,0,1] row_mask:0xf bank_mask:0xf
	v_add_f32_dpp v105, v105, v105 quad_perm:[2,3,0,1] row_mask:0xf bank_mask:0xf
	v_add_f32_dpp v106, v106, v106 quad_perm:[2,3,0,1] row_mask:0xf bank_mask:0xf
	v_add_f32_dpp v107, v107, v107 quad_perm:[2,3,0,1] row_mask:0xf bank_mask:0xf
	v_add_f32_dpp v100, v100, v100 row_half_mirror row_mask:0xf bank_mask:0xf
	v_add_f32_dpp v101, v101, v101 row_half_mirror row_mask:0xf bank_mask:0xf
	v_add_f32_dpp v102, v102, v102 row_half_mirror row_mask:0xf bank_mask:0xf
	v_add_f32_dpp v103, v103, v103 row_half_mirror row_mask:0xf bank_mask:0xf
	v_add_f32_dpp v104, v104, v104 row_half_mirror row_mask:0xf bank_mask:0xf
	v_add_f32_dpp v105, v105, v105 row_half_mirror row_mask:0xf bank_mask:0xf
	v_add_f32_dpp v106, v106, v106 row_half_mirror row_mask:0xf bank_mask:0xf
	v_add_f32_dpp v107, v107, v107 row_half_mirror row_mask:0xf bank_mask:0xf
	v_add_f32_dpp v100, v100, v100 row_mirror row_mask:0xf bank_mask:0xf
	v_add_f32_dpp v101, v101, v101 row_mirror row_mask:0xf bank_mask:0xf
	v_add_f32_dpp v102, v102, v102 row_mirror row_mask:0xf bank_mask:0xf
	v_add_f32_dpp v103, v103, v103 row_mirror row_mask:0xf bank_mask:0xf
	v_add_f32_dpp v104, v104, v104 row_mirror row_mask:0xf bank_mask:0xf
	v_add_f32_dpp v105, v105, v105 row_mirror row_mask:0xf bank_mask:0xf
	v_add_f32_dpp v106, v106, v106 row_mirror row_mask:0xf bank_mask:0xf
	v_add_f32_dpp v107, v107, v107 row_mirror row_mask:0xf bank_mask:0xf
	v_mov_b32_e32 v108, v100
	v_mov_b32_e32 v109, v101
	v_mov_b32_e32 v110, v102
	v_mov_b32_e32 v111, v103
	v_mov_b32_e32 v112, v104
	v_mov_b32_e32 v113, v105
	v_mov_b32_e32 v114, v106
	v_mov_b32_e32 v115, v107
	s_nop 1
	v_permlane16_swap_b32_e32 v108, v100
	v_permlane16_swap_b32_e32 v109, v101
	v_permlane16_swap_b32_e32 v110, v102
	v_permlane16_swap_b32_e32 v111, v103
	v_permlane16_swap_b32_e32 v112, v104
	v_permlane16_swap_b32_e32 v113, v105
	v_permlane16_swap_b32_e32 v114, v106
	v_permlane16_swap_b32_e32 v115, v107
	v_add_f32_e32 v100, v100, v108
	v_add_f32_e32 v101, v101, v109
	v_add_f32_e32 v102, v102, v110
	v_add_f32_e32 v103, v103, v111
	v_add_f32_e32 v104, v104, v112
	v_add_f32_e32 v105, v105, v113
	v_add_f32_e32 v106, v106, v114
	v_add_f32_e32 v107, v107, v115
	v_mov_b32_e32 v108, v100
	v_mov_b32_e32 v109, v101
	v_mov_b32_e32 v110, v102
	v_mov_b32_e32 v111, v103
	v_mov_b32_e32 v112, v104
	v_mov_b32_e32 v113, v105
	v_mov_b32_e32 v114, v106
	v_mov_b32_e32 v115, v107
	s_nop 1
	v_permlane32_swap_b32_e32 v108, v100
	v_permlane32_swap_b32_e32 v109, v101
	v_permlane32_swap_b32_e32 v110, v102
	v_permlane32_swap_b32_e32 v111, v103
	v_permlane32_swap_b32_e32 v112, v104
	v_permlane32_swap_b32_e32 v113, v105
	v_permlane32_swap_b32_e32 v114, v106
	v_permlane32_swap_b32_e32 v115, v107
	v_add_f32_e32 v100, v100, v108
	v_add_f32_e32 v101, v101, v109
	v_add_f32_e32 v102, v102, v110
	v_add_f32_e32 v103, v103, v111
	v_add_f32_e32 v104, v104, v112
	v_add_f32_e32 v105, v105, v113
	v_add_f32_e32 v106, v106, v114
	v_add_f32_e32 v107, v107, v115
	v_mul_f32_e32 v238, 0x3a800000, v100
	v_mul_f32_e32 v116, 0x3a800000, v101
	v_fma_f32 v116, -v238, v238, v116
	v_max_f32_e32 v116, 0, v116
	v_add_f32_e32 v116, 0x3727c5ac, v116
	v_mul_f32_e32 v240, 0x3a800000, v102
	v_mul_f32_e32 v118, 0x3a800000, v103
	v_fma_f32 v118, -v240, v240, v118
	v_max_f32_e32 v118, 0, v118
	v_add_f32_e32 v118, 0x3727c5ac, v118
	v_mul_f32_e32 v242, 0x3a800000, v104
	v_mul_f32_e32 v120, 0x3a800000, v105
	v_fma_f32 v120, -v242, v242, v120
	v_max_f32_e32 v120, 0, v120
	v_add_f32_e32 v120, 0x3727c5ac, v120
	v_mul_f32_e32 v244, 0x3a800000, v106
	v_mul_f32_e32 v122, 0x3a800000, v107
	v_fma_f32 v122, -v244, v244, v122
	v_max_f32_e32 v122, 0, v122
	v_add_f32_e32 v122, 0x3727c5ac, v122
	v_rsq_f32_e32 v117, v116
	v_rsq_f32_e32 v119, v118
	v_rsq_f32_e32 v121, v120
	v_rsq_f32_e32 v123, v122
	s_nop 0
	v_mul_f32_e32 v124, v116, v117
	v_mul_f32_e32 v124, v124, v117
	v_fmaak_f32 v124, -0.5, v124, 0x3fc00000
	v_mul_f32_e32 v239, v117, v124
	v_mul_f32_e32 v125, v118, v119
	v_mul_f32_e32 v125, v125, v119
	v_fmaak_f32 v125, -0.5, v125, 0x3fc00000
	v_mul_f32_e32 v241, v119, v125
	v_mul_f32_e32 v126, v120, v121
	v_mul_f32_e32 v126, v126, v121
	v_fmaak_f32 v126, -0.5, v126, 0x3fc00000
	v_mul_f32_e32 v243, v121, v126
	v_mul_f32_e32 v127, v122, v123
	v_mul_f32_e32 v127, v127, v123
	v_fmaak_f32 v127, -0.5, v127, 0x3fc00000
	v_mul_f32_e32 v245, v123, v127
	v_pk_add_f32 v[156:157], v[156:157], v[238:239] op_sel_hi:[1,0] neg_lo:[0,1] neg_hi:[0,1]
	v_pk_add_f32 v[158:159], v[158:159], v[238:239] op_sel_hi:[1,0] neg_lo:[0,1] neg_hi:[0,1]
	v_pk_add_f32 v[160:161], v[160:161], v[238:239] op_sel_hi:[1,0] neg_lo:[0,1] neg_hi:[0,1]
	v_pk_add_f32 v[162:163], v[162:163], v[238:239] op_sel_hi:[1,0] neg_lo:[0,1] neg_hi:[0,1]
	v_pk_add_f32 v[164:165], v[164:165], v[238:239] op_sel_hi:[1,0] neg_lo:[0,1] neg_hi:[0,1]
	v_pk_add_f32 v[166:167], v[166:167], v[238:239] op_sel_hi:[1,0] neg_lo:[0,1] neg_hi:[0,1]
	v_pk_add_f32 v[168:169], v[168:169], v[238:239] op_sel_hi:[1,0] neg_lo:[0,1] neg_hi:[0,1]
	v_pk_add_f32 v[170:171], v[170:171], v[238:239] op_sel_hi:[1,0] neg_lo:[0,1] neg_hi:[0,1]
	v_pk_mul_f32 v[156:157], v[156:157], v[238:239] op_sel:[0,1] op_sel_hi:[1,1]
	v_pk_mul_f32 v[158:159], v[158:159], v[238:239] op_sel:[0,1] op_sel_hi:[1,1]
	v_pk_mul_f32 v[160:161], v[160:161], v[238:239] op_sel:[0,1] op_sel_hi:[1,1]
	v_pk_mul_f32 v[162:163], v[162:163], v[238:239] op_sel:[0,1] op_sel_hi:[1,1]
	v_pk_mul_f32 v[164:165], v[164:165], v[238:239] op_sel:[0,1] op_sel_hi:[1,1]
	v_pk_mul_f32 v[166:167], v[166:167], v[238:239] op_sel:[0,1] op_sel_hi:[1,1]
	v_pk_mul_f32 v[168:169], v[168:169], v[238:239] op_sel:[0,1] op_sel_hi:[1,1]
	v_pk_mul_f32 v[170:171], v[170:171], v[238:239] op_sel:[0,1] op_sel_hi:[1,1]
	v_pk_fma_f32 v[156:157], v[4:5], v[156:157], v[20:21]
	v_pk_fma_f32 v[158:159], v[6:7], v[158:159], v[22:23]
	v_pk_fma_f32 v[160:161], v[8:9], v[160:161], v[24:25]
	v_pk_fma_f32 v[162:163], v[10:11], v[162:163], v[26:27]
	v_pk_fma_f32 v[164:165], v[12:13], v[164:165], v[28:29]
	v_pk_fma_f32 v[166:167], v[14:15], v[166:167], v[30:31]
	v_pk_fma_f32 v[168:169], v[16:17], v[168:169], v[32:33]
	v_pk_fma_f32 v[170:171], v[18:19], v[170:171], v[34:35]
	v_cvt_pk_bf16_f32 v156, v156, v157
	v_cvt_pk_bf16_f32 v157, v158, v159
	v_cvt_pk_bf16_f32 v158, v160, v161
	v_cvt_pk_bf16_f32 v159, v162, v163
	v_cvt_pk_bf16_f32 v164, v164, v165
	v_cvt_pk_bf16_f32 v165, v166, v167
	v_cvt_pk_bf16_f32 v166, v168, v169
	v_cvt_pk_bf16_f32 v167, v170, v171
	v_lshl_add_u32 v3, s40, 11, v2
	global_store_dwordx4 v3, v[156:159], s[96:97] sc1
	global_store_dwordx4 v3, v[164:167], s[96:97] offset:1024 sc1
	v_pk_add_f32 v[172:173], v[172:173], v[240:241] op_sel_hi:[1,0] neg_lo:[0,1] neg_hi:[0,1]
	v_pk_add_f32 v[174:175], v[174:175], v[240:241] op_sel_hi:[1,0] neg_lo:[0,1] neg_hi:[0,1]
	v_pk_add_f32 v[176:177], v[176:177], v[240:241] op_sel_hi:[1,0] neg_lo:[0,1] neg_hi:[0,1]
	v_pk_add_f32 v[178:179], v[178:179], v[240:241] op_sel_hi:[1,0] neg_lo:[0,1] neg_hi:[0,1]
	v_pk_add_f32 v[180:181], v[180:181], v[240:241] op_sel_hi:[1,0] neg_lo:[0,1] neg_hi:[0,1]
	v_pk_add_f32 v[182:183], v[182:183], v[240:241] op_sel_hi:[1,0] neg_lo:[0,1] neg_hi:[0,1]
	v_pk_add_f32 v[184:185], v[184:185], v[240:241] op_sel_hi:[1,0] neg_lo:[0,1] neg_hi:[0,1]
	v_pk_add_f32 v[186:187], v[186:187], v[240:241] op_sel_hi:[1,0] neg_lo:[0,1] neg_hi:[0,1]
	v_pk_mul_f32 v[172:173], v[172:173], v[240:241] op_sel:[0,1] op_sel_hi:[1,1]
	v_pk_mul_f32 v[174:175], v[174:175], v[240:241] op_sel:[0,1] op_sel_hi:[1,1]
	v_pk_mul_f32 v[176:177], v[176:177], v[240:241] op_sel:[0,1] op_sel_hi:[1,1]
	v_pk_mul_f32 v[178:179], v[178:179], v[240:241] op_sel:[0,1] op_sel_hi:[1,1]
	v_pk_mul_f32 v[180:181], v[180:181], v[240:241] op_sel:[0,1] op_sel_hi:[1,1]
	v_pk_mul_f32 v[182:183], v[182:183], v[240:241] op_sel:[0,1] op_sel_hi:[1,1]
	v_pk_mul_f32 v[184:185], v[184:185], v[240:241] op_sel:[0,1] op_sel_hi:[1,1]
	v_pk_mul_f32 v[186:187], v[186:187], v[240:241] op_sel:[0,1] op_sel_hi:[1,1]
	v_pk_fma_f32 v[172:173], v[4:5], v[172:173], v[20:21]
	v_pk_fma_f32 v[174:175], v[6:7], v[174:175], v[22:23]
	v_pk_fma_f32 v[176:177], v[8:9], v[176:177], v[24:25]
	v_pk_fma_f32 v[178:179], v[10:11], v[178:179], v[26:27]
	v_pk_fma_f32 v[180:181], v[12:13], v[180:181], v[28:29]
	v_pk_fma_f32 v[182:183], v[14:15], v[182:183], v[30:31]
	v_pk_fma_f32 v[184:185], v[16:17], v[184:185], v[32:33]
	v_pk_fma_f32 v[186:187], v[18:19], v[186:187], v[34:35]
	v_cvt_pk_bf16_f32 v172, v172, v173
	v_cvt_pk_bf16_f32 v173, v174, v175
	v_cvt_pk_bf16_f32 v174, v176, v177
	v_cvt_pk_bf16_f32 v175, v178, v179
	v_cvt_pk_bf16_f32 v180, v180, v181
	v_cvt_pk_bf16_f32 v181, v182, v183
	v_cvt_pk_bf16_f32 v182, v184, v185
	v_cvt_pk_bf16_f32 v183, v186, v187
	v_lshl_add_u32 v3, s41, 11, v2
	global_store_dwordx4 v3, v[172:175], s[96:97] sc1
	global_store_dwordx4 v3, v[180:183], s[96:97] offset:1024 sc1
	v_pk_add_f32 v[188:189], v[188:189], v[242:243] op_sel_hi:[1,0] neg_lo:[0,1] neg_hi:[0,1]
	v_pk_add_f32 v[190:191], v[190:191], v[242:243] op_sel_hi:[1,0] neg_lo:[0,1] neg_hi:[0,1]
	v_pk_add_f32 v[192:193], v[192:193], v[242:243] op_sel_hi:[1,0] neg_lo:[0,1] neg_hi:[0,1]
	v_pk_add_f32 v[194:195], v[194:195], v[242:243] op_sel_hi:[1,0] neg_lo:[0,1] neg_hi:[0,1]
	v_pk_add_f32 v[196:197], v[196:197], v[242:243] op_sel_hi:[1,0] neg_lo:[0,1] neg_hi:[0,1]
	v_pk_add_f32 v[198:199], v[198:199], v[242:243] op_sel_hi:[1,0] neg_lo:[0,1] neg_hi:[0,1]
	v_pk_add_f32 v[200:201], v[200:201], v[242:243] op_sel_hi:[1,0] neg_lo:[0,1] neg_hi:[0,1]
	v_pk_add_f32 v[202:203], v[202:203], v[242:243] op_sel_hi:[1,0] neg_lo:[0,1] neg_hi:[0,1]
	v_pk_mul_f32 v[188:189], v[188:189], v[242:243] op_sel:[0,1] op_sel_hi:[1,1]
	v_pk_mul_f32 v[190:191], v[190:191], v[242:243] op_sel:[0,1] op_sel_hi:[1,1]
	v_pk_mul_f32 v[192:193], v[192:193], v[242:243] op_sel:[0,1] op_sel_hi:[1,1]
	v_pk_mul_f32 v[194:195], v[194:195], v[242:243] op_sel:[0,1] op_sel_hi:[1,1]
	v_pk_mul_f32 v[196:197], v[196:197], v[242:243] op_sel:[0,1] op_sel_hi:[1,1]
	v_pk_mul_f32 v[198:199], v[198:199], v[242:243] op_sel:[0,1] op_sel_hi:[1,1]
	v_pk_mul_f32 v[200:201], v[200:201], v[242:243] op_sel:[0,1] op_sel_hi:[1,1]
	v_pk_mul_f32 v[202:203], v[202:203], v[242:243] op_sel:[0,1] op_sel_hi:[1,1]
	v_pk_fma_f32 v[188:189], v[4:5], v[188:189], v[20:21]
	v_pk_fma_f32 v[190:191], v[6:7], v[190:191], v[22:23]
	v_pk_fma_f32 v[192:193], v[8:9], v[192:193], v[24:25]
	v_pk_fma_f32 v[194:195], v[10:11], v[194:195], v[26:27]
	v_pk_fma_f32 v[196:197], v[12:13], v[196:197], v[28:29]
	v_pk_fma_f32 v[198:199], v[14:15], v[198:199], v[30:31]
	v_pk_fma_f32 v[200:201], v[16:17], v[200:201], v[32:33]
	v_pk_fma_f32 v[202:203], v[18:19], v[202:203], v[34:35]
	v_cvt_pk_bf16_f32 v188, v188, v189
	v_cvt_pk_bf16_f32 v189, v190, v191
	v_cvt_pk_bf16_f32 v190, v192, v193
	v_cvt_pk_bf16_f32 v191, v194, v195
	v_cvt_pk_bf16_f32 v196, v196, v197
	v_cvt_pk_bf16_f32 v197, v198, v199
	v_cvt_pk_bf16_f32 v198, v200, v201
	v_cvt_pk_bf16_f32 v199, v202, v203
	v_lshl_add_u32 v3, s42, 11, v2
	global_store_dwordx4 v3, v[188:191], s[96:97] sc1
	global_store_dwordx4 v3, v[196:199], s[96:97] offset:1024 sc1
	v_pk_add_f32 v[204:205], v[204:205], v[244:245] op_sel_hi:[1,0] neg_lo:[0,1] neg_hi:[0,1]
	v_pk_add_f32 v[206:207], v[206:207], v[244:245] op_sel_hi:[1,0] neg_lo:[0,1] neg_hi:[0,1]
	v_pk_add_f32 v[208:209], v[208:209], v[244:245] op_sel_hi:[1,0] neg_lo:[0,1] neg_hi:[0,1]
	v_pk_add_f32 v[210:211], v[210:211], v[244:245] op_sel_hi:[1,0] neg_lo:[0,1] neg_hi:[0,1]
	v_pk_add_f32 v[212:213], v[212:213], v[244:245] op_sel_hi:[1,0] neg_lo:[0,1] neg_hi:[0,1]
	v_pk_add_f32 v[214:215], v[214:215], v[244:245] op_sel_hi:[1,0] neg_lo:[0,1] neg_hi:[0,1]
	v_pk_add_f32 v[216:217], v[216:217], v[244:245] op_sel_hi:[1,0] neg_lo:[0,1] neg_hi:[0,1]
	v_pk_add_f32 v[218:219], v[218:219], v[244:245] op_sel_hi:[1,0] neg_lo:[0,1] neg_hi:[0,1]
	v_pk_mul_f32 v[204:205], v[204:205], v[244:245] op_sel:[0,1] op_sel_hi:[1,1]
	v_pk_mul_f32 v[206:207], v[206:207], v[244:245] op_sel:[0,1] op_sel_hi:[1,1]
	v_pk_mul_f32 v[208:209], v[208:209], v[244:245] op_sel:[0,1] op_sel_hi:[1,1]
	v_pk_mul_f32 v[210:211], v[210:211], v[244:245] op_sel:[0,1] op_sel_hi:[1,1]
	v_pk_mul_f32 v[212:213], v[212:213], v[244:245] op_sel:[0,1] op_sel_hi:[1,1]
	v_pk_mul_f32 v[214:215], v[214:215], v[244:245] op_sel:[0,1] op_sel_hi:[1,1]
	v_pk_mul_f32 v[216:217], v[216:217], v[244:245] op_sel:[0,1] op_sel_hi:[1,1]
	v_pk_mul_f32 v[218:219], v[218:219], v[244:245] op_sel:[0,1] op_sel_hi:[1,1]
	v_pk_fma_f32 v[204:205], v[4:5], v[204:205], v[20:21]
	v_pk_fma_f32 v[206:207], v[6:7], v[206:207], v[22:23]
	v_pk_fma_f32 v[208:209], v[8:9], v[208:209], v[24:25]
	v_pk_fma_f32 v[210:211], v[10:11], v[210:211], v[26:27]
	v_pk_fma_f32 v[212:213], v[12:13], v[212:213], v[28:29]
	v_pk_fma_f32 v[214:215], v[14:15], v[214:215], v[30:31]
	v_pk_fma_f32 v[216:217], v[16:17], v[216:217], v[32:33]
	v_pk_fma_f32 v[218:219], v[18:19], v[218:219], v[34:35]
	v_cvt_pk_bf16_f32 v204, v204, v205
	v_cvt_pk_bf16_f32 v205, v206, v207
	v_cvt_pk_bf16_f32 v206, v208, v209
	v_cvt_pk_bf16_f32 v207, v210, v211
	v_cvt_pk_bf16_f32 v212, v212, v213
	v_cvt_pk_bf16_f32 v213, v214, v215
	v_cvt_pk_bf16_f32 v214, v216, v217
	v_cvt_pk_bf16_f32 v215, v218, v219
	v_lshl_add_u32 v3, s43, 11, v2
	global_store_dwordx4 v3, v[204:207], s[96:97] sc1
	global_store_dwordx4 v3, v[212:215], s[96:97] offset:1024 sc1
	s_mov_b64 s[52:53], exec
	s_mov_b64 exec, 1
	v_mov_b32_e32 v3, s40
	v_lshlrev_b32_e32 v3, 3, v3
	global_store_dwordx2 v3, v[238:239], s[92:93] sc1
	v_mov_b32_e32 v3, s41
	v_lshlrev_b32_e32 v3, 3, v3
	global_store_dwordx2 v3, v[240:241], s[92:93] sc1
	v_mov_b32_e32 v3, s42
	v_lshlrev_b32_e32 v3, 3, v3
	global_store_dwordx2 v3, v[242:243], s[92:93] sc1
	v_mov_b32_e32 v3, s43
	v_lshlrev_b32_e32 v3, 3, v3
	global_store_dwordx2 v3, v[244:245], s[92:93] sc1
	s_mov_b64 exec, s[52:53]
	s_add_u32 s40, s46, 0x4800
	v_lshl_add_u32 v132, s40, 12, v1
	s_add_u32 s41, s46, 0x5800
	v_lshl_add_u32 v133, s41, 12, v1
	s_add_u32 s42, s46, 0x6800
	v_lshl_add_u32 v134, s42, 12, v1
	s_add_u32 s43, s46, 0x7800
	v_lshl_add_u32 v135, s43, 12, v1
	global_load_dwordx4 v[156:159], v132, s[64:65]
	global_load_dwordx4 v[160:163], v132, s[64:65] offset:16
	global_load_dwordx4 v[164:167], v132, s[64:65] offset:2048
	global_load_dwordx4 v[168:171], v132, s[64:65] offset:2064
	global_load_dwordx4 v[172:175], v133, s[64:65]
	global_load_dwordx4 v[176:179], v133, s[64:65] offset:16
	global_load_dwordx4 v[180:183], v133, s[64:65] offset:2048
	global_load_dwordx4 v[184:187], v133, s[64:65] offset:2064
	global_load_dwordx4 v[188:191], v134, s[64:65]
	global_load_dwordx4 v[192:195], v134, s[64:65] offset:16
	global_load_dwordx4 v[196:199], v134, s[64:65] offset:2048
	global_load_dwordx4 v[200:203], v134, s[64:65] offset:2064
	global_load_dwordx4 v[204:207], v135, s[64:65]
	global_load_dwordx4 v[208:211], v135, s[64:65] offset:16
	global_load_dwordx4 v[212:215], v135, s[64:65] offset:2048
	global_load_dwordx4 v[216:219], v135, s[64:65] offset:2064
	s_waitcnt vmcnt(28)
	v_pk_add_f32 v[108:109], v[36:37], v[38:39]
	v_pk_add_f32 v[110:111], v[40:41], v[42:43]
	v_pk_add_f32 v[112:113], v[44:45], v[46:47]
	v_pk_add_f32 v[114:115], v[48:49], v[50:51]
	v_pk_mul_f32 v[116:117], v[36:37], v[36:37]
	v_pk_fma_f32 v[116:117], v[38:39], v[38:39], v[116:117]
	v_pk_fma_f32 v[116:117], v[40:41], v[40:41], v[116:117]
	v_pk_fma_f32 v[116:117], v[42:43], v[42:43], v[116:117]
	v_pk_fma_f32 v[116:117], v[44:45], v[44:45], v[116:117]
	v_pk_fma_f32 v[116:117], v[46:47], v[46:47], v[116:117]
	v_pk_fma_f32 v[116:117], v[48:49], v[48:49], v[116:117]
	v_pk_fma_f32 v[116:117], v[50:51], v[50:51], v[116:117]
	v_pk_add_f32 v[108:109], v[108:109], v[110:111]
	v_pk_add_f32 v[112:113], v[112:113], v[114:115]
	v_pk_add_f32 v[108:109], v[108:109], v[112:113]
	v_add_f32_e32 v100, v108, v109
	v_add_f32_e32 v101, v116, v117
	v_pk_add_f32 v[108:109], v[52:53], v[54:55]
	v_pk_add_f32 v[110:111], v[56:57], v[58:59]
	v_pk_add_f32 v[112:113], v[60:61], v[62:63]
	v_pk_add_f32 v[114:115], v[64:65], v[66:67]
	v_pk_mul_f32 v[116:117], v[52:53], v[52:53]
	v_pk_fma_f32 v[116:117], v[54:55], v[54:55], v[116:117]
	v_pk_fma_f32 v[116:117], v[56:57], v[56:57], v[116:117]
	v_pk_fma_f32 v[116:117], v[58:59], v[58:59], v[116:117]
	v_pk_fma_f32 v[116:117], v[60:61], v[60:61], v[116:117]
	v_pk_fma_f32 v[116:117], v[62:63], v[62:63], v[116:117]
	v_pk_fma_f32 v[116:117], v[64:65], v[64:65], v[116:117]
	v_pk_fma_f32 v[116:117], v[66:67], v[66:67], v[116:117]
	v_pk_add_f32 v[108:109], v[108:109], v[110:111]
	v_pk_add_f32 v[112:113], v[112:113], v[114:115]
	v_pk_add_f32 v[108:109], v[108:109], v[112:113]
	v_add_f32_e32 v102, v108, v109
	v_add_f32_e32 v103, v116, v117
	v_pk_add_f32 v[108:109], v[68:69], v[70:71]
	v_pk_add_f32 v[110:111], v[72:73], v[74:75]
	v_pk_add_f32 v[112:113], v[76:77], v[78:79]
	v_pk_add_f32 v[114:115], v[80:81], v[82:83]
	v_pk_mul_f32 v[116:117], v[68:69], v[68:69]
	v_pk_fma_f32 v[116:117], v[70:71], v[70:71], v[116:117]
	v_pk_fma_f32 v[116:117], v[72:73], v[72:73], v[116:117]
	v_pk_fma_f32 v[116:117], v[74:75], v[74:75], v[116:117]
	v_pk_fma_f32 v[116:117], v[76:77], v[76:77], v[116:117]
	v_pk_fma_f32 v[116:117], v[78:79], v[78:79], v[116:117]
	v_pk_fma_f32 v[116:117], v[80:81], v[80:81], v[116:117]
	v_pk_fma_f32 v[116:117], v[82:83], v[82:83], v[116:117]
	v_pk_add_f32 v[108:109], v[108:109], v[110:111]
	v_pk_add_f32 v[112:113], v[112:113], v[114:115]
	v_pk_add_f32 v[108:109], v[108:109], v[112:113]
	v_add_f32_e32 v104, v108, v109
	v_add_f32_e32 v105, v116, v117
	v_pk_add_f32 v[108:109], v[84:85], v[86:87]
	v_pk_add_f32 v[110:111], v[88:89], v[90:91]
	v_pk_add_f32 v[112:113], v[92:93], v[94:95]
	v_pk_add_f32 v[114:115], v[96:97], v[98:99]
	v_pk_mul_f32 v[116:117], v[84:85], v[84:85]
	v_pk_fma_f32 v[116:117], v[86:87], v[86:87], v[116:117]
	v_pk_fma_f32 v[116:117], v[88:89], v[88:89], v[116:117]
	v_pk_fma_f32 v[116:117], v[90:91], v[90:91], v[116:117]
	v_pk_fma_f32 v[116:117], v[92:93], v[92:93], v[116:117]
	v_pk_fma_f32 v[116:117], v[94:95], v[94:95], v[116:117]
	v_pk_fma_f32 v[116:117], v[96:97], v[96:97], v[116:117]
	v_pk_fma_f32 v[116:117], v[98:99], v[98:99], v[116:117]
	v_pk_add_f32 v[108:109], v[108:109], v[110:111]
	v_pk_add_f32 v[112:113], v[112:113], v[114:115]
	v_pk_add_f32 v[108:109], v[108:109], v[112:113]
	v_add_f32_e32 v106, v108, v109
	v_add_f32_e32 v107, v116, v117
	v_add_f32_dpp v100, v100, v100 quad_perm:[1,0,3,2] row_mask:0xf bank_mask:0xf
	v_add_f32_dpp v101, v101, v101 quad_perm:[1,0,3,2] row_mask:0xf bank_mask:0xf
	v_add_f32_dpp v102, v102, v102 quad_perm:[1,0,3,2] row_mask:0xf bank_mask:0xf
	v_add_f32_dpp v103, v103, v103 quad_perm:[1,0,3,2] row_mask:0xf bank_mask:0xf
	v_add_f32_dpp v104, v104, v104 quad_perm:[1,0,3,2] row_mask:0xf bank_mask:0xf
	v_add_f32_dpp v105, v105, v105 quad_perm:[1,0,3,2] row_mask:0xf bank_mask:0xf
	v_add_f32_dpp v106, v106, v106 quad_perm:[1,0,3,2] row_mask:0xf bank_mask:0xf
	v_add_f32_dpp v107, v107, v107 quad_perm:[1,0,3,2] row_mask:0xf bank_mask:0xf
	v_add_f32_dpp v100, v100, v100 quad_perm:[2,3,0,1] row_mask:0xf bank_mask:0xf
	v_add_f32_dpp v101, v101, v101 quad_perm:[2,3,0,1] row_mask:0xf bank_mask:0xf
	v_add_f32_dpp v102, v102, v102 quad_perm:[2,3,0,1] row_mask:0xf bank_mask:0xf
	v_add_f32_dpp v103, v103, v103 quad_perm:[2,3,0,1] row_mask:0xf bank_mask:0xf
	v_add_f32_dpp v104, v104, v104 quad_perm:[2,3,0,1] row_mask:0xf bank_mask:0xf
	v_add_f32_dpp v105, v105, v105 quad_perm:[2,3,0,1] row_mask:0xf bank_mask:0xf
	v_add_f32_dpp v106, v106, v106 quad_perm:[2,3,0,1] row_mask:0xf bank_mask:0xf
	v_add_f32_dpp v107, v107, v107 quad_perm:[2,3,0,1] row_mask:0xf bank_mask:0xf
	v_add_f32_dpp v100, v100, v100 row_half_mirror row_mask:0xf bank_mask:0xf
	v_add_f32_dpp v101, v101, v101 row_half_mirror row_mask:0xf bank_mask:0xf
	v_add_f32_dpp v102, v102, v102 row_half_mirror row_mask:0xf bank_mask:0xf
	v_add_f32_dpp v103, v103, v103 row_half_mirror row_mask:0xf bank_mask:0xf
	v_add_f32_dpp v104, v104, v104 row_half_mirror row_mask:0xf bank_mask:0xf
	v_add_f32_dpp v105, v105, v105 row_half_mirror row_mask:0xf bank_mask:0xf
	v_add_f32_dpp v106, v106, v106 row_half_mirror row_mask:0xf bank_mask:0xf
	v_add_f32_dpp v107, v107, v107 row_half_mirror row_mask:0xf bank_mask:0xf
	v_add_f32_dpp v100, v100, v100 row_mirror row_mask:0xf bank_mask:0xf
	v_add_f32_dpp v101, v101, v101 row_mirror row_mask:0xf bank_mask:0xf
	v_add_f32_dpp v102, v102, v102 row_mirror row_mask:0xf bank_mask:0xf
	v_add_f32_dpp v103, v103, v103 row_mirror row_mask:0xf bank_mask:0xf
	v_add_f32_dpp v104, v104, v104 row_mirror row_mask:0xf bank_mask:0xf
	v_add_f32_dpp v105, v105, v105 row_mirror row_mask:0xf bank_mask:0xf
	v_add_f32_dpp v106, v106, v106 row_mirror row_mask:0xf bank_mask:0xf
	v_add_f32_dpp v107, v107, v107 row_mirror row_mask:0xf bank_mask:0xf
	v_mov_b32_e32 v108, v100
	v_mov_b32_e32 v109, v101
	v_mov_b32_e32 v110, v102
	v_mov_b32_e32 v111, v103
	v_mov_b32_e32 v112, v104
	v_mov_b32_e32 v113, v105
	v_mov_b32_e32 v114, v106
	v_mov_b32_e32 v115, v107
	s_nop 1
	v_permlane16_swap_b32_e32 v108, v100
	v_permlane16_swap_b32_e32 v109, v101
	v_permlane16_swap_b32_e32 v110, v102
	v_permlane16_swap_b32_e32 v111, v103
	v_permlane16_swap_b32_e32 v112, v104
	v_permlane16_swap_b32_e32 v113, v105
	v_permlane16_swap_b32_e32 v114, v106
	v_permlane16_swap_b32_e32 v115, v107
	v_add_f32_e32 v100, v100, v108
	v_add_f32_e32 v101, v101, v109
	v_add_f32_e32 v102, v102, v110
	v_add_f32_e32 v103, v103, v111
	v_add_f32_e32 v104, v104, v112
	v_add_f32_e32 v105, v105, v113
	v_add_f32_e32 v106, v106, v114
	v_add_f32_e32 v107, v107, v115
	v_mov_b32_e32 v108, v100
	v_mov_b32_e32 v109, v101
	v_mov_b32_e32 v110, v102
	v_mov_b32_e32 v111, v103
	v_mov_b32_e32 v112, v104
	v_mov_b32_e32 v113, v105
	v_mov_b32_e32 v114, v106
	v_mov_b32_e32 v115, v107
	s_nop 1
	v_permlane32_swap_b32_e32 v108, v100
	v_permlane32_swap_b32_e32 v109, v101
	v_permlane32_swap_b32_e32 v110, v102
	v_permlane32_swap_b32_e32 v111, v103
	v_permlane32_swap_b32_e32 v112, v104
	v_permlane32_swap_b32_e32 v113, v105
	v_permlane32_swap_b32_e32 v114, v106
	v_permlane32_swap_b32_e32 v115, v107
	v_add_f32_e32 v100, v100, v108
	v_add_f32_e32 v101, v101, v109
	v_add_f32_e32 v102, v102, v110
	v_add_f32_e32 v103, v103, v111
	v_add_f32_e32 v104, v104, v112
	v_add_f32_e32 v105, v105, v113
	v_add_f32_e32 v106, v106, v114
	v_add_f32_e32 v107, v107, v115
	v_mul_f32_e32 v230, 0x3a800000, v100
	v_mul_f32_e32 v116, 0x3a800000, v101
	v_fma_f32 v116, -v230, v230, v116
	v_max_f32_e32 v116, 0, v116
	v_add_f32_e32 v116, 0x3727c5ac, v116
	v_mul_f32_e32 v232, 0x3a800000, v102
	v_mul_f32_e32 v118, 0x3a800000, v103
	v_fma_f32 v118, -v232, v232, v118
	v_max_f32_e32 v118, 0, v118
	v_add_f32_e32 v118, 0x3727c5ac, v118
	v_mul_f32_e32 v234, 0x3a800000, v104
	v_mul_f32_e32 v120, 0x3a800000, v105
	v_fma_f32 v120, -v234, v234, v120
	v_max_f32_e32 v120, 0, v120
	v_add_f32_e32 v120, 0x3727c5ac, v120
	v_mul_f32_e32 v236, 0x3a800000, v106
	v_mul_f32_e32 v122, 0x3a800000, v107
	v_fma_f32 v122, -v236, v236, v122
	v_max_f32_e32 v122, 0, v122
	v_add_f32_e32 v122, 0x3727c5ac, v122
	v_rsq_f32_e32 v117, v116
	v_rsq_f32_e32 v119, v118
	v_rsq_f32_e32 v121, v120
	v_rsq_f32_e32 v123, v122
	s_nop 0
	v_mul_f32_e32 v124, v116, v117
	v_mul_f32_e32 v124, v124, v117
	v_fmaak_f32 v124, -0.5, v124, 0x3fc00000
	v_mul_f32_e32 v231, v117, v124
	v_mul_f32_e32 v125, v118, v119
	v_mul_f32_e32 v125, v125, v119
	v_fmaak_f32 v125, -0.5, v125, 0x3fc00000
	v_mul_f32_e32 v233, v119, v125
	v_mul_f32_e32 v126, v120, v121
	v_mul_f32_e32 v126, v126, v121
	v_fmaak_f32 v126, -0.5, v126, 0x3fc00000
	v_mul_f32_e32 v235, v121, v126
	v_mul_f32_e32 v127, v122, v123
	v_mul_f32_e32 v127, v127, v123
	v_fmaak_f32 v127, -0.5, v127, 0x3fc00000
	v_mul_f32_e32 v237, v123, v127
	v_pk_add_f32 v[36:37], v[36:37], v[230:231] op_sel_hi:[1,0] neg_lo:[0,1] neg_hi:[0,1]
	v_pk_add_f32 v[38:39], v[38:39], v[230:231] op_sel_hi:[1,0] neg_lo:[0,1] neg_hi:[0,1]
	v_pk_add_f32 v[40:41], v[40:41], v[230:231] op_sel_hi:[1,0] neg_lo:[0,1] neg_hi:[0,1]
	v_pk_add_f32 v[42:43], v[42:43], v[230:231] op_sel_hi:[1,0] neg_lo:[0,1] neg_hi:[0,1]
	v_pk_add_f32 v[44:45], v[44:45], v[230:231] op_sel_hi:[1,0] neg_lo:[0,1] neg_hi:[0,1]
	v_pk_add_f32 v[46:47], v[46:47], v[230:231] op_sel_hi:[1,0] neg_lo:[0,1] neg_hi:[0,1]
	v_pk_add_f32 v[48:49], v[48:49], v[230:231] op_sel_hi:[1,0] neg_lo:[0,1] neg_hi:[0,1]
	v_pk_add_f32 v[50:51], v[50:51], v[230:231] op_sel_hi:[1,0] neg_lo:[0,1] neg_hi:[0,1]
	v_pk_mul_f32 v[36:37], v[36:37], v[230:231] op_sel:[0,1] op_sel_hi:[1,1]
	v_pk_mul_f32 v[38:39], v[38:39], v[230:231] op_sel:[0,1] op_sel_hi:[1,1]
	v_pk_mul_f32 v[40:41], v[40:41], v[230:231] op_sel:[0,1] op_sel_hi:[1,1]
	v_pk_mul_f32 v[42:43], v[42:43], v[230:231] op_sel:[0,1] op_sel_hi:[1,1]
	v_pk_mul_f32 v[44:45], v[44:45], v[230:231] op_sel:[0,1] op_sel_hi:[1,1]
	v_pk_mul_f32 v[46:47], v[46:47], v[230:231] op_sel:[0,1] op_sel_hi:[1,1]
	v_pk_mul_f32 v[48:49], v[48:49], v[230:231] op_sel:[0,1] op_sel_hi:[1,1]
	v_pk_mul_f32 v[50:51], v[50:51], v[230:231] op_sel:[0,1] op_sel_hi:[1,1]
	v_pk_fma_f32 v[36:37], v[4:5], v[36:37], v[20:21]
	v_pk_fma_f32 v[38:39], v[6:7], v[38:39], v[22:23]
	v_pk_fma_f32 v[40:41], v[8:9], v[40:41], v[24:25]
	v_pk_fma_f32 v[42:43], v[10:11], v[42:43], v[26:27]
	v_pk_fma_f32 v[44:45], v[12:13], v[44:45], v[28:29]
	v_pk_fma_f32 v[46:47], v[14:15], v[46:47], v[30:31]
	v_pk_fma_f32 v[48:49], v[16:17], v[48:49], v[32:33]
	v_pk_fma_f32 v[50:51], v[18:19], v[50:51], v[34:35]
	v_cvt_pk_bf16_f32 v36, v36, v37
	v_cvt_pk_bf16_f32 v37, v38, v39
	v_cvt_pk_bf16_f32 v38, v40, v41
	v_cvt_pk_bf16_f32 v39, v42, v43
	v_cvt_pk_bf16_f32 v44, v44, v45
	v_cvt_pk_bf16_f32 v45, v46, v47
	v_cvt_pk_bf16_f32 v46, v48, v49
	v_cvt_pk_bf16_f32 v47, v50, v51
	v_lshl_add_u32 v3, s36, 11, v2
	global_store_dwordx4 v3, v[36:39], s[96:97] sc1
	global_store_dwordx4 v3, v[44:47], s[96:97] offset:1024 sc1
	v_pk_add_f32 v[52:53], v[52:53], v[232:233] op_sel_hi:[1,0] neg_lo:[0,1] neg_hi:[0,1]
	v_pk_add_f32 v[54:55], v[54:55], v[232:233] op_sel_hi:[1,0] neg_lo:[0,1] neg_hi:[0,1]
	v_pk_add_f32 v[56:57], v[56:57], v[232:233] op_sel_hi:[1,0] neg_lo:[0,1] neg_hi:[0,1]
	v_pk_add_f32 v[58:59], v[58:59], v[232:233] op_sel_hi:[1,0] neg_lo:[0,1] neg_hi:[0,1]
	v_pk_add_f32 v[60:61], v[60:61], v[232:233] op_sel_hi:[1,0] neg_lo:[0,1] neg_hi:[0,1]
	v_pk_add_f32 v[62:63], v[62:63], v[232:233] op_sel_hi:[1,0] neg_lo:[0,1] neg_hi:[0,1]
	v_pk_add_f32 v[64:65], v[64:65], v[232:233] op_sel_hi:[1,0] neg_lo:[0,1] neg_hi:[0,1]
	v_pk_add_f32 v[66:67], v[66:67], v[232:233] op_sel_hi:[1,0] neg_lo:[0,1] neg_hi:[0,1]
	v_pk_mul_f32 v[52:53], v[52:53], v[232:233] op_sel:[0,1] op_sel_hi:[1,1]
	v_pk_mul_f32 v[54:55], v[54:55], v[232:233] op_sel:[0,1] op_sel_hi:[1,1]
	v_pk_mul_f32 v[56:57], v[56:57], v[232:233] op_sel:[0,1] op_sel_hi:[1,1]
	v_pk_mul_f32 v[58:59], v[58:59], v[232:233] op_sel:[0,1] op_sel_hi:[1,1]
	v_pk_mul_f32 v[60:61], v[60:61], v[232:233] op_sel:[0,1] op_sel_hi:[1,1]
	v_pk_mul_f32 v[62:63], v[62:63], v[232:233] op_sel:[0,1] op_sel_hi:[1,1]
	v_pk_mul_f32 v[64:65], v[64:65], v[232:233] op_sel:[0,1] op_sel_hi:[1,1]
	v_pk_mul_f32 v[66:67], v[66:67], v[232:233] op_sel:[0,1] op_sel_hi:[1,1]
	v_pk_fma_f32 v[52:53], v[4:5], v[52:53], v[20:21]
	v_pk_fma_f32 v[54:55], v[6:7], v[54:55], v[22:23]
	v_pk_fma_f32 v[56:57], v[8:9], v[56:57], v[24:25]
	v_pk_fma_f32 v[58:59], v[10:11], v[58:59], v[26:27]
	v_pk_fma_f32 v[60:61], v[12:13], v[60:61], v[28:29]
	v_pk_fma_f32 v[62:63], v[14:15], v[62:63], v[30:31]
	v_pk_fma_f32 v[64:65], v[16:17], v[64:65], v[32:33]
	v_pk_fma_f32 v[66:67], v[18:19], v[66:67], v[34:35]
	v_cvt_pk_bf16_f32 v52, v52, v53
	v_cvt_pk_bf16_f32 v53, v54, v55
	v_cvt_pk_bf16_f32 v54, v56, v57
	v_cvt_pk_bf16_f32 v55, v58, v59
	v_cvt_pk_bf16_f32 v60, v60, v61
	v_cvt_pk_bf16_f32 v61, v62, v63
	v_cvt_pk_bf16_f32 v62, v64, v65
	v_cvt_pk_bf16_f32 v63, v66, v67
	v_lshl_add_u32 v3, s37, 11, v2
	global_store_dwordx4 v3, v[52:55], s[96:97] sc1
	global_store_dwordx4 v3, v[60:63], s[96:97] offset:1024 sc1
	v_pk_add_f32 v[68:69], v[68:69], v[234:235] op_sel_hi:[1,0] neg_lo:[0,1] neg_hi:[0,1]
	v_pk_add_f32 v[70:71], v[70:71], v[234:235] op_sel_hi:[1,0] neg_lo:[0,1] neg_hi:[0,1]
	v_pk_add_f32 v[72:73], v[72:73], v[234:235] op_sel_hi:[1,0] neg_lo:[0,1] neg_hi:[0,1]
	v_pk_add_f32 v[74:75], v[74:75], v[234:235] op_sel_hi:[1,0] neg_lo:[0,1] neg_hi:[0,1]
	v_pk_add_f32 v[76:77], v[76:77], v[234:235] op_sel_hi:[1,0] neg_lo:[0,1] neg_hi:[0,1]
	v_pk_add_f32 v[78:79], v[78:79], v[234:235] op_sel_hi:[1,0] neg_lo:[0,1] neg_hi:[0,1]
	v_pk_add_f32 v[80:81], v[80:81], v[234:235] op_sel_hi:[1,0] neg_lo:[0,1] neg_hi:[0,1]
	v_pk_add_f32 v[82:83], v[82:83], v[234:235] op_sel_hi:[1,0] neg_lo:[0,1] neg_hi:[0,1]
	v_pk_mul_f32 v[68:69], v[68:69], v[234:235] op_sel:[0,1] op_sel_hi:[1,1]
	v_pk_mul_f32 v[70:71], v[70:71], v[234:235] op_sel:[0,1] op_sel_hi:[1,1]
	v_pk_mul_f32 v[72:73], v[72:73], v[234:235] op_sel:[0,1] op_sel_hi:[1,1]
	v_pk_mul_f32 v[74:75], v[74:75], v[234:235] op_sel:[0,1] op_sel_hi:[1,1]
	v_pk_mul_f32 v[76:77], v[76:77], v[234:235] op_sel:[0,1] op_sel_hi:[1,1]
	v_pk_mul_f32 v[78:79], v[78:79], v[234:235] op_sel:[0,1] op_sel_hi:[1,1]
	v_pk_mul_f32 v[80:81], v[80:81], v[234:235] op_sel:[0,1] op_sel_hi:[1,1]
	v_pk_mul_f32 v[82:83], v[82:83], v[234:235] op_sel:[0,1] op_sel_hi:[1,1]
	v_pk_fma_f32 v[68:69], v[4:5], v[68:69], v[20:21]
	v_pk_fma_f32 v[70:71], v[6:7], v[70:71], v[22:23]
	v_pk_fma_f32 v[72:73], v[8:9], v[72:73], v[24:25]
	v_pk_fma_f32 v[74:75], v[10:11], v[74:75], v[26:27]
	v_pk_fma_f32 v[76:77], v[12:13], v[76:77], v[28:29]
	v_pk_fma_f32 v[78:79], v[14:15], v[78:79], v[30:31]
	v_pk_fma_f32 v[80:81], v[16:17], v[80:81], v[32:33]
	v_pk_fma_f32 v[82:83], v[18:19], v[82:83], v[34:35]
	v_cvt_pk_bf16_f32 v68, v68, v69
	v_cvt_pk_bf16_f32 v69, v70, v71
	v_cvt_pk_bf16_f32 v70, v72, v73
	v_cvt_pk_bf16_f32 v71, v74, v75
	v_cvt_pk_bf16_f32 v76, v76, v77
	v_cvt_pk_bf16_f32 v77, v78, v79
	v_cvt_pk_bf16_f32 v78, v80, v81
	v_cvt_pk_bf16_f32 v79, v82, v83
	v_lshl_add_u32 v3, s38, 11, v2
	global_store_dwordx4 v3, v[68:71], s[96:97] sc1
	global_store_dwordx4 v3, v[76:79], s[96:97] offset:1024 sc1
	v_pk_add_f32 v[84:85], v[84:85], v[236:237] op_sel_hi:[1,0] neg_lo:[0,1] neg_hi:[0,1]
	v_pk_add_f32 v[86:87], v[86:87], v[236:237] op_sel_hi:[1,0] neg_lo:[0,1] neg_hi:[0,1]
	v_pk_add_f32 v[88:89], v[88:89], v[236:237] op_sel_hi:[1,0] neg_lo:[0,1] neg_hi:[0,1]
	v_pk_add_f32 v[90:91], v[90:91], v[236:237] op_sel_hi:[1,0] neg_lo:[0,1] neg_hi:[0,1]
	v_pk_add_f32 v[92:93], v[92:93], v[236:237] op_sel_hi:[1,0] neg_lo:[0,1] neg_hi:[0,1]
	v_pk_add_f32 v[94:95], v[94:95], v[236:237] op_sel_hi:[1,0] neg_lo:[0,1] neg_hi:[0,1]
	v_pk_add_f32 v[96:97], v[96:97], v[236:237] op_sel_hi:[1,0] neg_lo:[0,1] neg_hi:[0,1]
	v_pk_add_f32 v[98:99], v[98:99], v[236:237] op_sel_hi:[1,0] neg_lo:[0,1] neg_hi:[0,1]
	v_pk_mul_f32 v[84:85], v[84:85], v[236:237] op_sel:[0,1] op_sel_hi:[1,1]
	v_pk_mul_f32 v[86:87], v[86:87], v[236:237] op_sel:[0,1] op_sel_hi:[1,1]
	v_pk_mul_f32 v[88:89], v[88:89], v[236:237] op_sel:[0,1] op_sel_hi:[1,1]
	v_pk_mul_f32 v[90:91], v[90:91], v[236:237] op_sel:[0,1] op_sel_hi:[1,1]
	v_pk_mul_f32 v[92:93], v[92:93], v[236:237] op_sel:[0,1] op_sel_hi:[1,1]
	v_pk_mul_f32 v[94:95], v[94:95], v[236:237] op_sel:[0,1] op_sel_hi:[1,1]
	v_pk_mul_f32 v[96:97], v[96:97], v[236:237] op_sel:[0,1] op_sel_hi:[1,1]
	v_pk_mul_f32 v[98:99], v[98:99], v[236:237] op_sel:[0,1] op_sel_hi:[1,1]
	v_pk_fma_f32 v[84:85], v[4:5], v[84:85], v[20:21]
	v_pk_fma_f32 v[86:87], v[6:7], v[86:87], v[22:23]
	v_pk_fma_f32 v[88:89], v[8:9], v[88:89], v[24:25]
	v_pk_fma_f32 v[90:91], v[10:11], v[90:91], v[26:27]
	v_pk_fma_f32 v[92:93], v[12:13], v[92:93], v[28:29]
	v_pk_fma_f32 v[94:95], v[14:15], v[94:95], v[30:31]
	v_pk_fma_f32 v[96:97], v[16:17], v[96:97], v[32:33]
	v_pk_fma_f32 v[98:99], v[18:19], v[98:99], v[34:35]
	v_cvt_pk_bf16_f32 v84, v84, v85
	v_cvt_pk_bf16_f32 v85, v86, v87
	v_cvt_pk_bf16_f32 v86, v88, v89
	v_cvt_pk_bf16_f32 v87, v90, v91
	v_cvt_pk_bf16_f32 v92, v92, v93
	v_cvt_pk_bf16_f32 v93, v94, v95
	v_cvt_pk_bf16_f32 v94, v96, v97
	v_cvt_pk_bf16_f32 v95, v98, v99
	v_lshl_add_u32 v3, s39, 11, v2
	global_store_dwordx4 v3, v[84:87], s[96:97] sc1
	global_store_dwordx4 v3, v[92:95], s[96:97] offset:1024 sc1
	s_mov_b64 s[52:53], exec
	s_mov_b64 exec, 1
	v_mov_b32_e32 v3, s36
	v_lshlrev_b32_e32 v3, 3, v3
	global_store_dwordx2 v3, v[230:231], s[92:93] sc1
	v_mov_b32_e32 v3, s37
	v_lshlrev_b32_e32 v3, 3, v3
	global_store_dwordx2 v3, v[232:233], s[92:93] sc1
	v_mov_b32_e32 v3, s38
	v_lshlrev_b32_e32 v3, 3, v3
	global_store_dwordx2 v3, v[234:235], s[92:93] sc1
	v_mov_b32_e32 v3, s39
	v_lshlrev_b32_e32 v3, 3, v3
	global_store_dwordx2 v3, v[236:237], s[92:93] sc1
	s_mov_b64 exec, s[52:53]
	s_waitcnt vmcnt(12)
	v_pk_add_f32 v[108:109], v[156:157], v[158:159]
	v_pk_add_f32 v[110:111], v[160:161], v[162:163]
	v_pk_add_f32 v[112:113], v[164:165], v[166:167]
	v_pk_add_f32 v[114:115], v[168:169], v[170:171]
	v_pk_mul_f32 v[116:117], v[156:157], v[156:157]
	v_pk_fma_f32 v[116:117], v[158:159], v[158:159], v[116:117]
	v_pk_fma_f32 v[116:117], v[160:161], v[160:161], v[116:117]
	v_pk_fma_f32 v[116:117], v[162:163], v[162:163], v[116:117]
	v_pk_fma_f32 v[116:117], v[164:165], v[164:165], v[116:117]
	v_pk_fma_f32 v[116:117], v[166:167], v[166:167], v[116:117]
	v_pk_fma_f32 v[116:117], v[168:169], v[168:169], v[116:117]
	v_pk_fma_f32 v[116:117], v[170:171], v[170:171], v[116:117]
	v_pk_add_f32 v[108:109], v[108:109], v[110:111]
	v_pk_add_f32 v[112:113], v[112:113], v[114:115]
	v_pk_add_f32 v[108:109], v[108:109], v[112:113]
	v_add_f32_e32 v100, v108, v109
	v_add_f32_e32 v101, v116, v117
	v_pk_add_f32 v[108:109], v[172:173], v[174:175]
	v_pk_add_f32 v[110:111], v[176:177], v[178:179]
	v_pk_add_f32 v[112:113], v[180:181], v[182:183]
	v_pk_add_f32 v[114:115], v[184:185], v[186:187]
	v_pk_mul_f32 v[116:117], v[172:173], v[172:173]
	v_pk_fma_f32 v[116:117], v[174:175], v[174:175], v[116:117]
	v_pk_fma_f32 v[116:117], v[176:177], v[176:177], v[116:117]
	v_pk_fma_f32 v[116:117], v[178:179], v[178:179], v[116:117]
	v_pk_fma_f32 v[116:117], v[180:181], v[180:181], v[116:117]
	v_pk_fma_f32 v[116:117], v[182:183], v[182:183], v[116:117]
	v_pk_fma_f32 v[116:117], v[184:185], v[184:185], v[116:117]
	v_pk_fma_f32 v[116:117], v[186:187], v[186:187], v[116:117]
	v_pk_add_f32 v[108:109], v[108:109], v[110:111]
	v_pk_add_f32 v[112:113], v[112:113], v[114:115]
	v_pk_add_f32 v[108:109], v[108:109], v[112:113]
	v_add_f32_e32 v102, v108, v109
	v_add_f32_e32 v103, v116, v117
	v_pk_add_f32 v[108:109], v[188:189], v[190:191]
	v_pk_add_f32 v[110:111], v[192:193], v[194:195]
	v_pk_add_f32 v[112:113], v[196:197], v[198:199]
	v_pk_add_f32 v[114:115], v[200:201], v[202:203]
	v_pk_mul_f32 v[116:117], v[188:189], v[188:189]
	v_pk_fma_f32 v[116:117], v[190:191], v[190:191], v[116:117]
	v_pk_fma_f32 v[116:117], v[192:193], v[192:193], v[116:117]
	v_pk_fma_f32 v[116:117], v[194:195], v[194:195], v[116:117]
	v_pk_fma_f32 v[116:117], v[196:197], v[196:197], v[116:117]
	v_pk_fma_f32 v[116:117], v[198:199], v[198:199], v[116:117]
	v_pk_fma_f32 v[116:117], v[200:201], v[200:201], v[116:117]
	v_pk_fma_f32 v[116:117], v[202:203], v[202:203], v[116:117]
	v_pk_add_f32 v[108:109], v[108:109], v[110:111]
	v_pk_add_f32 v[112:113], v[112:113], v[114:115]
	v_pk_add_f32 v[108:109], v[108:109], v[112:113]
	v_add_f32_e32 v104, v108, v109
	v_add_f32_e32 v105, v116, v117
	v_pk_add_f32 v[108:109], v[204:205], v[206:207]
	v_pk_add_f32 v[110:111], v[208:209], v[210:211]
	v_pk_add_f32 v[112:113], v[212:213], v[214:215]
	v_pk_add_f32 v[114:115], v[216:217], v[218:219]
	v_pk_mul_f32 v[116:117], v[204:205], v[204:205]
	v_pk_fma_f32 v[116:117], v[206:207], v[206:207], v[116:117]
	v_pk_fma_f32 v[116:117], v[208:209], v[208:209], v[116:117]
	v_pk_fma_f32 v[116:117], v[210:211], v[210:211], v[116:117]
	v_pk_fma_f32 v[116:117], v[212:213], v[212:213], v[116:117]
	v_pk_fma_f32 v[116:117], v[214:215], v[214:215], v[116:117]
	v_pk_fma_f32 v[116:117], v[216:217], v[216:217], v[116:117]
	v_pk_fma_f32 v[116:117], v[218:219], v[218:219], v[116:117]
	v_pk_add_f32 v[108:109], v[108:109], v[110:111]
	v_pk_add_f32 v[112:113], v[112:113], v[114:115]
	v_pk_add_f32 v[108:109], v[108:109], v[112:113]
	v_add_f32_e32 v106, v108, v109
	v_add_f32_e32 v107, v116, v117
	v_add_f32_dpp v100, v100, v100 quad_perm:[1,0,3,2] row_mask:0xf bank_mask:0xf
	v_add_f32_dpp v101, v101, v101 quad_perm:[1,0,3,2] row_mask:0xf bank_mask:0xf
	v_add_f32_dpp v102, v102, v102 quad_perm:[1,0,3,2] row_mask:0xf bank_mask:0xf
	v_add_f32_dpp v103, v103, v103 quad_perm:[1,0,3,2] row_mask:0xf bank_mask:0xf
	v_add_f32_dpp v104, v104, v104 quad_perm:[1,0,3,2] row_mask:0xf bank_mask:0xf
	v_add_f32_dpp v105, v105, v105 quad_perm:[1,0,3,2] row_mask:0xf bank_mask:0xf
	v_add_f32_dpp v106, v106, v106 quad_perm:[1,0,3,2] row_mask:0xf bank_mask:0xf
	v_add_f32_dpp v107, v107, v107 quad_perm:[1,0,3,2] row_mask:0xf bank_mask:0xf
	v_add_f32_dpp v100, v100, v100 quad_perm:[2,3,0,1] row_mask:0xf bank_mask:0xf
	v_add_f32_dpp v101, v101, v101 quad_perm:[2,3,0,1] row_mask:0xf bank_mask:0xf
	v_add_f32_dpp v102, v102, v102 quad_perm:[2,3,0,1] row_mask:0xf bank_mask:0xf
	v_add_f32_dpp v103, v103, v103 quad_perm:[2,3,0,1] row_mask:0xf bank_mask:0xf
	v_add_f32_dpp v104, v104, v104 quad_perm:[2,3,0,1] row_mask:0xf bank_mask:0xf
	v_add_f32_dpp v105, v105, v105 quad_perm:[2,3,0,1] row_mask:0xf bank_mask:0xf
	v_add_f32_dpp v106, v106, v106 quad_perm:[2,3,0,1] row_mask:0xf bank_mask:0xf
	v_add_f32_dpp v107, v107, v107 quad_perm:[2,3,0,1] row_mask:0xf bank_mask:0xf
	v_add_f32_dpp v100, v100, v100 row_half_mirror row_mask:0xf bank_mask:0xf
	v_add_f32_dpp v101, v101, v101 row_half_mirror row_mask:0xf bank_mask:0xf
	v_add_f32_dpp v102, v102, v102 row_half_mirror row_mask:0xf bank_mask:0xf
	v_add_f32_dpp v103, v103, v103 row_half_mirror row_mask:0xf bank_mask:0xf
	v_add_f32_dpp v104, v104, v104 row_half_mirror row_mask:0xf bank_mask:0xf
	v_add_f32_dpp v105, v105, v105 row_half_mirror row_mask:0xf bank_mask:0xf
	v_add_f32_dpp v106, v106, v106 row_half_mirror row_mask:0xf bank_mask:0xf
	v_add_f32_dpp v107, v107, v107 row_half_mirror row_mask:0xf bank_mask:0xf
	v_add_f32_dpp v100, v100, v100 row_mirror row_mask:0xf bank_mask:0xf
	v_add_f32_dpp v101, v101, v101 row_mirror row_mask:0xf bank_mask:0xf
	v_add_f32_dpp v102, v102, v102 row_mirror row_mask:0xf bank_mask:0xf
	v_add_f32_dpp v103, v103, v103 row_mirror row_mask:0xf bank_mask:0xf
	v_add_f32_dpp v104, v104, v104 row_mirror row_mask:0xf bank_mask:0xf
	v_add_f32_dpp v105, v105, v105 row_mirror row_mask:0xf bank_mask:0xf
	v_add_f32_dpp v106, v106, v106 row_mirror row_mask:0xf bank_mask:0xf
	v_add_f32_dpp v107, v107, v107 row_mirror row_mask:0xf bank_mask:0xf
	v_mov_b32_e32 v108, v100
	v_mov_b32_e32 v109, v101
	v_mov_b32_e32 v110, v102
	v_mov_b32_e32 v111, v103
	v_mov_b32_e32 v112, v104
	v_mov_b32_e32 v113, v105
	v_mov_b32_e32 v114, v106
	v_mov_b32_e32 v115, v107
	s_nop 1
	v_permlane16_swap_b32_e32 v108, v100
	v_permlane16_swap_b32_e32 v109, v101
	v_permlane16_swap_b32_e32 v110, v102
	v_permlane16_swap_b32_e32 v111, v103
	v_permlane16_swap_b32_e32 v112, v104
	v_permlane16_swap_b32_e32 v113, v105
	v_permlane16_swap_b32_e32 v114, v106
	v_permlane16_swap_b32_e32 v115, v107
	v_add_f32_e32 v100, v100, v108
	v_add_f32_e32 v101, v101, v109
	v_add_f32_e32 v102, v102, v110
	v_add_f32_e32 v103, v103, v111
	v_add_f32_e32 v104, v104, v112
	v_add_f32_e32 v105, v105, v113
	v_add_f32_e32 v106, v106, v114
	v_add_f32_e32 v107, v107, v115
	v_mov_b32_e32 v108, v100
	v_mov_b32_e32 v109, v101
	v_mov_b32_e32 v110, v102
	v_mov_b32_e32 v111, v103
	v_mov_b32_e32 v112, v104
	v_mov_b32_e32 v113, v105
	v_mov_b32_e32 v114, v106
	v_mov_b32_e32 v115, v107
	s_nop 1
	v_permlane32_swap_b32_e32 v108, v100
	v_permlane32_swap_b32_e32 v109, v101
	v_permlane32_swap_b32_e32 v110, v102
	v_permlane32_swap_b32_e32 v111, v103
	v_permlane32_swap_b32_e32 v112, v104
	v_permlane32_swap_b32_e32 v113, v105
	v_permlane32_swap_b32_e32 v114, v106
	v_permlane32_swap_b32_e32 v115, v107
	v_add_f32_e32 v100, v100, v108
	v_add_f32_e32 v101, v101, v109
	v_add_f32_e32 v102, v102, v110
	v_add_f32_e32 v103, v103, v111
	v_add_f32_e32 v104, v104, v112
	v_add_f32_e32 v105, v105, v113
	v_add_f32_e32 v106, v106, v114
	v_add_f32_e32 v107, v107, v115
	v_mul_f32_e32 v238, 0x3a800000, v100
	v_mul_f32_e32 v116, 0x3a800000, v101
	v_fma_f32 v116, -v238, v238, v116
	v_max_f32_e32 v116, 0, v116
	v_add_f32_e32 v116, 0x3727c5ac, v116
	v_mul_f32_e32 v240, 0x3a800000, v102
	v_mul_f32_e32 v118, 0x3a800000, v103
	v_fma_f32 v118, -v240, v240, v118
	v_max_f32_e32 v118, 0, v118
	v_add_f32_e32 v118, 0x3727c5ac, v118
	v_mul_f32_e32 v242, 0x3a800000, v104
	v_mul_f32_e32 v120, 0x3a800000, v105
	v_fma_f32 v120, -v242, v242, v120
	v_max_f32_e32 v120, 0, v120
	v_add_f32_e32 v120, 0x3727c5ac, v120
	v_mul_f32_e32 v244, 0x3a800000, v106
	v_mul_f32_e32 v122, 0x3a800000, v107
	v_fma_f32 v122, -v244, v244, v122
	v_max_f32_e32 v122, 0, v122
	v_add_f32_e32 v122, 0x3727c5ac, v122
	v_rsq_f32_e32 v117, v116
	v_rsq_f32_e32 v119, v118
	v_rsq_f32_e32 v121, v120
	v_rsq_f32_e32 v123, v122
	s_nop 0
	v_mul_f32_e32 v124, v116, v117
	v_mul_f32_e32 v124, v124, v117
	v_fmaak_f32 v124, -0.5, v124, 0x3fc00000
	v_mul_f32_e32 v239, v117, v124
	v_mul_f32_e32 v125, v118, v119
	v_mul_f32_e32 v125, v125, v119
	v_fmaak_f32 v125, -0.5, v125, 0x3fc00000
	v_mul_f32_e32 v241, v119, v125
	v_mul_f32_e32 v126, v120, v121
	v_mul_f32_e32 v126, v126, v121
	v_fmaak_f32 v126, -0.5, v126, 0x3fc00000
	v_mul_f32_e32 v243, v121, v126
	v_mul_f32_e32 v127, v122, v123
	v_mul_f32_e32 v127, v127, v123
	v_fmaak_f32 v127, -0.5, v127, 0x3fc00000
	v_mul_f32_e32 v245, v123, v127
	v_pk_add_f32 v[156:157], v[156:157], v[238:239] op_sel_hi:[1,0] neg_lo:[0,1] neg_hi:[0,1]
	v_pk_add_f32 v[158:159], v[158:159], v[238:239] op_sel_hi:[1,0] neg_lo:[0,1] neg_hi:[0,1]
	v_pk_add_f32 v[160:161], v[160:161], v[238:239] op_sel_hi:[1,0] neg_lo:[0,1] neg_hi:[0,1]
	v_pk_add_f32 v[162:163], v[162:163], v[238:239] op_sel_hi:[1,0] neg_lo:[0,1] neg_hi:[0,1]
	v_pk_add_f32 v[164:165], v[164:165], v[238:239] op_sel_hi:[1,0] neg_lo:[0,1] neg_hi:[0,1]
	v_pk_add_f32 v[166:167], v[166:167], v[238:239] op_sel_hi:[1,0] neg_lo:[0,1] neg_hi:[0,1]
	v_pk_add_f32 v[168:169], v[168:169], v[238:239] op_sel_hi:[1,0] neg_lo:[0,1] neg_hi:[0,1]
	v_pk_add_f32 v[170:171], v[170:171], v[238:239] op_sel_hi:[1,0] neg_lo:[0,1] neg_hi:[0,1]
	v_pk_mul_f32 v[156:157], v[156:157], v[238:239] op_sel:[0,1] op_sel_hi:[1,1]
	v_pk_mul_f32 v[158:159], v[158:159], v[238:239] op_sel:[0,1] op_sel_hi:[1,1]
	v_pk_mul_f32 v[160:161], v[160:161], v[238:239] op_sel:[0,1] op_sel_hi:[1,1]
	v_pk_mul_f32 v[162:163], v[162:163], v[238:239] op_sel:[0,1] op_sel_hi:[1,1]
	v_pk_mul_f32 v[164:165], v[164:165], v[238:239] op_sel:[0,1] op_sel_hi:[1,1]
	v_pk_mul_f32 v[166:167], v[166:167], v[238:239] op_sel:[0,1] op_sel_hi:[1,1]
	v_pk_mul_f32 v[168:169], v[168:169], v[238:239] op_sel:[0,1] op_sel_hi:[1,1]
	v_pk_mul_f32 v[170:171], v[170:171], v[238:239] op_sel:[0,1] op_sel_hi:[1,1]
	v_pk_fma_f32 v[156:157], v[4:5], v[156:157], v[20:21]
	v_pk_fma_f32 v[158:159], v[6:7], v[158:159], v[22:23]
	v_pk_fma_f32 v[160:161], v[8:9], v[160:161], v[24:25]
	v_pk_fma_f32 v[162:163], v[10:11], v[162:163], v[26:27]
	v_pk_fma_f32 v[164:165], v[12:13], v[164:165], v[28:29]
	v_pk_fma_f32 v[166:167], v[14:15], v[166:167], v[30:31]
	v_pk_fma_f32 v[168:169], v[16:17], v[168:169], v[32:33]
	v_pk_fma_f32 v[170:171], v[18:19], v[170:171], v[34:35]
	v_cvt_pk_bf16_f32 v156, v156, v157
	v_cvt_pk_bf16_f32 v157, v158, v159
	v_cvt_pk_bf16_f32 v158, v160, v161
	v_cvt_pk_bf16_f32 v159, v162, v163
	v_cvt_pk_bf16_f32 v164, v164, v165
	v_cvt_pk_bf16_f32 v165, v166, v167
	v_cvt_pk_bf16_f32 v166, v168, v169
	v_cvt_pk_bf16_f32 v167, v170, v171
	v_lshl_add_u32 v3, s40, 11, v2
	global_store_dwordx4 v3, v[156:159], s[96:97] sc1
	global_store_dwordx4 v3, v[164:167], s[96:97] offset:1024 sc1
	v_pk_add_f32 v[172:173], v[172:173], v[240:241] op_sel_hi:[1,0] neg_lo:[0,1] neg_hi:[0,1]
	v_pk_add_f32 v[174:175], v[174:175], v[240:241] op_sel_hi:[1,0] neg_lo:[0,1] neg_hi:[0,1]
	v_pk_add_f32 v[176:177], v[176:177], v[240:241] op_sel_hi:[1,0] neg_lo:[0,1] neg_hi:[0,1]
	v_pk_add_f32 v[178:179], v[178:179], v[240:241] op_sel_hi:[1,0] neg_lo:[0,1] neg_hi:[0,1]
	v_pk_add_f32 v[180:181], v[180:181], v[240:241] op_sel_hi:[1,0] neg_lo:[0,1] neg_hi:[0,1]
	v_pk_add_f32 v[182:183], v[182:183], v[240:241] op_sel_hi:[1,0] neg_lo:[0,1] neg_hi:[0,1]
	v_pk_add_f32 v[184:185], v[184:185], v[240:241] op_sel_hi:[1,0] neg_lo:[0,1] neg_hi:[0,1]
	v_pk_add_f32 v[186:187], v[186:187], v[240:241] op_sel_hi:[1,0] neg_lo:[0,1] neg_hi:[0,1]
	v_pk_mul_f32 v[172:173], v[172:173], v[240:241] op_sel:[0,1] op_sel_hi:[1,1]
	v_pk_mul_f32 v[174:175], v[174:175], v[240:241] op_sel:[0,1] op_sel_hi:[1,1]
	v_pk_mul_f32 v[176:177], v[176:177], v[240:241] op_sel:[0,1] op_sel_hi:[1,1]
	v_pk_mul_f32 v[178:179], v[178:179], v[240:241] op_sel:[0,1] op_sel_hi:[1,1]
	v_pk_mul_f32 v[180:181], v[180:181], v[240:241] op_sel:[0,1] op_sel_hi:[1,1]
	v_pk_mul_f32 v[182:183], v[182:183], v[240:241] op_sel:[0,1] op_sel_hi:[1,1]
	v_pk_mul_f32 v[184:185], v[184:185], v[240:241] op_sel:[0,1] op_sel_hi:[1,1]
	v_pk_mul_f32 v[186:187], v[186:187], v[240:241] op_sel:[0,1] op_sel_hi:[1,1]
	v_pk_fma_f32 v[172:173], v[4:5], v[172:173], v[20:21]
	v_pk_fma_f32 v[174:175], v[6:7], v[174:175], v[22:23]
	v_pk_fma_f32 v[176:177], v[8:9], v[176:177], v[24:25]
	v_pk_fma_f32 v[178:179], v[10:11], v[178:179], v[26:27]
	v_pk_fma_f32 v[180:181], v[12:13], v[180:181], v[28:29]
	v_pk_fma_f32 v[182:183], v[14:15], v[182:183], v[30:31]
	v_pk_fma_f32 v[184:185], v[16:17], v[184:185], v[32:33]
	v_pk_fma_f32 v[186:187], v[18:19], v[186:187], v[34:35]
	v_cvt_pk_bf16_f32 v172, v172, v173
	v_cvt_pk_bf16_f32 v173, v174, v175
	v_cvt_pk_bf16_f32 v174, v176, v177
	v_cvt_pk_bf16_f32 v175, v178, v179
	v_cvt_pk_bf16_f32 v180, v180, v181
	v_cvt_pk_bf16_f32 v181, v182, v183
	v_cvt_pk_bf16_f32 v182, v184, v185
	v_cvt_pk_bf16_f32 v183, v186, v187
	v_lshl_add_u32 v3, s41, 11, v2
	global_store_dwordx4 v3, v[172:175], s[96:97] sc1
	global_store_dwordx4 v3, v[180:183], s[96:97] offset:1024 sc1
	v_pk_add_f32 v[188:189], v[188:189], v[242:243] op_sel_hi:[1,0] neg_lo:[0,1] neg_hi:[0,1]
	v_pk_add_f32 v[190:191], v[190:191], v[242:243] op_sel_hi:[1,0] neg_lo:[0,1] neg_hi:[0,1]
	v_pk_add_f32 v[192:193], v[192:193], v[242:243] op_sel_hi:[1,0] neg_lo:[0,1] neg_hi:[0,1]
	v_pk_add_f32 v[194:195], v[194:195], v[242:243] op_sel_hi:[1,0] neg_lo:[0,1] neg_hi:[0,1]
	v_pk_add_f32 v[196:197], v[196:197], v[242:243] op_sel_hi:[1,0] neg_lo:[0,1] neg_hi:[0,1]
	v_pk_add_f32 v[198:199], v[198:199], v[242:243] op_sel_hi:[1,0] neg_lo:[0,1] neg_hi:[0,1]
	v_pk_add_f32 v[200:201], v[200:201], v[242:243] op_sel_hi:[1,0] neg_lo:[0,1] neg_hi:[0,1]
	v_pk_add_f32 v[202:203], v[202:203], v[242:243] op_sel_hi:[1,0] neg_lo:[0,1] neg_hi:[0,1]
	v_pk_mul_f32 v[188:189], v[188:189], v[242:243] op_sel:[0,1] op_sel_hi:[1,1]
	v_pk_mul_f32 v[190:191], v[190:191], v[242:243] op_sel:[0,1] op_sel_hi:[1,1]
	v_pk_mul_f32 v[192:193], v[192:193], v[242:243] op_sel:[0,1] op_sel_hi:[1,1]
	v_pk_mul_f32 v[194:195], v[194:195], v[242:243] op_sel:[0,1] op_sel_hi:[1,1]
	v_pk_mul_f32 v[196:197], v[196:197], v[242:243] op_sel:[0,1] op_sel_hi:[1,1]
	v_pk_mul_f32 v[198:199], v[198:199], v[242:243] op_sel:[0,1] op_sel_hi:[1,1]
	v_pk_mul_f32 v[200:201], v[200:201], v[242:243] op_sel:[0,1] op_sel_hi:[1,1]
	v_pk_mul_f32 v[202:203], v[202:203], v[242:243] op_sel:[0,1] op_sel_hi:[1,1]
	v_pk_fma_f32 v[188:189], v[4:5], v[188:189], v[20:21]
	v_pk_fma_f32 v[190:191], v[6:7], v[190:191], v[22:23]
	v_pk_fma_f32 v[192:193], v[8:9], v[192:193], v[24:25]
	v_pk_fma_f32 v[194:195], v[10:11], v[194:195], v[26:27]
	v_pk_fma_f32 v[196:197], v[12:13], v[196:197], v[28:29]
	v_pk_fma_f32 v[198:199], v[14:15], v[198:199], v[30:31]
	v_pk_fma_f32 v[200:201], v[16:17], v[200:201], v[32:33]
	v_pk_fma_f32 v[202:203], v[18:19], v[202:203], v[34:35]
	v_cvt_pk_bf16_f32 v188, v188, v189
	v_cvt_pk_bf16_f32 v189, v190, v191
	v_cvt_pk_bf16_f32 v190, v192, v193
	v_cvt_pk_bf16_f32 v191, v194, v195
	v_cvt_pk_bf16_f32 v196, v196, v197
	v_cvt_pk_bf16_f32 v197, v198, v199
	v_cvt_pk_bf16_f32 v198, v200, v201
	v_cvt_pk_bf16_f32 v199, v202, v203
	v_lshl_add_u32 v3, s42, 11, v2
	global_store_dwordx4 v3, v[188:191], s[96:97] sc1
	global_store_dwordx4 v3, v[196:199], s[96:97] offset:1024 sc1
	v_pk_add_f32 v[204:205], v[204:205], v[244:245] op_sel_hi:[1,0] neg_lo:[0,1] neg_hi:[0,1]
	v_pk_add_f32 v[206:207], v[206:207], v[244:245] op_sel_hi:[1,0] neg_lo:[0,1] neg_hi:[0,1]
	v_pk_add_f32 v[208:209], v[208:209], v[244:245] op_sel_hi:[1,0] neg_lo:[0,1] neg_hi:[0,1]
	v_pk_add_f32 v[210:211], v[210:211], v[244:245] op_sel_hi:[1,0] neg_lo:[0,1] neg_hi:[0,1]
	v_pk_add_f32 v[212:213], v[212:213], v[244:245] op_sel_hi:[1,0] neg_lo:[0,1] neg_hi:[0,1]
	v_pk_add_f32 v[214:215], v[214:215], v[244:245] op_sel_hi:[1,0] neg_lo:[0,1] neg_hi:[0,1]
	v_pk_add_f32 v[216:217], v[216:217], v[244:245] op_sel_hi:[1,0] neg_lo:[0,1] neg_hi:[0,1]
	v_pk_add_f32 v[218:219], v[218:219], v[244:245] op_sel_hi:[1,0] neg_lo:[0,1] neg_hi:[0,1]
	v_pk_mul_f32 v[204:205], v[204:205], v[244:245] op_sel:[0,1] op_sel_hi:[1,1]
	v_pk_mul_f32 v[206:207], v[206:207], v[244:245] op_sel:[0,1] op_sel_hi:[1,1]
	v_pk_mul_f32 v[208:209], v[208:209], v[244:245] op_sel:[0,1] op_sel_hi:[1,1]
	v_pk_mul_f32 v[210:211], v[210:211], v[244:245] op_sel:[0,1] op_sel_hi:[1,1]
	v_pk_mul_f32 v[212:213], v[212:213], v[244:245] op_sel:[0,1] op_sel_hi:[1,1]
	v_pk_mul_f32 v[214:215], v[214:215], v[244:245] op_sel:[0,1] op_sel_hi:[1,1]
	v_pk_mul_f32 v[216:217], v[216:217], v[244:245] op_sel:[0,1] op_sel_hi:[1,1]
	v_pk_mul_f32 v[218:219], v[218:219], v[244:245] op_sel:[0,1] op_sel_hi:[1,1]
	v_pk_fma_f32 v[204:205], v[4:5], v[204:205], v[20:21]
	v_pk_fma_f32 v[206:207], v[6:7], v[206:207], v[22:23]
	v_pk_fma_f32 v[208:209], v[8:9], v[208:209], v[24:25]
	v_pk_fma_f32 v[210:211], v[10:11], v[210:211], v[26:27]
	v_pk_fma_f32 v[212:213], v[12:13], v[212:213], v[28:29]
	v_pk_fma_f32 v[214:215], v[14:15], v[214:215], v[30:31]
	v_pk_fma_f32 v[216:217], v[16:17], v[216:217], v[32:33]
	v_pk_fma_f32 v[218:219], v[18:19], v[218:219], v[34:35]
	v_cvt_pk_bf16_f32 v204, v204, v205
	v_cvt_pk_bf16_f32 v205, v206, v207
	v_cvt_pk_bf16_f32 v206, v208, v209
	v_cvt_pk_bf16_f32 v207, v210, v211
	v_cvt_pk_bf16_f32 v212, v212, v213
	v_cvt_pk_bf16_f32 v213, v214, v215
	v_cvt_pk_bf16_f32 v214, v216, v217
	v_cvt_pk_bf16_f32 v215, v218, v219
	v_lshl_add_u32 v3, s43, 11, v2
	global_store_dwordx4 v3, v[204:207], s[96:97] sc1
	global_store_dwordx4 v3, v[212:215], s[96:97] offset:1024 sc1
	s_mov_b64 s[52:53], exec
	s_mov_b64 exec, 1
	v_mov_b32_e32 v3, s40
	v_lshlrev_b32_e32 v3, 3, v3
	global_store_dwordx2 v3, v[238:239], s[92:93] sc1
	v_mov_b32_e32 v3, s41
	v_lshlrev_b32_e32 v3, 3, v3
	global_store_dwordx2 v3, v[240:241], s[92:93] sc1
	v_mov_b32_e32 v3, s42
	v_lshlrev_b32_e32 v3, 3, v3
	global_store_dwordx2 v3, v[242:243], s[92:93] sc1
	v_mov_b32_e32 v3, s43
	v_lshlrev_b32_e32 v3, 3, v3
	global_store_dwordx2 v3, v[244:245], s[92:93] sc1
	s_mov_b64 exec, s[52:53]
	s_cmp_gt_u32 s46, 15
	s_cbranch_scc1 .Lln2_done
	v_lshl_add_u32 v128, s46, 12, v1
	global_load_dwordx4 v[36:39], v128, s[30:31]
	global_load_dwordx4 v[40:43], v128, s[30:31] offset:16
	global_load_dwordx4 v[44:47], v128, s[30:31] offset:2048
	global_load_dwordx4 v[48:51], v128, s[30:31] offset:2064
	s_add_u32 s36, s46, 0x8000
	s_waitcnt vmcnt(0)
	v_pk_add_f32 v[108:109], v[36:37], v[38:39]
	v_pk_add_f32 v[110:111], v[40:41], v[42:43]
	v_pk_add_f32 v[112:113], v[44:45], v[46:47]
	v_pk_add_f32 v[114:115], v[48:49], v[50:51]
	v_pk_mul_f32 v[116:117], v[36:37], v[36:37]
	v_pk_fma_f32 v[116:117], v[38:39], v[38:39], v[116:117]
	v_pk_fma_f32 v[116:117], v[40:41], v[40:41], v[116:117]
	v_pk_fma_f32 v[116:117], v[42:43], v[42:43], v[116:117]
	v_pk_fma_f32 v[116:117], v[44:45], v[44:45], v[116:117]
	v_pk_fma_f32 v[116:117], v[46:47], v[46:47], v[116:117]
	v_pk_fma_f32 v[116:117], v[48:49], v[48:49], v[116:117]
	v_pk_fma_f32 v[116:117], v[50:51], v[50:51], v[116:117]
	v_pk_add_f32 v[108:109], v[108:109], v[110:111]
	v_pk_add_f32 v[112:113], v[112:113], v[114:115]
	v_pk_add_f32 v[108:109], v[108:109], v[112:113]
	v_add_f32_e32 v100, v108, v109
	v_add_f32_e32 v101, v116, v117
	s_nop 1
	v_add_f32_dpp v100, v100, v100 quad_perm:[1,0,3,2] row_mask:0xf bank_mask:0xf
	v_add_f32_dpp v101, v101, v101 quad_perm:[1,0,3,2] row_mask:0xf bank_mask:0xf
	s_nop 1
	v_add_f32_dpp v100, v100, v100 quad_perm:[2,3,0,1] row_mask:0xf bank_mask:0xf
	v_add_f32_dpp v101, v101, v101 quad_perm:[2,3,0,1] row_mask:0xf bank_mask:0xf
	s_nop 1
	v_add_f32_dpp v100, v100, v100 row_half_mirror row_mask:0xf bank_mask:0xf
	v_add_f32_dpp v101, v101, v101 row_half_mirror row_mask:0xf bank_mask:0xf
	s_nop 1
	v_add_f32_dpp v100, v100, v100 row_mirror row_mask:0xf bank_mask:0xf
	v_add_f32_dpp v101, v101, v101 row_mirror row_mask:0xf bank_mask:0xf
	s_nop 1
	v_mov_b32_e32 v108, v100
	v_mov_b32_e32 v109, v101
	s_nop 1
	v_permlane16_swap_b32_e32 v108, v100
	v_permlane16_swap_b32_e32 v109, v101
	v_add_f32_e32 v100, v100, v108
	v_add_f32_e32 v101, v101, v109
	v_mov_b32_e32 v108, v100
	v_mov_b32_e32 v109, v101
	s_nop 1
	v_permlane32_swap_b32_e32 v108, v100
	v_permlane32_swap_b32_e32 v109, v101
	v_add_f32_e32 v100, v100, v108
	v_add_f32_e32 v101, v101, v109
	v_mul_f32_e32 v230, 0x3a800000, v100
	v_mul_f32_e32 v116, 0x3a800000, v101
	v_fma_f32 v116, -v230, v230, v116
	v_max_f32_e32 v116, 0, v116
	v_add_f32_e32 v116, 0x3727c5ac, v116
	v_rsq_f32_e32 v117, v116
	s_nop 0
	v_mul_f32_e32 v124, v116, v117
	v_mul_f32_e32 v124, v124, v117
	v_fmaak_f32 v124, -0.5, v124, 0x3fc00000
	v_mul_f32_e32 v231, v117, v124
	v_pk_add_f32 v[36:37], v[36:37], v[230:231] op_sel_hi:[1,0] neg_lo:[0,1] neg_hi:[0,1]
	v_pk_add_f32 v[38:39], v[38:39], v[230:231] op_sel_hi:[1,0] neg_lo:[0,1] neg_hi:[0,1]
	v_pk_add_f32 v[40:41], v[40:41], v[230:231] op_sel_hi:[1,0] neg_lo:[0,1] neg_hi:[0,1]
	v_pk_add_f32 v[42:43], v[42:43], v[230:231] op_sel_hi:[1,0] neg_lo:[0,1] neg_hi:[0,1]
	v_pk_add_f32 v[44:45], v[44:45], v[230:231] op_sel_hi:[1,0] neg_lo:[0,1] neg_hi:[0,1]
	v_pk_add_f32 v[46:47], v[46:47], v[230:231] op_sel_hi:[1,0] neg_lo:[0,1] neg_hi:[0,1]
	v_pk_add_f32 v[48:49], v[48:49], v[230:231] op_sel_hi:[1,0] neg_lo:[0,1] neg_hi:[0,1]
	v_pk_add_f32 v[50:51], v[50:51], v[230:231] op_sel_hi:[1,0] neg_lo:[0,1] neg_hi:[0,1]
	v_pk_mul_f32 v[36:37], v[36:37], v[230:231] op_sel:[0,1] op_sel_hi:[1,1]
	v_pk_mul_f32 v[38:39], v[38:39], v[230:231] op_sel:[0,1] op_sel_hi:[1,1]
	v_pk_mul_f32 v[40:41], v[40:41], v[230:231] op_sel:[0,1] op_sel_hi:[1,1]
	v_pk_mul_f32 v[42:43], v[42:43], v[230:231] op_sel:[0,1] op_sel_hi:[1,1]
	v_pk_mul_f32 v[44:45], v[44:45], v[230:231] op_sel:[0,1] op_sel_hi:[1,1]
	v_pk_mul_f32 v[46:47], v[46:47], v[230:231] op_sel:[0,1] op_sel_hi:[1,1]
	v_pk_mul_f32 v[48:49], v[48:49], v[230:231] op_sel:[0,1] op_sel_hi:[1,1]
	v_pk_mul_f32 v[50:51], v[50:51], v[230:231] op_sel:[0,1] op_sel_hi:[1,1]
	v_pk_fma_f32 v[36:37], v[4:5], v[36:37], v[20:21]
	v_pk_fma_f32 v[38:39], v[6:7], v[38:39], v[22:23]
	v_pk_fma_f32 v[40:41], v[8:9], v[40:41], v[24:25]
	v_pk_fma_f32 v[42:43], v[10:11], v[42:43], v[26:27]
	v_pk_fma_f32 v[44:45], v[12:13], v[44:45], v[28:29]
	v_pk_fma_f32 v[46:47], v[14:15], v[46:47], v[30:31]
	v_pk_fma_f32 v[48:49], v[16:17], v[48:49], v[32:33]
	v_pk_fma_f32 v[50:51], v[18:19], v[50:51], v[34:35]
	v_cvt_pk_bf16_f32 v36, v36, v37
	v_cvt_pk_bf16_f32 v37, v38, v39
	v_cvt_pk_bf16_f32 v38, v40, v41
	v_cvt_pk_bf16_f32 v39, v42, v43
	v_cvt_pk_bf16_f32 v44, v44, v45
	v_cvt_pk_bf16_f32 v45, v46, v47
	v_cvt_pk_bf16_f32 v46, v48, v49
	v_cvt_pk_bf16_f32 v47, v50, v51
	v_lshl_add_u32 v3, s36, 11, v2
	global_store_dwordx4 v3, v[36:39], s[96:97] sc1
	global_store_dwordx4 v3, v[44:47], s[96:97] offset:1024 sc1
	s_mov_b64 s[52:53], exec
	s_mov_b64 exec, 1
	v_mov_b32_e32 v3, s36
	v_lshlrev_b32_e32 v3, 3, v3
	global_store_dwordx2 v3, v[230:231], s[92:93] sc1
	s_mov_b64 exec, s[52:53]
.Lln2_done:
	s_branch .LBB0_1165
	s_nop 0
	v_readfirstlane_b32 s2, v0
	s_ashr_i32 s2, s2, 6
	s_add_i32 s52, s2, s95
	s_cmp_lt_i32 s52, 0x8010
	s_cbranch_scc0 .LBB0_1165
	s_ashr_i32 s39, s38, 31
	s_lshl_b64 s[28:29], s[38:39], 2
	v_readlane_b32 s36, v252, 18
	v_readlane_b32 s40, v252, 22
	v_readlane_b32 s37, v252, 19
	v_readlane_b32 s41, v252, 23
	s_add_u32 s36, s40, s28
	v_readlane_b32 s42, v252, 24
	s_addc_u32 s37, s41, s29
	v_and_b32_e32 v96, 63, v0
	v_readlane_b32 s43, v252, 25
	s_add_u32 s28, s42, s28
	v_lshlrev_b32_e32 v28, 4, v96
	s_addc_u32 s29, s43, s29
	global_load_dwordx4 v[0:3], v28, s[36:37]
	global_load_dwordx4 v[4:7], v28, s[36:37] offset:1024
	global_load_dwordx4 v[8:11], v28, s[28:29]
	global_load_dwordx4 v[12:15], v28, s[28:29] offset:1024
	global_load_dwordx4 v[16:19], v28, s[36:37] offset:2048
	global_load_dwordx4 v[20:23], v28, s[36:37] offset:3072
	global_load_dwordx4 v[24:27], v28, s[28:29] offset:2048
	s_nop 0
	global_load_dwordx4 v[28:31], v28, s[28:29] offset:3072
	v_and_b32_e32 v32, 64, v227
	v_add_u32_e32 v32, 64, v32
	v_xor_b32_e32 v33, 1, v227
	v_cmp_lt_i32_e32 vcc, v33, v32
	v_lshlrev_b32_e32 v142, 3, v96
	v_cmp_eq_u32_e64 s[36:37], 0, v96
	v_cndmask_b32_e32 v33, v227, v33, vcc
	v_lshlrev_b32_e32 v97, 2, v33
	v_xor_b32_e32 v33, 2, v227
	v_cmp_lt_i32_e32 vcc, v33, v32
	v_lshl_add_u64 v[98:99], s[96:97], 0, v[142:143]
	v_readlane_b32 s38, v252, 20
	v_cndmask_b32_e32 v33, v227, v33, vcc
	v_lshlrev_b32_e32 v114, 2, v33
	v_xor_b32_e32 v33, 4, v227
	v_cmp_lt_i32_e32 vcc, v33, v32
	v_readlane_b32 s39, v252, 21
	v_readlane_b32 s44, v252, 26
	v_cndmask_b32_e32 v33, v227, v33, vcc
	v_lshlrev_b32_e32 v115, 2, v33
	v_xor_b32_e32 v33, 8, v227
	v_cmp_lt_i32_e32 vcc, v33, v32
	v_readlane_b32 s45, v252, 27
	v_readlane_b32 s46, v252, 28
	v_cndmask_b32_e32 v33, v227, v33, vcc
	v_lshlrev_b32_e32 v116, 2, v33
	v_xor_b32_e32 v33, 16, v227
	v_cmp_lt_i32_e32 vcc, v33, v32
	v_readlane_b32 s47, v252, 29
	v_readlane_b32 s48, v252, 30
	v_cndmask_b32_e32 v33, v227, v33, vcc
	v_lshlrev_b32_e32 v117, 2, v33
	v_xor_b32_e32 v33, 32, v227
	v_cmp_lt_i32_e32 vcc, v33, v32
	v_readlane_b32 s49, v252, 31
	v_readlane_b32 s50, v252, 32
	v_cndmask_b32_e32 v32, v227, v33, vcc
	v_lshlrev_b32_e32 v118, 2, v32
	v_readlane_b32 s51, v252, 33
	s_branch .LBB0_1146
